# stack7 plus accumulator zeroing folded into the full-line epilogues (6 GEMM instances; the unit header zero block only runs for the first unit)
# baseline (speedup 1.0000x reference)
; template <class Epi, class Sched, bool ALIGN_EPI = false, bool SP2 = false>
; __device__ __forceinline__ void gemm_phase(PG8_LAS unsigned char* lds, const Gemm g, const Sched& S, const Epi& E) {
;     ...
;         const bool has_next = S.next(ui + 1, nxt);
;         const char* nA = has_next ? (const char*)g.A + (size_t)nxt.pm * tstep : cA; const char* nB = has_next ? (const char*)g.Bt + (size_t)nxt.pn * tstep : cB;
; #pragma nounroll
;         for (int t = 0; t < nt; t += 2) {
;             const bool last = (t == nt - 2);
;             const char* a1 = cA + (size_t)(t + 1) * kstep;
;             const char* a2 = last ? nA : cA + (size_t)(t + 2) * kstep; const char* b2 = last ? nB : cB + (size_t)(t + 2) * kstep;
;     ...
; #pragma unroll
;         for (int a = 0; a < 2; ++a)
; #pragma unroll
;             for (int b = 0; b < 2; ++b)
; #pragma unroll
;                 for (int m = 0; m < 4; ++m)
; #pragma unroll
;                     for (int n = 0; n < 2; ++n) acc[a][b][m][n] = (f32x4){0.f, 0.f, 0.f, 0.f};
.LBB0_36:
	s_ashr_i32 s45, s44, 31
	s_lshl_b64 s[34:35], s[44:45], 22
	s_add_u32 s52, s8, s34
	s_addc_u32 s53, s9, s35
	s_and_b64 s[34:35], s[40:41], exec
	s_cselect_b32 s34, s53, s57
	s_cselect_b32 s35, s52, s56
	s_ashr_i32 s47, s46, 31
	s_lshl_b64 s[54:55], s[46:47], 22
	s_add_u32 s54, s18, s54
	s_addc_u32 s55, s19, s55
	s_and_b64 s[60:61], s[40:41], exec
	s_cselect_b32 s37, s55, s59
	s_cselect_b32 s45, s54, s58
	s_add_u32 s56, s56, 0x200080
	s_addc_u32 s57, s57, 0
	s_add_u32 s47, s58, 0x100
	v_mov_b32_e32 v0, 0
	s_addc_u32 s49, s59, 0
	s_mov_b32 s51, -2
	s_cmp_lt_u32 s33, 2
	s_cbranch_scc0 .Lzs19
	v_mov_b32_e32 v1, v0
	v_mov_b32_e32 v2, v0
	v_mov_b32_e32 v3, v0
	v_mov_b32_e32 v4, v0
	v_mov_b32_e32 v5, v0
	v_mov_b32_e32 v6, v0
	v_mov_b32_e32 v7, v0
	v_mov_b32_e32 v8, v0
	v_mov_b32_e32 v9, v0
	v_mov_b32_e32 v10, v0
	v_mov_b32_e32 v11, v0
	v_mov_b32_e32 v16, v0
	v_mov_b32_e32 v17, v0
	v_mov_b32_e32 v18, v0
	v_mov_b32_e32 v19, v0
	v_mov_b32_e32 v24, v0
	v_mov_b32_e32 v25, v0
	v_mov_b32_e32 v26, v0
	v_mov_b32_e32 v27, v0
	v_mov_b32_e32 v32, v0
	v_mov_b32_e32 v33, v0
	v_mov_b32_e32 v34, v0
	v_mov_b32_e32 v35, v0
	v_mov_b32_e32 v40, v0
	v_mov_b32_e32 v41, v0
	v_mov_b32_e32 v42, v0
	v_mov_b32_e32 v43, v0
	v_mov_b32_e32 v48, v0
	v_mov_b32_e32 v49, v0
	v_mov_b32_e32 v50, v0
	v_mov_b32_e32 v51, v0
	v_mov_b32_e32 v12, v0
	v_mov_b32_e32 v13, v0
	v_mov_b32_e32 v14, v0
	v_mov_b32_e32 v15, v0
	v_mov_b32_e32 v20, v0
	v_mov_b32_e32 v21, v0
	v_mov_b32_e32 v22, v0
	v_mov_b32_e32 v23, v0
	v_mov_b32_e32 v28, v0
	v_mov_b32_e32 v29, v0
	v_mov_b32_e32 v30, v0
	v_mov_b32_e32 v31, v0
	v_mov_b32_e32 v36, v0
	v_mov_b32_e32 v37, v0
	v_mov_b32_e32 v38, v0
	v_mov_b32_e32 v39, v0
	v_mov_b32_e32 v44, v0
	v_mov_b32_e32 v45, v0
	v_mov_b32_e32 v46, v0
	v_mov_b32_e32 v47, v0
	v_mov_b32_e32 v52, v0
	v_mov_b32_e32 v53, v0
	v_mov_b32_e32 v54, v0
	v_mov_b32_e32 v55, v0
	v_mov_b32_e32 v56, v0
	v_mov_b32_e32 v57, v0
	v_mov_b32_e32 v58, v0
	v_mov_b32_e32 v59, v0
	v_mov_b32_e32 v60, v0
	v_mov_b32_e32 v61, v0
	v_mov_b32_e32 v62, v0
	v_mov_b32_e32 v63, v0
	v_mov_b32_e32 v64, v0
	v_mov_b32_e32 v65, v0
	v_mov_b32_e32 v66, v0
	v_mov_b32_e32 v67, v0
	v_mov_b32_e32 v68, v0
	v_mov_b32_e32 v69, v0
	v_mov_b32_e32 v70, v0
	v_mov_b32_e32 v71, v0
	v_mov_b32_e32 v72, v0
	v_mov_b32_e32 v73, v0
	v_mov_b32_e32 v74, v0
	v_mov_b32_e32 v75, v0
	v_mov_b32_e32 v80, v0
	v_mov_b32_e32 v81, v0
	v_mov_b32_e32 v82, v0
	v_mov_b32_e32 v83, v0
	v_mov_b32_e32 v88, v0
	v_mov_b32_e32 v89, v0
	v_mov_b32_e32 v90, v0
	v_mov_b32_e32 v91, v0
	v_mov_b32_e32 v96, v0
	v_mov_b32_e32 v97, v0
	v_mov_b32_e32 v98, v0
	v_mov_b32_e32 v99, v0
	v_mov_b32_e32 v104, v0
	v_mov_b32_e32 v105, v0
	v_mov_b32_e32 v106, v0
	v_mov_b32_e32 v107, v0
	v_mov_b32_e32 v112, v0
	v_mov_b32_e32 v113, v0
	v_mov_b32_e32 v114, v0
	v_mov_b32_e32 v115, v0
	v_mov_b32_e32 v76, v0
	v_mov_b32_e32 v77, v0
	v_mov_b32_e32 v78, v0
	v_mov_b32_e32 v79, v0
	v_mov_b32_e32 v84, v0
	v_mov_b32_e32 v85, v0
	v_mov_b32_e32 v86, v0
	v_mov_b32_e32 v87, v0
	v_mov_b32_e32 v92, v0
	v_mov_b32_e32 v93, v0
	v_mov_b32_e32 v94, v0
	v_mov_b32_e32 v95, v0
	v_mov_b32_e32 v100, v0
	v_mov_b32_e32 v101, v0
	v_mov_b32_e32 v102, v0
	v_mov_b32_e32 v103, v0
	v_mov_b32_e32 v108, v0
	v_mov_b32_e32 v109, v0
	v_mov_b32_e32 v110, v0
	v_mov_b32_e32 v111, v0
	v_mov_b32_e32 v116, v0
	v_mov_b32_e32 v117, v0
	v_mov_b32_e32 v118, v0
	v_mov_b32_e32 v119, v0
	v_mov_b32_e32 v120, v0
	v_mov_b32_e32 v121, v0
	v_mov_b32_e32 v122, v0
	v_mov_b32_e32 v123, v0
	v_mov_b32_e32 v124, v0
	v_mov_b32_e32 v125, v0
	v_mov_b32_e32 v126, v0
	v_mov_b32_e32 v127, v0
.Lzs19:
.LBB0_37:
	s_add_u32 s7, s56, 0xffe00080
	s_addc_u32 s58, s57, -1
	s_add_i32 s62, 0, 0x10000
	s_cmpk_eq_i32 s51, 0x7c
	s_cselect_b32 s61, s34, s58
	s_cselect_b32 s60, s35, s7
	v_add_u32_e32 v140, s62, v143
	s_cselect_b32 s59, s37, s49
	s_cselect_b32 s58, s45, s47
	s_add_i32 s7, 0, 0x14000
	ds_read_b128 v[146:149], v140
	ds_read_b128 v[150:153], v140 offset:1024
	ds_read_b128 v[154:157], v140 offset:2048
	ds_read_b128 v[158:161], v140 offset:3072
	v_add_u32_e32 v140, s7, v143
	ds_read_b128 v[162:165], v140
	ds_read_b128 v[166:169], v140 offset:1024
	ds_read_b128 v[170:173], v140 offset:2048
	ds_read_b128 v[174:177], v140 offset:3072
	v_lshl_add_u64 v[140:141], s[56:57], 0, v[136:137]
	s_add_i32 m0, s10, 0xc000
	ds_read_b128 v[178:181], v145
	ds_read_b128 v[182:185], v145 offset:1024
	ds_read_b128 v[186:189], v145 offset:2048
	ds_read_b128 v[190:193], v145 offset:3072
	ds_read_b128 v[214:217], v145 offset:4096
	ds_read_b128 v[220:223], v145 offset:5120
	ds_read_b128 v[224:227], v145 offset:6144
	ds_read_b128 v[228:231], v145 offset:7168
	global_load_lds_dwordx4 v[140:141], off
	v_lshl_add_u64 v[140:141], s[56:57], 0, v[138:139]
	s_add_i32 m0, s10, 0xe000
	s_nop 0
	global_load_lds_dwordx4 v[140:141], off
	s_cmp_lt_i32 s51, 0
	s_cbranch_scc0 .Lrx19_0_norm
	s_cmp_lt_u32 s33, 2
	s_cbranch_scc1 .Lrx19_0_norm
	s_waitcnt vmcnt(24)
	s_branch .Lrx19_0_join

; __device__ __forceinline__ u32x4 pack8_bf16(f32x4 a, f32x4 b) { u32x4 w; w.x = cvt_pk_bf16(a[0], a[1]); w.y = cvt_pk_bf16(a[2], a[3]); w.z = cvt_pk_bf16(b[0], b[1]); w.w = cvt_pk_bf16(b[2], b[3]); return w; }
; #define ACT(t) (KBASE(t) <= qlo + QBLK - 1 && KBASE(t) + KVBLK - 1 >= qlo - W + 1)
;     __device__ __forceinline__ void operator()(const f32x4 (&acc)[2][2][4][2], const Unit& u, int wr, int wc, int fr, int fq) const {
;         const int g = u.pn / nNper, pnl = u.pn - g * nNper, pml = u.pm & 63;
;         bf16_t* base = O + (size_t)g * gstride;
;         const int row0 = pml * BM + wr * 64 + fr, col0 = pnl * BM + wc * 32 + 8 * fq;
; #pragma unroll
;         for (int ai = 0; ai < 2; ++ai)
; #pragma unroll
;             for (int m = 0; m < 4; ++m) { bf16_t* rowp = base + (size_t)(row0 + ai * HALF + m * 16) * ldc + col0;
; #pragma unroll
;                 for (int bj = 0; bj < 2; ++bj) { f32x4 v0 = acc[ai][bj][m][0], v1 = acc[ai][bj][m][1];
;                     if (ACT == 1) {
; #pragma unroll
;                         for (int j = 0; j < 4; ++j) { float a = fmaxf(v0[j], 0.f), b = fmaxf(v1[j], 0.f); v0[j] = a * a; v1[j] = b * b; } }
;                     *(u32x4*)(rowp + bj * HALF) = pack8_bf16(v0, v1); } }
; template <class Epi, class Sched, bool ALIGN_EPI = false, bool SP2 = false>
; __device__ __forceinline__ void gemm_phase(PG8_LAS unsigned char* lds, const Gemm g, const Sched& S, const Epi& E) {
;     ...
;         for (int a = 0; a < 2; ++a)
; #pragma unroll
;             for (int b = 0; b < 2; ++b)
; #pragma unroll
;                 for (int m = 0; m < 4; ++m)
; #pragma unroll
;                     for (int n = 0; n < 2; ++n) acc[a][b][m][n] = (f32x4){0.f, 0.f, 0.f, 0.f};
.LBB0_40:
	s_ashr_i32 s7, s50, 31
	s_lshr_b32 s7, s7, 29
	s_add_i32 s7, s50, s7
	s_and_b32 s7, s7, 0xfffff8
	s_lshl_b32 s34, s48, 8
	s_sub_i32 s7, s50, s7
	s_and_b32 s34, s34, 0x3f00
	v_add_u32_e32 v146, s34, v142
	v_lshl_or_b32 v140, s7, 8, v144
	v_ashrrev_i32_e32 v141, 31, v140
	v_ashrrev_i32_e32 v147, 31, v146
	v_lshl_add_u64 v[148:149], v[140:141], 1, s[12:13]
	v_lshlrev_b64 v[140:141], 12, v[146:147]
	v_lshl_add_u64 v[140:141], v[148:149], 0, v[140:141]
	s_mov_b64 s[34:35], 0x10000
	v_mov_b32_e32 v242, 0x8000
	v_mov_b32_e32 v243, 0
	v_and_b32_e32 v238, 8, v208
	v_cmp_ne_u32_e32 vcc, 0, v238
	v_and_b32_e32 v240, 63, v208
	v_lshrrev_b32_e32 v241, 3, v240
	v_and_b32_e32 v244, 3, v240
	v_lshl_add_u32 v241, v244, 4, v241
	v_and_b32_e32 v244, 4, v240
	v_lshl_add_u32 v241, v244, 1, v241
	v_lshlrev_b32_e32 v240, 2, v241
	v_cvt_pk_bf16_f32 v124, v124, v125
	v_cvt_pk_bf16_f32 v125, v126, v127
	v_cvt_pk_bf16_f32 v126, v120, v121
	v_cvt_pk_bf16_f32 v127, v122, v123
	v_cvt_pk_bf16_f32 v112, v112, v113
	v_cvt_pk_bf16_f32 v113, v114, v115
	v_cvt_pk_bf16_f32 v114, v104, v105
	v_cvt_pk_bf16_f32 v115, v106, v107
	v_mov_b32_dpp v246, v112 row_ror:8 row_mask:0xf bank_mask:0xf
	v_mov_b32_dpp v247, v113 row_ror:8 row_mask:0xf bank_mask:0xf
	v_mov_b32_dpp v248, v114 row_ror:8 row_mask:0xf bank_mask:0xf
	v_mov_b32_dpp v249, v115 row_ror:8 row_mask:0xf bank_mask:0xf
	v_mov_b32_dpp v250, v124 row_ror:8 row_mask:0xf bank_mask:0xf
	v_mov_b32_dpp v251, v125 row_ror:8 row_mask:0xf bank_mask:0xf
	v_mov_b32_dpp v252, v126 row_ror:8 row_mask:0xf bank_mask:0xf
	v_mov_b32_dpp v253, v127 row_ror:8 row_mask:0xf bank_mask:0xf
	v_cndmask_b32_e32 v246, v124, v246, vcc
	v_cndmask_b32_e32 v247, v125, v247, vcc
	v_cndmask_b32_e32 v248, v126, v248, vcc
	v_cndmask_b32_e32 v249, v127, v249, vcc
	v_cndmask_b32_e32 v250, v250, v112, vcc
	v_cndmask_b32_e32 v251, v251, v113, vcc
	v_cndmask_b32_e32 v252, v252, v114, vcc
	v_cndmask_b32_e32 v253, v253, v115, vcc
	ds_bpermute_b32 v246, v240, v246
	ds_bpermute_b32 v247, v240, v247
	ds_bpermute_b32 v248, v240, v248
	ds_bpermute_b32 v249, v240, v249
	ds_bpermute_b32 v250, v240, v250
	ds_bpermute_b32 v251, v240, v251
	ds_bpermute_b32 v252, v240, v252
	ds_bpermute_b32 v253, v240, v253
	v_mov_b32_e32 v124, 0
	v_mov_b32_e32 v125, 0
	v_mov_b32_e32 v126, 0
	v_mov_b32_e32 v127, 0
	v_mov_b32_e32 v120, 0
	v_mov_b32_e32 v121, 0
	v_mov_b32_e32 v122, 0
	v_mov_b32_e32 v123, 0
	v_mov_b32_e32 v112, 0
	v_mov_b32_e32 v113, 0
	v_mov_b32_e32 v114, 0
	v_mov_b32_e32 v115, 0
	v_mov_b32_e32 v104, 0
	v_mov_b32_e32 v105, 0
	v_mov_b32_e32 v106, 0
	v_mov_b32_e32 v107, 0
	v_lshl_add_u64 v[238:239], v[140:141], 0, v[242:243]
	s_waitcnt lgkmcnt(4)
	global_store_dwordx4 v[140:141], v[246:249], off
	s_waitcnt lgkmcnt(0)
	global_store_dwordx4 v[238:239], v[250:253], off
	v_lshl_add_u64 v[140:141], v[140:141], 0, s[34:35]
	v_cvt_pk_bf16_f32 v116, v116, v117
	v_cvt_pk_bf16_f32 v117, v118, v119
	v_cvt_pk_bf16_f32 v118, v108, v109
	v_cvt_pk_bf16_f32 v119, v110, v111
	v_cvt_pk_bf16_f32 v96, v96, v97
	v_cvt_pk_bf16_f32 v97, v98, v99
	v_cvt_pk_bf16_f32 v98, v88, v89
	v_cvt_pk_bf16_f32 v99, v90, v91
	v_mov_b32_dpp v246, v96 row_ror:8 row_mask:0xf bank_mask:0xf
	v_mov_b32_dpp v247, v97 row_ror:8 row_mask:0xf bank_mask:0xf
	v_mov_b32_dpp v248, v98 row_ror:8 row_mask:0xf bank_mask:0xf
	v_mov_b32_dpp v249, v99 row_ror:8 row_mask:0xf bank_mask:0xf
	v_mov_b32_dpp v250, v116 row_ror:8 row_mask:0xf bank_mask:0xf
	v_mov_b32_dpp v251, v117 row_ror:8 row_mask:0xf bank_mask:0xf
	v_mov_b32_dpp v252, v118 row_ror:8 row_mask:0xf bank_mask:0xf
	v_mov_b32_dpp v253, v119 row_ror:8 row_mask:0xf bank_mask:0xf
	v_cndmask_b32_e32 v246, v116, v246, vcc
	v_cndmask_b32_e32 v247, v117, v247, vcc
	v_cndmask_b32_e32 v248, v118, v248, vcc
	v_cndmask_b32_e32 v249, v119, v249, vcc
	v_cndmask_b32_e32 v250, v250, v96, vcc
	v_cndmask_b32_e32 v251, v251, v97, vcc
	v_cndmask_b32_e32 v252, v252, v98, vcc
	v_cndmask_b32_e32 v253, v253, v99, vcc
	ds_bpermute_b32 v246, v240, v246
	ds_bpermute_b32 v247, v240, v247
	ds_bpermute_b32 v248, v240, v248
	ds_bpermute_b32 v249, v240, v249
	ds_bpermute_b32 v250, v240, v250
	ds_bpermute_b32 v251, v240, v251
	ds_bpermute_b32 v252, v240, v252
	ds_bpermute_b32 v253, v240, v253
	v_mov_b32_e32 v116, 0
	v_mov_b32_e32 v117, 0
	v_mov_b32_e32 v118, 0
	v_mov_b32_e32 v119, 0
	v_mov_b32_e32 v108, 0
	v_mov_b32_e32 v109, 0
	v_mov_b32_e32 v110, 0
	v_mov_b32_e32 v111, 0
	v_mov_b32_e32 v96, 0
	v_mov_b32_e32 v97, 0
	v_mov_b32_e32 v98, 0
	v_mov_b32_e32 v99, 0
	v_mov_b32_e32 v88, 0
	v_mov_b32_e32 v89, 0
	v_mov_b32_e32 v90, 0
	v_mov_b32_e32 v91, 0
	v_lshl_add_u64 v[238:239], v[140:141], 0, v[242:243]
	s_waitcnt lgkmcnt(4)
	global_store_dwordx4 v[140:141], v[246:249], off
	s_waitcnt lgkmcnt(0)
; __device__ __forceinline__ u32x4 pack8_bf16(f32x4 a, f32x4 b) { u32x4 w; w.x = cvt_pk_bf16(a[0], a[1]); w.y = cvt_pk_bf16(a[2], a[3]); w.z = cvt_pk_bf16(b[0], b[1]); w.w = cvt_pk_bf16(b[2], b[3]); return w; }
; #define ACT(t) (KBASE(t) <= qlo + QBLK - 1 && KBASE(t) + KVBLK - 1 >= qlo - W + 1)
;     __device__ __forceinline__ void operator()(const f32x4 (&acc)[2][2][4][2], const Unit& u, int wr, int wc, int fr, int fq) const {
;         const int g = u.pn / nNper, pnl = u.pn - g * nNper, pml = u.pm & 63;
;         bf16_t* base = O + (size_t)g * gstride;
;         const int row0 = pml * BM + wr * 64 + fr, col0 = pnl * BM + wc * 32 + 8 * fq;
; #pragma unroll
;         for (int ai = 0; ai < 2; ++ai)
; #pragma unroll
;             for (int m = 0; m < 4; ++m) { bf16_t* rowp = base + (size_t)(row0 + ai * HALF + m * 16) * ldc + col0;
; #pragma unroll
;                 for (int bj = 0; bj < 2; ++bj) { f32x4 v0 = acc[ai][bj][m][0], v1 = acc[ai][bj][m][1];
;                     if (ACT == 1) {
; #pragma unroll
;                         for (int j = 0; j < 4; ++j) { float a = fmaxf(v0[j], 0.f), b = fmaxf(v1[j], 0.f); v0[j] = a * a; v1[j] = b * b; } }
;                     *(u32x4*)(rowp + bj * HALF) = pack8_bf16(v0, v1); } }
; template <class Epi, class Sched, bool ALIGN_EPI = false, bool SP2 = false>
; __device__ __forceinline__ void gemm_phase(PG8_LAS unsigned char* lds, const Gemm g, const Sched& S, const Epi& E) {
;     ...
;         for (int a = 0; a < 2; ++a)
; #pragma unroll
;             for (int b = 0; b < 2; ++b)
; #pragma unroll
;                 for (int m = 0; m < 4; ++m)
; #pragma unroll
;                     for (int n = 0; n < 2; ++n) acc[a][b][m][n] = (f32x4){0.f, 0.f, 0.f, 0.f};
	global_store_dwordx4 v[238:239], v[250:253], off
	v_lshl_add_u64 v[140:141], v[140:141], 0, s[34:35]
	v_cvt_pk_bf16_f32 v100, v100, v101
	v_cvt_pk_bf16_f32 v101, v102, v103
	v_cvt_pk_bf16_f32 v102, v92, v93
	v_cvt_pk_bf16_f32 v103, v94, v95
	v_cvt_pk_bf16_f32 v80, v80, v81
	v_cvt_pk_bf16_f32 v81, v82, v83
	v_cvt_pk_bf16_f32 v82, v72, v73
	v_cvt_pk_bf16_f32 v83, v74, v75
	v_mov_b32_dpp v246, v80 row_ror:8 row_mask:0xf bank_mask:0xf
	v_mov_b32_dpp v247, v81 row_ror:8 row_mask:0xf bank_mask:0xf
	v_mov_b32_dpp v248, v82 row_ror:8 row_mask:0xf bank_mask:0xf
	v_mov_b32_dpp v249, v83 row_ror:8 row_mask:0xf bank_mask:0xf
	v_mov_b32_dpp v250, v100 row_ror:8 row_mask:0xf bank_mask:0xf
	v_mov_b32_dpp v251, v101 row_ror:8 row_mask:0xf bank_mask:0xf
	v_mov_b32_dpp v252, v102 row_ror:8 row_mask:0xf bank_mask:0xf
	v_mov_b32_dpp v253, v103 row_ror:8 row_mask:0xf bank_mask:0xf
	v_cndmask_b32_e32 v246, v100, v246, vcc
	v_cndmask_b32_e32 v247, v101, v247, vcc
	v_cndmask_b32_e32 v248, v102, v248, vcc
	v_cndmask_b32_e32 v249, v103, v249, vcc
	v_cndmask_b32_e32 v250, v250, v80, vcc
	v_cndmask_b32_e32 v251, v251, v81, vcc
	v_cndmask_b32_e32 v252, v252, v82, vcc
	v_cndmask_b32_e32 v253, v253, v83, vcc
	ds_bpermute_b32 v246, v240, v246
	ds_bpermute_b32 v247, v240, v247
	ds_bpermute_b32 v248, v240, v248
	ds_bpermute_b32 v249, v240, v249
	ds_bpermute_b32 v250, v240, v250
	ds_bpermute_b32 v251, v240, v251
	ds_bpermute_b32 v252, v240, v252
	ds_bpermute_b32 v253, v240, v253
	v_mov_b32_e32 v100, 0
	v_mov_b32_e32 v101, 0
	v_mov_b32_e32 v102, 0
	v_mov_b32_e32 v103, 0
	v_mov_b32_e32 v92, 0
	v_mov_b32_e32 v93, 0
	v_mov_b32_e32 v94, 0
	v_mov_b32_e32 v95, 0
	v_mov_b32_e32 v80, 0
	v_mov_b32_e32 v81, 0
	v_mov_b32_e32 v82, 0
	v_mov_b32_e32 v83, 0
	v_mov_b32_e32 v72, 0
	v_mov_b32_e32 v73, 0
	v_mov_b32_e32 v74, 0
	v_mov_b32_e32 v75, 0
	v_lshl_add_u64 v[238:239], v[140:141], 0, v[242:243]
	s_waitcnt lgkmcnt(4)
	global_store_dwordx4 v[140:141], v[246:249], off
	s_waitcnt lgkmcnt(0)
	global_store_dwordx4 v[238:239], v[250:253], off
	v_lshl_add_u64 v[140:141], v[140:141], 0, s[34:35]
	v_cvt_pk_bf16_f32 v84, v84, v85
	v_cvt_pk_bf16_f32 v85, v86, v87
	v_cvt_pk_bf16_f32 v86, v76, v77
	v_cvt_pk_bf16_f32 v87, v78, v79
	v_cvt_pk_bf16_f32 v68, v68, v69
	v_cvt_pk_bf16_f32 v69, v70, v71
	v_cvt_pk_bf16_f32 v70, v64, v65
	v_cvt_pk_bf16_f32 v71, v66, v67
	v_mov_b32_dpp v246, v68 row_ror:8 row_mask:0xf bank_mask:0xf
	v_mov_b32_dpp v247, v69 row_ror:8 row_mask:0xf bank_mask:0xf
	v_mov_b32_dpp v248, v70 row_ror:8 row_mask:0xf bank_mask:0xf
	v_mov_b32_dpp v249, v71 row_ror:8 row_mask:0xf bank_mask:0xf
	v_mov_b32_dpp v250, v84 row_ror:8 row_mask:0xf bank_mask:0xf
	v_mov_b32_dpp v251, v85 row_ror:8 row_mask:0xf bank_mask:0xf
	v_mov_b32_dpp v252, v86 row_ror:8 row_mask:0xf bank_mask:0xf
	v_mov_b32_dpp v253, v87 row_ror:8 row_mask:0xf bank_mask:0xf
	v_cndmask_b32_e32 v246, v84, v246, vcc
	v_cndmask_b32_e32 v247, v85, v247, vcc
	v_cndmask_b32_e32 v248, v86, v248, vcc
	v_cndmask_b32_e32 v249, v87, v249, vcc
	v_cndmask_b32_e32 v250, v250, v68, vcc
	v_cndmask_b32_e32 v251, v251, v69, vcc
	v_cndmask_b32_e32 v252, v252, v70, vcc
	v_cndmask_b32_e32 v253, v253, v71, vcc
	ds_bpermute_b32 v246, v240, v246
	ds_bpermute_b32 v247, v240, v247
	ds_bpermute_b32 v248, v240, v248
	ds_bpermute_b32 v249, v240, v249
	ds_bpermute_b32 v250, v240, v250
	ds_bpermute_b32 v251, v240, v251
	ds_bpermute_b32 v252, v240, v252
	ds_bpermute_b32 v253, v240, v253
	v_mov_b32_e32 v84, 0
	v_mov_b32_e32 v85, 0
	v_mov_b32_e32 v86, 0
	v_mov_b32_e32 v87, 0
	v_mov_b32_e32 v76, 0
	v_mov_b32_e32 v77, 0
	v_mov_b32_e32 v78, 0
	v_mov_b32_e32 v79, 0
	v_mov_b32_e32 v68, 0
	v_mov_b32_e32 v69, 0
	v_mov_b32_e32 v70, 0
	v_mov_b32_e32 v71, 0
	v_mov_b32_e32 v64, 0
	v_mov_b32_e32 v65, 0
	v_mov_b32_e32 v66, 0
	v_mov_b32_e32 v67, 0
	v_lshl_add_u64 v[238:239], v[140:141], 0, v[242:243]
	s_waitcnt lgkmcnt(4)
	global_store_dwordx4 v[140:141], v[246:249], off
	s_waitcnt lgkmcnt(0)
	global_store_dwordx4 v[238:239], v[250:253], off
	s_mov_b64 s[34:35], 0x50000
	v_lshl_add_u64 v[140:141], v[140:141], 0, s[34:35]
	s_mov_b64 s[34:35], 0x10000
	v_cvt_pk_bf16_f32 v60, v60, v61
	v_cvt_pk_bf16_f32 v61, v62, v63
	v_cvt_pk_bf16_f32 v62, v56, v57
	v_cvt_pk_bf16_f32 v63, v58, v59
	v_cvt_pk_bf16_f32 v48, v48, v49
	v_cvt_pk_bf16_f32 v49, v50, v51
	v_cvt_pk_bf16_f32 v50, v40, v41
	v_cvt_pk_bf16_f32 v51, v42, v43
	v_mov_b32_dpp v246, v48 row_ror:8 row_mask:0xf bank_mask:0xf
	v_mov_b32_dpp v247, v49 row_ror:8 row_mask:0xf bank_mask:0xf
	v_mov_b32_dpp v248, v50 row_ror:8 row_mask:0xf bank_mask:0xf
	v_mov_b32_dpp v249, v51 row_ror:8 row_mask:0xf bank_mask:0xf
	v_mov_b32_dpp v250, v60 row_ror:8 row_mask:0xf bank_mask:0xf
	v_mov_b32_dpp v251, v61 row_ror:8 row_mask:0xf bank_mask:0xf
	v_mov_b32_dpp v252, v62 row_ror:8 row_mask:0xf bank_mask:0xf
	v_mov_b32_dpp v253, v63 row_ror:8 row_mask:0xf bank_mask:0xf
	v_cndmask_b32_e32 v246, v60, v246, vcc
	v_cndmask_b32_e32 v247, v61, v247, vcc
	v_cndmask_b32_e32 v248, v62, v248, vcc
	v_cndmask_b32_e32 v249, v63, v249, vcc
	v_cndmask_b32_e32 v250, v250, v48, vcc
	v_cndmask_b32_e32 v251, v251, v49, vcc
	v_cndmask_b32_e32 v252, v252, v50, vcc
	v_cndmask_b32_e32 v253, v253, v51, vcc
	ds_bpermute_b32 v246, v240, v246
	ds_bpermute_b32 v247, v240, v247
	ds_bpermute_b32 v248, v240, v248
	ds_bpermute_b32 v249, v240, v249
	ds_bpermute_b32 v250, v240, v250
	ds_bpermute_b32 v251, v240, v251
	ds_bpermute_b32 v252, v240, v252
	ds_bpermute_b32 v253, v240, v253
	v_mov_b32_e32 v60, 0
	v_mov_b32_e32 v61, 0
	v_mov_b32_e32 v62, 0
	v_mov_b32_e32 v63, 0
	v_mov_b32_e32 v56, 0
	v_mov_b32_e32 v57, 0
	v_mov_b32_e32 v58, 0
	v_mov_b32_e32 v59, 0
	v_mov_b32_e32 v48, 0
	v_mov_b32_e32 v49, 0
	v_mov_b32_e32 v50, 0
	v_mov_b32_e32 v51, 0
	v_mov_b32_e32 v40, 0
	v_mov_b32_e32 v41, 0
	v_mov_b32_e32 v42, 0
	v_mov_b32_e32 v43, 0
	v_lshl_add_u64 v[238:239], v[140:141], 0, v[242:243]
	s_waitcnt lgkmcnt(4)
; __device__ __forceinline__ u32x4 pack8_bf16(f32x4 a, f32x4 b) { u32x4 w; w.x = cvt_pk_bf16(a[0], a[1]); w.y = cvt_pk_bf16(a[2], a[3]); w.z = cvt_pk_bf16(b[0], b[1]); w.w = cvt_pk_bf16(b[2], b[3]); return w; }
; #define PG8_BAR __builtin_amdgcn_s_barrier()
; #define ACT(t) (KBASE(t) <= qlo + QBLK - 1 && KBASE(t) + KVBLK - 1 >= qlo - W + 1)
;     __device__ __forceinline__ void operator()(const f32x4 (&acc)[2][2][4][2], const Unit& u, int wr, int wc, int fr, int fq) const {
;         const int g = u.pn / nNper, pnl = u.pn - g * nNper, pml = u.pm & 63;
;         bf16_t* base = O + (size_t)g * gstride;
;         const int row0 = pml * BM + wr * 64 + fr, col0 = pnl * BM + wc * 32 + 8 * fq;
; #pragma unroll
;         for (int ai = 0; ai < 2; ++ai)
; #pragma unroll
;             for (int m = 0; m < 4; ++m) { bf16_t* rowp = base + (size_t)(row0 + ai * HALF + m * 16) * ldc + col0;
; #pragma unroll
;                 for (int bj = 0; bj < 2; ++bj) { f32x4 v0 = acc[ai][bj][m][0], v1 = acc[ai][bj][m][1];
;                     if (ACT == 1) {
; #pragma unroll
;                         for (int j = 0; j < 4; ++j) { float a = fmaxf(v0[j], 0.f), b = fmaxf(v1[j], 0.f); v0[j] = a * a; v1[j] = b * b; } }
;                     *(u32x4*)(rowp + bj * HALF) = pack8_bf16(v0, v1); } }
;     }
; template <class Epi, class Sched, bool ALIGN_EPI = false, bool SP2 = false>
; __device__ __forceinline__ void gemm_phase(PG8_LAS unsigned char* lds, const Gemm g, const Sched& S, const Epi& E) {
;     ...
;         if constexpr (ALIGN_EPI) { if (wr == 0) PG8_BAR; }
;         if constexpr (!Epi::AFTER_DRAIN) { E(acc, cur, wr, wc, fr, fq); S.done(cur); }
;         if (!has_next) break;
; #pragma unroll
;         for (int a = 0; a < 2; ++a)
; #pragma unroll
;             for (int b = 0; b < 2; ++b)
; #pragma unroll
;                 for (int m = 0; m < 4; ++m)
; #pragma unroll
;                     for (int n = 0; n < 2; ++n) acc[a][b][m][n] = (f32x4){0.f, 0.f, 0.f, 0.f};
;         cur = nxt; cA = nA; cB = nB; ++ui;
;         if constexpr (ALIGN_EPI) { if (wr == 1) PG8_BAR; }
	global_store_dwordx4 v[140:141], v[246:249], off
	s_waitcnt lgkmcnt(0)
	global_store_dwordx4 v[238:239], v[250:253], off
	v_lshl_add_u64 v[140:141], v[140:141], 0, s[34:35]
	v_cvt_pk_bf16_f32 v52, v52, v53
	v_cvt_pk_bf16_f32 v53, v54, v55
	v_cvt_pk_bf16_f32 v54, v44, v45
	v_cvt_pk_bf16_f32 v55, v46, v47
	v_cvt_pk_bf16_f32 v32, v32, v33
	v_cvt_pk_bf16_f32 v33, v34, v35
	v_cvt_pk_bf16_f32 v34, v24, v25
	v_cvt_pk_bf16_f32 v35, v26, v27
	v_mov_b32_dpp v246, v32 row_ror:8 row_mask:0xf bank_mask:0xf
	v_mov_b32_dpp v247, v33 row_ror:8 row_mask:0xf bank_mask:0xf
	v_mov_b32_dpp v248, v34 row_ror:8 row_mask:0xf bank_mask:0xf
	v_mov_b32_dpp v249, v35 row_ror:8 row_mask:0xf bank_mask:0xf
	v_mov_b32_dpp v250, v52 row_ror:8 row_mask:0xf bank_mask:0xf
	v_mov_b32_dpp v251, v53 row_ror:8 row_mask:0xf bank_mask:0xf
	v_mov_b32_dpp v252, v54 row_ror:8 row_mask:0xf bank_mask:0xf
	v_mov_b32_dpp v253, v55 row_ror:8 row_mask:0xf bank_mask:0xf
	v_cndmask_b32_e32 v246, v52, v246, vcc
	v_cndmask_b32_e32 v247, v53, v247, vcc
	v_cndmask_b32_e32 v248, v54, v248, vcc
	v_cndmask_b32_e32 v249, v55, v249, vcc
	v_cndmask_b32_e32 v250, v250, v32, vcc
	v_cndmask_b32_e32 v251, v251, v33, vcc
	v_cndmask_b32_e32 v252, v252, v34, vcc
	v_cndmask_b32_e32 v253, v253, v35, vcc
	ds_bpermute_b32 v246, v240, v246
	ds_bpermute_b32 v247, v240, v247
	ds_bpermute_b32 v248, v240, v248
	ds_bpermute_b32 v249, v240, v249
	ds_bpermute_b32 v250, v240, v250
	ds_bpermute_b32 v251, v240, v251
	ds_bpermute_b32 v252, v240, v252
	ds_bpermute_b32 v253, v240, v253
	v_mov_b32_e32 v52, 0
	v_mov_b32_e32 v53, 0
	v_mov_b32_e32 v54, 0
	v_mov_b32_e32 v55, 0
	v_mov_b32_e32 v44, 0
	v_mov_b32_e32 v45, 0
	v_mov_b32_e32 v46, 0
	v_mov_b32_e32 v47, 0
	v_mov_b32_e32 v32, 0
	v_mov_b32_e32 v33, 0
	v_mov_b32_e32 v34, 0
	v_mov_b32_e32 v35, 0
	v_mov_b32_e32 v24, 0
	v_mov_b32_e32 v25, 0
	v_mov_b32_e32 v26, 0
	v_mov_b32_e32 v27, 0
	v_lshl_add_u64 v[238:239], v[140:141], 0, v[242:243]
	s_waitcnt lgkmcnt(4)
	global_store_dwordx4 v[140:141], v[246:249], off
	s_waitcnt lgkmcnt(0)
	global_store_dwordx4 v[238:239], v[250:253], off
	v_lshl_add_u64 v[140:141], v[140:141], 0, s[34:35]
	v_cvt_pk_bf16_f32 v36, v36, v37
	v_cvt_pk_bf16_f32 v37, v38, v39
	v_cvt_pk_bf16_f32 v38, v28, v29
	v_cvt_pk_bf16_f32 v39, v30, v31
	v_cvt_pk_bf16_f32 v16, v16, v17
	v_cvt_pk_bf16_f32 v17, v18, v19
	v_cvt_pk_bf16_f32 v18, v8, v9
	v_cvt_pk_bf16_f32 v19, v10, v11
	v_mov_b32_dpp v246, v16 row_ror:8 row_mask:0xf bank_mask:0xf
	v_mov_b32_dpp v247, v17 row_ror:8 row_mask:0xf bank_mask:0xf
	v_mov_b32_dpp v248, v18 row_ror:8 row_mask:0xf bank_mask:0xf
	v_mov_b32_dpp v249, v19 row_ror:8 row_mask:0xf bank_mask:0xf
	v_mov_b32_dpp v250, v36 row_ror:8 row_mask:0xf bank_mask:0xf
	v_mov_b32_dpp v251, v37 row_ror:8 row_mask:0xf bank_mask:0xf
	v_mov_b32_dpp v252, v38 row_ror:8 row_mask:0xf bank_mask:0xf
	v_mov_b32_dpp v253, v39 row_ror:8 row_mask:0xf bank_mask:0xf
	v_cndmask_b32_e32 v246, v36, v246, vcc
	v_cndmask_b32_e32 v247, v37, v247, vcc
	v_cndmask_b32_e32 v248, v38, v248, vcc
	v_cndmask_b32_e32 v249, v39, v249, vcc
	v_cndmask_b32_e32 v250, v250, v16, vcc
	v_cndmask_b32_e32 v251, v251, v17, vcc
	v_cndmask_b32_e32 v252, v252, v18, vcc
	v_cndmask_b32_e32 v253, v253, v19, vcc
	ds_bpermute_b32 v246, v240, v246
	ds_bpermute_b32 v247, v240, v247
	ds_bpermute_b32 v248, v240, v248
	ds_bpermute_b32 v249, v240, v249
	ds_bpermute_b32 v250, v240, v250
	ds_bpermute_b32 v251, v240, v251
	ds_bpermute_b32 v252, v240, v252
	ds_bpermute_b32 v253, v240, v253
	v_mov_b32_e32 v36, 0
	v_mov_b32_e32 v37, 0
	v_mov_b32_e32 v38, 0
	v_mov_b32_e32 v39, 0
	v_mov_b32_e32 v28, 0
	v_mov_b32_e32 v29, 0
	v_mov_b32_e32 v30, 0
	v_mov_b32_e32 v31, 0
	v_mov_b32_e32 v16, 0
	v_mov_b32_e32 v17, 0
	v_mov_b32_e32 v18, 0
	v_mov_b32_e32 v19, 0
	v_mov_b32_e32 v8, 0
	v_mov_b32_e32 v9, 0
	v_mov_b32_e32 v10, 0
	v_mov_b32_e32 v11, 0
	v_lshl_add_u64 v[238:239], v[140:141], 0, v[242:243]
	s_waitcnt lgkmcnt(4)
	global_store_dwordx4 v[140:141], v[246:249], off
	s_waitcnt lgkmcnt(0)
	global_store_dwordx4 v[238:239], v[250:253], off
	v_lshl_add_u64 v[140:141], v[140:141], 0, s[34:35]
	v_cvt_pk_bf16_f32 v20, v20, v21
	v_cvt_pk_bf16_f32 v21, v22, v23
	v_cvt_pk_bf16_f32 v22, v12, v13
	v_cvt_pk_bf16_f32 v23, v14, v15
	v_cvt_pk_bf16_f32 v4, v4, v5
	v_cvt_pk_bf16_f32 v5, v6, v7
	v_cvt_pk_bf16_f32 v6, v0, v1
	v_cvt_pk_bf16_f32 v7, v2, v3
	v_mov_b32_dpp v246, v4 row_ror:8 row_mask:0xf bank_mask:0xf
	v_mov_b32_dpp v247, v5 row_ror:8 row_mask:0xf bank_mask:0xf
	v_mov_b32_dpp v248, v6 row_ror:8 row_mask:0xf bank_mask:0xf
	v_mov_b32_dpp v249, v7 row_ror:8 row_mask:0xf bank_mask:0xf
	v_mov_b32_dpp v250, v20 row_ror:8 row_mask:0xf bank_mask:0xf
	v_mov_b32_dpp v251, v21 row_ror:8 row_mask:0xf bank_mask:0xf
	v_mov_b32_dpp v252, v22 row_ror:8 row_mask:0xf bank_mask:0xf
	v_mov_b32_dpp v253, v23 row_ror:8 row_mask:0xf bank_mask:0xf
	v_cndmask_b32_e32 v246, v20, v246, vcc
	v_cndmask_b32_e32 v247, v21, v247, vcc
	v_cndmask_b32_e32 v248, v22, v248, vcc
	v_cndmask_b32_e32 v249, v23, v249, vcc
	v_cndmask_b32_e32 v250, v250, v4, vcc
	v_cndmask_b32_e32 v251, v251, v5, vcc
	v_cndmask_b32_e32 v252, v252, v6, vcc
	v_cndmask_b32_e32 v253, v253, v7, vcc
	ds_bpermute_b32 v246, v240, v246
	ds_bpermute_b32 v247, v240, v247
	ds_bpermute_b32 v248, v240, v248
	ds_bpermute_b32 v249, v240, v249
	ds_bpermute_b32 v250, v240, v250
	ds_bpermute_b32 v251, v240, v251
	ds_bpermute_b32 v252, v240, v252
	ds_bpermute_b32 v253, v240, v253
	v_mov_b32_e32 v20, 0
	v_mov_b32_e32 v21, 0
	v_mov_b32_e32 v22, 0
	v_mov_b32_e32 v23, 0
	v_mov_b32_e32 v12, 0
	v_mov_b32_e32 v13, 0
	v_mov_b32_e32 v14, 0
	v_mov_b32_e32 v15, 0
	v_mov_b32_e32 v4, 0
	v_mov_b32_e32 v5, 0
	v_mov_b32_e32 v6, 0
	v_mov_b32_e32 v7, 0
	v_mov_b32_e32 v0, 0
	v_mov_b32_e32 v1, 0
	v_mov_b32_e32 v2, 0
	v_mov_b32_e32 v3, 0
	v_lshl_add_u64 v[238:239], v[140:141], 0, v[242:243]
	s_waitcnt lgkmcnt(4)
	global_store_dwordx4 v[140:141], v[246:249], off
	s_waitcnt lgkmcnt(0)
	global_store_dwordx4 v[238:239], v[250:253], off
	s_andn2_b64 vcc, exec, s[40:41]
	s_mov_b64 s[34:35], -1
	s_cbranch_vccnz .LBB0_29
	s_andn2_b64 vcc, exec, s[30:31]
	s_cbranch_vccnz .LBB0_28
	s_barrier
	s_branch .LBB0_28

; #define PG8_STAGE(bufoff, gbase, voff) do { _Pragma("unroll") for (int _i = 0; _i < 2; ++_i) \
;         __builtin_amdgcn_global_load_lds((const unsigned*)((const char*)(gbase) + (voff)[_i]), (PG8_LAS unsigned*)(lds + (bufoff) + ldsw + _i * 8192), 16, 0, 0); } while (0)
; #define PG8_LDA(dst, b, h) do { _Pragma("unroll") for (int m = 0; m < 4; ++m) _Pragma("unroll") for (int k = 0; k < 2; ++k) dst[m][k] = *(const PG8_LAS bf16x8*)(lds + PG8_SA(b, h) + aoff + m * 2048 + k * 1024); } while (0)
; #define PG8_LDB(dst, b, h) do { _Pragma("unroll") for (int n = 0; n < 2; ++n) _Pragma("unroll") for (int k = 0; k < 2; ++k) dst[n][k] = *(const PG8_LAS bf16x8*)(lds + PG8_SB(b, h) + boff + n * 2048 + k * 1024); } while (0)
; #define PG8_SCHED __builtin_amdgcn_sched_barrier(0)
; template <class Epi, class Sched, bool ALIGN_EPI = false, bool SP2 = false>
; __device__ __forceinline__ void gemm_phase(PG8_LAS unsigned char* lds, const Gemm g, const Sched& S, const Epi& E) {
;     ...
;         const bool has_next = S.next(ui + 1, nxt);
;         const char* nA = has_next ? (const char*)g.A + (size_t)nxt.pm * tstep : cA; const char* nB = has_next ? (const char*)g.Bt + (size_t)nxt.pn * tstep : cB;
; #pragma nounroll
;         for (int t = 0; t < nt; t += 2) {
;             const bool last = (t == nt - 2);
;             const char* a1 = cA + (size_t)(t + 1) * kstep;
;             const char* a2 = last ? nA : cA + (size_t)(t + 2) * kstep; const char* b2 = last ? nB : cB + (size_t)(t + 2) * kstep;
;             const char* a3 = a2 + kstep; const char* b3 = b2 + kstep;
;             if (last && has_next) S.a_ready(nxt);
;             if constexpr (SP2) {
;             PG8_LDB(B0, 0, 0); PG8_LDB(B1, 0, 1); PG8_SCHED; PG8_LDA(At, 0, 0); PG8_STAGE(PG8_SA(1, 1), a1 + hstep, voffA);
;     ...
; #pragma unroll
;         for (int a = 0; a < 2; ++a)
; #pragma unroll
;             for (int b = 0; b < 2; ++b)
; #pragma unroll
;                 for (int m = 0; m < 4; ++m)
; #pragma unroll
;                     for (int n = 0; n < 2; ++n) acc[a][b][m][n] = (f32x4){0.f, 0.f, 0.f, 0.f};
.LBB0_58:
	s_ashr_i32 s45, s44, 31
	s_lshl_b64 s[34:35], s[44:45], 20
	s_add_u32 s48, s83, s34
	s_addc_u32 s49, s93, s35
	s_and_b64 s[34:35], s[40:41], exec
	s_cselect_b32 s34, s49, s57
	s_cselect_b32 s35, s48, s56
	s_ashr_i32 s47, s46, 31
	s_lshl_b64 s[50:51], s[46:47], 20
	s_add_u32 s50, s84, s50
	s_addc_u32 s51, s85, s51
	s_and_b64 s[60:61], s[40:41], exec
	s_cselect_b32 s37, s51, s59
	s_cselect_b32 s45, s50, s58
	s_add_u32 s56, s56, 0x80080
	s_addc_u32 s57, s57, 0
	s_add_u32 s47, s58, 0x100
	v_mov_b32_e32 v0, 0
	s_addc_u32 s53, s59, 0
	s_mov_b32 s55, -2
	s_cmp_lt_u32 s33, 2
	s_cbranch_scc0 .Lzs18
	v_mov_b32_e32 v1, v0
	v_mov_b32_e32 v2, v0
	v_mov_b32_e32 v3, v0
	v_mov_b32_e32 v4, v0
	v_mov_b32_e32 v5, v0
	v_mov_b32_e32 v6, v0
	v_mov_b32_e32 v7, v0
	v_mov_b32_e32 v16, v0
	v_mov_b32_e32 v17, v0
	v_mov_b32_e32 v18, v0
	v_mov_b32_e32 v19, v0
	v_mov_b32_e32 v20, v0
	v_mov_b32_e32 v21, v0
	v_mov_b32_e32 v22, v0
	v_mov_b32_e32 v23, v0
	v_mov_b32_e32 v32, v0
	v_mov_b32_e32 v33, v0
	v_mov_b32_e32 v34, v0
	v_mov_b32_e32 v35, v0
	v_mov_b32_e32 v36, v0
	v_mov_b32_e32 v37, v0
	v_mov_b32_e32 v38, v0
	v_mov_b32_e32 v39, v0
	v_mov_b32_e32 v48, v0
	v_mov_b32_e32 v49, v0
	v_mov_b32_e32 v50, v0
	v_mov_b32_e32 v51, v0
	v_mov_b32_e32 v52, v0
	v_mov_b32_e32 v53, v0
	v_mov_b32_e32 v54, v0
	v_mov_b32_e32 v55, v0
	v_mov_b32_e32 v8, v0
	v_mov_b32_e32 v9, v0
	v_mov_b32_e32 v10, v0
	v_mov_b32_e32 v11, v0
	v_mov_b32_e32 v12, v0
	v_mov_b32_e32 v13, v0
	v_mov_b32_e32 v14, v0
	v_mov_b32_e32 v15, v0
	v_mov_b32_e32 v24, v0
	v_mov_b32_e32 v25, v0
	v_mov_b32_e32 v26, v0
	v_mov_b32_e32 v27, v0
	v_mov_b32_e32 v28, v0
	v_mov_b32_e32 v29, v0
	v_mov_b32_e32 v30, v0
	v_mov_b32_e32 v31, v0
	v_mov_b32_e32 v40, v0
	v_mov_b32_e32 v41, v0
	v_mov_b32_e32 v42, v0
	v_mov_b32_e32 v43, v0
	v_mov_b32_e32 v44, v0
	v_mov_b32_e32 v45, v0
	v_mov_b32_e32 v46, v0
	v_mov_b32_e32 v47, v0
	v_mov_b32_e32 v56, v0
	v_mov_b32_e32 v57, v0
	v_mov_b32_e32 v58, v0
	v_mov_b32_e32 v59, v0
	v_mov_b32_e32 v60, v0
	v_mov_b32_e32 v61, v0
	v_mov_b32_e32 v62, v0
	v_mov_b32_e32 v63, v0
	v_mov_b32_e32 v64, v0
	v_mov_b32_e32 v65, v0
	v_mov_b32_e32 v66, v0
	v_mov_b32_e32 v67, v0
	v_mov_b32_e32 v68, v0
	v_mov_b32_e32 v69, v0
	v_mov_b32_e32 v70, v0
	v_mov_b32_e32 v71, v0
	v_mov_b32_e32 v80, v0
	v_mov_b32_e32 v81, v0
	v_mov_b32_e32 v82, v0
	v_mov_b32_e32 v83, v0
	v_mov_b32_e32 v84, v0
	v_mov_b32_e32 v85, v0
	v_mov_b32_e32 v86, v0
	v_mov_b32_e32 v87, v0
	v_mov_b32_e32 v96, v0
	v_mov_b32_e32 v97, v0
	v_mov_b32_e32 v98, v0
	v_mov_b32_e32 v99, v0
	v_mov_b32_e32 v100, v0
	v_mov_b32_e32 v101, v0
	v_mov_b32_e32 v102, v0
	v_mov_b32_e32 v103, v0
	v_mov_b32_e32 v112, v0
	v_mov_b32_e32 v113, v0
	v_mov_b32_e32 v114, v0
	v_mov_b32_e32 v115, v0
	v_mov_b32_e32 v116, v0
	v_mov_b32_e32 v117, v0
	v_mov_b32_e32 v118, v0
	v_mov_b32_e32 v119, v0
	v_mov_b32_e32 v72, v0
	v_mov_b32_e32 v73, v0
	v_mov_b32_e32 v74, v0
	v_mov_b32_e32 v75, v0
	v_mov_b32_e32 v76, v0
	v_mov_b32_e32 v77, v0
	v_mov_b32_e32 v78, v0
	v_mov_b32_e32 v79, v0
	v_mov_b32_e32 v88, v0
	v_mov_b32_e32 v89, v0
	v_mov_b32_e32 v90, v0
	v_mov_b32_e32 v91, v0
	v_mov_b32_e32 v92, v0
	v_mov_b32_e32 v93, v0
	v_mov_b32_e32 v94, v0
	v_mov_b32_e32 v95, v0
	v_mov_b32_e32 v104, v0
	v_mov_b32_e32 v105, v0
	v_mov_b32_e32 v106, v0
	v_mov_b32_e32 v107, v0
	v_mov_b32_e32 v108, v0
	v_mov_b32_e32 v109, v0
	v_mov_b32_e32 v110, v0
	v_mov_b32_e32 v111, v0
	v_mov_b32_e32 v120, v0
	v_mov_b32_e32 v121, v0
	v_mov_b32_e32 v122, v0
	v_mov_b32_e32 v123, v0
	v_mov_b32_e32 v124, v0
	v_mov_b32_e32 v125, v0
	v_mov_b32_e32 v126, v0
	v_mov_b32_e32 v127, v0
.Lzs18:
.LBB0_59:
	s_add_u32 s7, s56, 0xfff80080
	s_addc_u32 s58, s57, -1
	s_add_i32 s62, 0, 0x10000
	s_cmp_eq_u32 s55, 28
	s_cselect_b32 s61, s34, s58
	s_cselect_b32 s60, s35, s7
	v_add_u32_e32 v140, s62, v143
	s_cselect_b32 s59, s37, s53
	s_cselect_b32 s58, s45, s47
	s_add_i32 s7, 0, 0x14000
	ds_read_b128 v[146:149], v140
	ds_read_b128 v[150:153], v140 offset:1024
	ds_read_b128 v[154:157], v140 offset:2048
	ds_read_b128 v[158:161], v140 offset:3072
	v_add_u32_e32 v140, s7, v143
	ds_read_b128 v[162:165], v140
	ds_read_b128 v[166:169], v140 offset:1024
	ds_read_b128 v[170:173], v140 offset:2048
	ds_read_b128 v[174:177], v140 offset:3072
	v_lshl_add_u64 v[140:141], s[56:57], 0, v[136:137]
	s_add_i32 m0, s10, 0xc000
	ds_read_b128 v[178:181], v145
	ds_read_b128 v[182:185], v145 offset:1024
	ds_read_b128 v[186:189], v145 offset:2048
	ds_read_b128 v[190:193], v145 offset:3072
	ds_read_b128 v[214:217], v145 offset:4096
	ds_read_b128 v[220:223], v145 offset:5120
	ds_read_b128 v[224:227], v145 offset:6144
	ds_read_b128 v[228:231], v145 offset:7168
	global_load_lds_dwordx4 v[140:141], off
	v_lshl_add_u64 v[140:141], s[56:57], 0, v[138:139]
	s_add_i32 m0, s10, 0xe000
	s_nop 0
	global_load_lds_dwordx4 v[140:141], off
	s_cmp_lt_i32 s55, 0
	s_cbranch_scc0 .Lrx18_0_norm
	s_cmp_lt_u32 s33, 2
	s_cbranch_scc1 .Lrx18_0_norm
	s_waitcnt vmcnt(24)
	s_branch .Lrx18_0_join

; __device__ __forceinline__ u32x4 pack8_bf16(f32x4 a, f32x4 b) { u32x4 w; w.x = cvt_pk_bf16(a[0], a[1]); w.y = cvt_pk_bf16(a[2], a[3]); w.z = cvt_pk_bf16(b[0], b[1]); w.w = cvt_pk_bf16(b[2], b[3]); return w; }
; #define ACT(t) (KBASE(t) <= qlo + QBLK - 1 && KBASE(t) + KVBLK - 1 >= qlo - W + 1)
;     __device__ __forceinline__ void operator()(const f32x4 (&acc)[2][2][4][2], const Unit& u, int wr, int wc, int fr, int fq) const {
;         const int g = u.pn / nNper, pnl = u.pn - g * nNper, pml = u.pm & 63;
;         bf16_t* base = O + (size_t)g * gstride;
;         const int row0 = pml * BM + wr * 64 + fr, col0 = pnl * BM + wc * 32 + 8 * fq;
; #pragma unroll
;         for (int ai = 0; ai < 2; ++ai)
; #pragma unroll
;             for (int m = 0; m < 4; ++m) { bf16_t* rowp = base + (size_t)(row0 + ai * HALF + m * 16) * ldc + col0;
; #pragma unroll
;                 for (int bj = 0; bj < 2; ++bj) { f32x4 v0 = acc[ai][bj][m][0], v1 = acc[ai][bj][m][1];
;                     if (ACT == 1) {
; #pragma unroll
;                         for (int j = 0; j < 4; ++j) { float a = fmaxf(v0[j], 0.f), b = fmaxf(v1[j], 0.f); v0[j] = a * a; v1[j] = b * b; } }
;                     *(u32x4*)(rowp + bj * HALF) = pack8_bf16(v0, v1); } }
.LBB0_62:
	s_ashr_i32 s7, s54, 31
	s_lshr_b32 s7, s7, 27
	s_add_i32 s7, s54, s7
	s_and_b32 s7, s7, 0xffffe0
	s_lshl_b32 s34, s52, 8
	s_sub_i32 s7, s54, s7
	s_and_b32 s34, s34, 0x3f00
	v_add_u32_e32 v146, s34, v142
	v_lshl_or_b32 v140, s7, 8, v144
	v_ashrrev_i32_e32 v141, 31, v140
	v_ashrrev_i32_e32 v147, 31, v146
	v_lshl_add_u64 v[148:149], v[140:141], 1, s[8:9]
	v_lshlrev_b64 v[140:141], 14, v[146:147]
	v_lshl_add_u64 v[140:141], v[148:149], 0, v[140:141]
	s_mov_b64 s[34:35], 0x40000
	v_mov_b32_e32 v242, 0x20000
	v_mov_b32_e32 v243, 0
	v_and_b32_e32 v238, 8, v208
	v_cmp_ne_u32_e32 vcc, 0, v238
	v_and_b32_e32 v240, 63, v208
	v_lshrrev_b32_e32 v241, 3, v240
	v_and_b32_e32 v244, 3, v240
	v_lshl_add_u32 v241, v244, 4, v241
	v_and_b32_e32 v244, 4, v240
	v_lshl_add_u32 v241, v244, 1, v241
	v_lshlrev_b32_e32 v240, 2, v241
	v_max_f32_e32 v124, 0, v124
	v_max_f32_e32 v125, 0, v125
	v_max_f32_e32 v126, 0, v126
	v_max_f32_e32 v127, 0, v127
	v_max_f32_e32 v120, 0, v120
	v_max_f32_e32 v121, 0, v121
	v_max_f32_e32 v122, 0, v122
	v_max_f32_e32 v123, 0, v123
	v_max_f32_e32 v116, 0, v116
	v_max_f32_e32 v117, 0, v117
	v_max_f32_e32 v118, 0, v118
	v_max_f32_e32 v119, 0, v119
	v_max_f32_e32 v112, 0, v112
	v_max_f32_e32 v113, 0, v113
	v_max_f32_e32 v114, 0, v114
	v_max_f32_e32 v115, 0, v115
	v_mul_f32_e32 v124, v124, v124
	v_mul_f32_e32 v125, v125, v125
	v_mul_f32_e32 v126, v126, v126
	v_mul_f32_e32 v127, v127, v127
	v_mul_f32_e32 v120, v120, v120
	v_mul_f32_e32 v121, v121, v121
	v_mul_f32_e32 v122, v122, v122
	v_mul_f32_e32 v123, v123, v123
	v_mul_f32_e32 v116, v116, v116
	v_mul_f32_e32 v117, v117, v117
	v_mul_f32_e32 v118, v118, v118
	v_mul_f32_e32 v119, v119, v119
	v_mul_f32_e32 v112, v112, v112
	v_mul_f32_e32 v113, v113, v113
	v_mul_f32_e32 v114, v114, v114
	v_mul_f32_e32 v115, v115, v115
	v_cvt_pk_bf16_f32 v124, v124, v125
	v_cvt_pk_bf16_f32 v125, v126, v127
	v_cvt_pk_bf16_f32 v126, v120, v121
	v_cvt_pk_bf16_f32 v127, v122, v123
	v_cvt_pk_bf16_f32 v116, v116, v117
	v_cvt_pk_bf16_f32 v117, v118, v119
	v_cvt_pk_bf16_f32 v118, v112, v113
	v_cvt_pk_bf16_f32 v119, v114, v115
	v_mov_b32_dpp v246, v116 row_ror:8 row_mask:0xf bank_mask:0xf
	v_mov_b32_dpp v247, v117 row_ror:8 row_mask:0xf bank_mask:0xf
	v_mov_b32_dpp v248, v118 row_ror:8 row_mask:0xf bank_mask:0xf
	v_mov_b32_dpp v249, v119 row_ror:8 row_mask:0xf bank_mask:0xf
	v_mov_b32_dpp v250, v124 row_ror:8 row_mask:0xf bank_mask:0xf
	v_mov_b32_dpp v251, v125 row_ror:8 row_mask:0xf bank_mask:0xf
	v_mov_b32_dpp v252, v126 row_ror:8 row_mask:0xf bank_mask:0xf
	v_mov_b32_dpp v253, v127 row_ror:8 row_mask:0xf bank_mask:0xf
	v_cndmask_b32_e32 v246, v124, v246, vcc
	v_cndmask_b32_e32 v247, v125, v247, vcc
	v_cndmask_b32_e32 v248, v126, v248, vcc
	v_cndmask_b32_e32 v249, v127, v249, vcc
	v_cndmask_b32_e32 v250, v250, v116, vcc
	v_cndmask_b32_e32 v251, v251, v117, vcc
	v_cndmask_b32_e32 v252, v252, v118, vcc
	v_cndmask_b32_e32 v253, v253, v119, vcc
	ds_bpermute_b32 v246, v240, v246
	ds_bpermute_b32 v247, v240, v247
	ds_bpermute_b32 v248, v240, v248
	ds_bpermute_b32 v249, v240, v249
	ds_bpermute_b32 v250, v240, v250
	ds_bpermute_b32 v251, v240, v251
	ds_bpermute_b32 v252, v240, v252
	ds_bpermute_b32 v253, v240, v253
	v_mov_b32_e32 v124, 0
	v_mov_b32_e32 v125, 0
	v_mov_b32_e32 v126, 0
	v_mov_b32_e32 v127, 0
	v_mov_b32_e32 v120, 0
	v_mov_b32_e32 v121, 0
	v_mov_b32_e32 v122, 0
	v_mov_b32_e32 v123, 0
	v_mov_b32_e32 v116, 0
	v_mov_b32_e32 v117, 0
	v_mov_b32_e32 v118, 0
	v_mov_b32_e32 v119, 0
	v_mov_b32_e32 v112, 0
	v_mov_b32_e32 v113, 0
	v_mov_b32_e32 v114, 0
	v_mov_b32_e32 v115, 0
	v_lshl_add_u64 v[238:239], v[140:141], 0, v[242:243]
	s_waitcnt lgkmcnt(4)
	global_store_dwordx4 v[140:141], v[246:249], off
	s_waitcnt lgkmcnt(0)
	global_store_dwordx4 v[238:239], v[250:253], off
	v_lshl_add_u64 v[140:141], v[140:141], 0, s[34:35]
	v_max_f32_e32 v108, 0, v108
	v_max_f32_e32 v109, 0, v109
	v_max_f32_e32 v110, 0, v110
	v_max_f32_e32 v111, 0, v111
	v_max_f32_e32 v104, 0, v104
	v_max_f32_e32 v105, 0, v105
	v_max_f32_e32 v106, 0, v106
	v_max_f32_e32 v107, 0, v107
	v_max_f32_e32 v100, 0, v100
	v_max_f32_e32 v101, 0, v101
	v_max_f32_e32 v102, 0, v102
	v_max_f32_e32 v103, 0, v103
	v_max_f32_e32 v96, 0, v96
	v_max_f32_e32 v97, 0, v97
	v_max_f32_e32 v98, 0, v98
	v_max_f32_e32 v99, 0, v99
	v_mul_f32_e32 v108, v108, v108
	v_mul_f32_e32 v109, v109, v109
	v_mul_f32_e32 v110, v110, v110
	v_mul_f32_e32 v111, v111, v111
	v_mul_f32_e32 v104, v104, v104
	v_mul_f32_e32 v105, v105, v105
	v_mul_f32_e32 v106, v106, v106
	v_mul_f32_e32 v107, v107, v107
	v_mul_f32_e32 v100, v100, v100
	v_mul_f32_e32 v101, v101, v101
	v_mul_f32_e32 v102, v102, v102
	v_mul_f32_e32 v103, v103, v103
	v_mul_f32_e32 v96, v96, v96
	v_mul_f32_e32 v97, v97, v97
	v_mul_f32_e32 v98, v98, v98
	v_mul_f32_e32 v99, v99, v99
	v_cvt_pk_bf16_f32 v108, v108, v109
	v_cvt_pk_bf16_f32 v109, v110, v111
	v_cvt_pk_bf16_f32 v110, v104, v105
	v_cvt_pk_bf16_f32 v111, v106, v107
	v_cvt_pk_bf16_f32 v100, v100, v101
	v_cvt_pk_bf16_f32 v101, v102, v103
	v_cvt_pk_bf16_f32 v102, v96, v97
	v_cvt_pk_bf16_f32 v103, v98, v99
	v_mov_b32_dpp v246, v100 row_ror:8 row_mask:0xf bank_mask:0xf
	v_mov_b32_dpp v247, v101 row_ror:8 row_mask:0xf bank_mask:0xf
	v_mov_b32_dpp v248, v102 row_ror:8 row_mask:0xf bank_mask:0xf
	v_mov_b32_dpp v249, v103 row_ror:8 row_mask:0xf bank_mask:0xf
	v_mov_b32_dpp v250, v108 row_ror:8 row_mask:0xf bank_mask:0xf
	v_mov_b32_dpp v251, v109 row_ror:8 row_mask:0xf bank_mask:0xf
	v_mov_b32_dpp v252, v110 row_ror:8 row_mask:0xf bank_mask:0xf
	v_mov_b32_dpp v253, v111 row_ror:8 row_mask:0xf bank_mask:0xf
	v_cndmask_b32_e32 v246, v108, v246, vcc
	v_cndmask_b32_e32 v247, v109, v247, vcc
	v_cndmask_b32_e32 v248, v110, v248, vcc
	v_cndmask_b32_e32 v249, v111, v249, vcc
	v_cndmask_b32_e32 v250, v250, v100, vcc
	v_cndmask_b32_e32 v251, v251, v101, vcc
	v_cndmask_b32_e32 v252, v252, v102, vcc
	v_cndmask_b32_e32 v253, v253, v103, vcc
	ds_bpermute_b32 v246, v240, v246
	ds_bpermute_b32 v247, v240, v247
	ds_bpermute_b32 v248, v240, v248
	ds_bpermute_b32 v249, v240, v249
	ds_bpermute_b32 v250, v240, v250
	ds_bpermute_b32 v251, v240, v251
	ds_bpermute_b32 v252, v240, v252
	ds_bpermute_b32 v253, v240, v253
	v_mov_b32_e32 v108, 0
	v_mov_b32_e32 v109, 0
	v_mov_b32_e32 v110, 0
	v_mov_b32_e32 v111, 0
	v_mov_b32_e32 v104, 0
	v_mov_b32_e32 v105, 0
	v_mov_b32_e32 v106, 0
	v_mov_b32_e32 v107, 0
	v_mov_b32_e32 v100, 0
	v_mov_b32_e32 v101, 0
	v_mov_b32_e32 v102, 0
	v_mov_b32_e32 v103, 0
	v_mov_b32_e32 v96, 0
	v_mov_b32_e32 v97, 0
	v_mov_b32_e32 v98, 0
	v_mov_b32_e32 v99, 0
	v_lshl_add_u64 v[238:239], v[140:141], 0, v[242:243]
	s_waitcnt lgkmcnt(4)
; __device__ __forceinline__ u32x4 pack8_bf16(f32x4 a, f32x4 b) { u32x4 w; w.x = cvt_pk_bf16(a[0], a[1]); w.y = cvt_pk_bf16(a[2], a[3]); w.z = cvt_pk_bf16(b[0], b[1]); w.w = cvt_pk_bf16(b[2], b[3]); return w; }
; #define ACT(t) (KBASE(t) <= qlo + QBLK - 1 && KBASE(t) + KVBLK - 1 >= qlo - W + 1)
;     __device__ __forceinline__ void operator()(const f32x4 (&acc)[2][2][4][2], const Unit& u, int wr, int wc, int fr, int fq) const {
;     ...
;             for (int m = 0; m < 4; ++m) { bf16_t* rowp = base + (size_t)(row0 + ai * HALF + m * 16) * ldc + col0;
; #pragma unroll
;                 for (int bj = 0; bj < 2; ++bj) { f32x4 v0 = acc[ai][bj][m][0], v1 = acc[ai][bj][m][1];
;                     if (ACT == 1) {
; #pragma unroll
;                         for (int j = 0; j < 4; ++j) { float a = fmaxf(v0[j], 0.f), b = fmaxf(v1[j], 0.f); v0[j] = a * a; v1[j] = b * b; } }
;                     *(u32x4*)(rowp + bj * HALF) = pack8_bf16(v0, v1); } }
	global_store_dwordx4 v[140:141], v[246:249], off
	s_waitcnt lgkmcnt(0)
	global_store_dwordx4 v[238:239], v[250:253], off
	v_lshl_add_u64 v[140:141], v[140:141], 0, s[34:35]
	v_max_f32_e32 v92, 0, v92
	v_max_f32_e32 v93, 0, v93
	v_max_f32_e32 v94, 0, v94
	v_max_f32_e32 v95, 0, v95
	v_max_f32_e32 v88, 0, v88
	v_max_f32_e32 v89, 0, v89
	v_max_f32_e32 v90, 0, v90
	v_max_f32_e32 v91, 0, v91
	v_max_f32_e32 v84, 0, v84
	v_max_f32_e32 v85, 0, v85
	v_max_f32_e32 v86, 0, v86
	v_max_f32_e32 v87, 0, v87
	v_max_f32_e32 v80, 0, v80
	v_max_f32_e32 v81, 0, v81
	v_max_f32_e32 v82, 0, v82
	v_max_f32_e32 v83, 0, v83
	v_mul_f32_e32 v92, v92, v92
	v_mul_f32_e32 v93, v93, v93
	v_mul_f32_e32 v94, v94, v94
	v_mul_f32_e32 v95, v95, v95
	v_mul_f32_e32 v88, v88, v88
	v_mul_f32_e32 v89, v89, v89
	v_mul_f32_e32 v90, v90, v90
	v_mul_f32_e32 v91, v91, v91
	v_mul_f32_e32 v84, v84, v84
	v_mul_f32_e32 v85, v85, v85
	v_mul_f32_e32 v86, v86, v86
	v_mul_f32_e32 v87, v87, v87
	v_mul_f32_e32 v80, v80, v80
	v_mul_f32_e32 v81, v81, v81
	v_mul_f32_e32 v82, v82, v82
	v_mul_f32_e32 v83, v83, v83
	v_cvt_pk_bf16_f32 v92, v92, v93
	v_cvt_pk_bf16_f32 v93, v94, v95
	v_cvt_pk_bf16_f32 v94, v88, v89
	v_cvt_pk_bf16_f32 v95, v90, v91
	v_cvt_pk_bf16_f32 v84, v84, v85
	v_cvt_pk_bf16_f32 v85, v86, v87
	v_cvt_pk_bf16_f32 v86, v80, v81
	v_cvt_pk_bf16_f32 v87, v82, v83
	v_mov_b32_dpp v246, v84 row_ror:8 row_mask:0xf bank_mask:0xf
	v_mov_b32_dpp v247, v85 row_ror:8 row_mask:0xf bank_mask:0xf
	v_mov_b32_dpp v248, v86 row_ror:8 row_mask:0xf bank_mask:0xf
	v_mov_b32_dpp v249, v87 row_ror:8 row_mask:0xf bank_mask:0xf
	v_mov_b32_dpp v250, v92 row_ror:8 row_mask:0xf bank_mask:0xf
	v_mov_b32_dpp v251, v93 row_ror:8 row_mask:0xf bank_mask:0xf
	v_mov_b32_dpp v252, v94 row_ror:8 row_mask:0xf bank_mask:0xf
	v_mov_b32_dpp v253, v95 row_ror:8 row_mask:0xf bank_mask:0xf
	v_cndmask_b32_e32 v246, v92, v246, vcc
	v_cndmask_b32_e32 v247, v93, v247, vcc
	v_cndmask_b32_e32 v248, v94, v248, vcc
	v_cndmask_b32_e32 v249, v95, v249, vcc
	v_cndmask_b32_e32 v250, v250, v84, vcc
	v_cndmask_b32_e32 v251, v251, v85, vcc
	v_cndmask_b32_e32 v252, v252, v86, vcc
	v_cndmask_b32_e32 v253, v253, v87, vcc
	ds_bpermute_b32 v246, v240, v246
	ds_bpermute_b32 v247, v240, v247
	ds_bpermute_b32 v248, v240, v248
	ds_bpermute_b32 v249, v240, v249
	ds_bpermute_b32 v250, v240, v250
	ds_bpermute_b32 v251, v240, v251
	ds_bpermute_b32 v252, v240, v252
	ds_bpermute_b32 v253, v240, v253
	v_mov_b32_e32 v92, 0
	v_mov_b32_e32 v93, 0
	v_mov_b32_e32 v94, 0
	v_mov_b32_e32 v95, 0
	v_mov_b32_e32 v88, 0
	v_mov_b32_e32 v89, 0
	v_mov_b32_e32 v90, 0
	v_mov_b32_e32 v91, 0
	v_mov_b32_e32 v84, 0
	v_mov_b32_e32 v85, 0
	v_mov_b32_e32 v86, 0
	v_mov_b32_e32 v87, 0
	v_mov_b32_e32 v80, 0
	v_mov_b32_e32 v81, 0
	v_mov_b32_e32 v82, 0
	v_mov_b32_e32 v83, 0
	v_lshl_add_u64 v[238:239], v[140:141], 0, v[242:243]
	s_waitcnt lgkmcnt(4)
	global_store_dwordx4 v[140:141], v[246:249], off
	s_waitcnt lgkmcnt(0)
	global_store_dwordx4 v[238:239], v[250:253], off
	v_lshl_add_u64 v[140:141], v[140:141], 0, s[34:35]
	v_max_f32_e32 v76, 0, v76
	v_max_f32_e32 v77, 0, v77
	v_max_f32_e32 v78, 0, v78
	v_max_f32_e32 v79, 0, v79
	v_max_f32_e32 v72, 0, v72
	v_max_f32_e32 v73, 0, v73
	v_max_f32_e32 v74, 0, v74
	v_max_f32_e32 v75, 0, v75
	v_max_f32_e32 v68, 0, v68
	v_max_f32_e32 v69, 0, v69
	v_max_f32_e32 v70, 0, v70
	v_max_f32_e32 v71, 0, v71
	v_max_f32_e32 v64, 0, v64
	v_max_f32_e32 v65, 0, v65
	v_max_f32_e32 v66, 0, v66
	v_max_f32_e32 v67, 0, v67
	v_mul_f32_e32 v76, v76, v76
	v_mul_f32_e32 v77, v77, v77
	v_mul_f32_e32 v78, v78, v78
	v_mul_f32_e32 v79, v79, v79
	v_mul_f32_e32 v72, v72, v72
	v_mul_f32_e32 v73, v73, v73
	v_mul_f32_e32 v74, v74, v74
	v_mul_f32_e32 v75, v75, v75
	v_mul_f32_e32 v68, v68, v68
	v_mul_f32_e32 v69, v69, v69
	v_mul_f32_e32 v70, v70, v70
	v_mul_f32_e32 v71, v71, v71
	v_mul_f32_e32 v64, v64, v64
	v_mul_f32_e32 v65, v65, v65
	v_mul_f32_e32 v66, v66, v66
	v_mul_f32_e32 v67, v67, v67
	v_cvt_pk_bf16_f32 v76, v76, v77
	v_cvt_pk_bf16_f32 v77, v78, v79
	v_cvt_pk_bf16_f32 v78, v72, v73
	v_cvt_pk_bf16_f32 v79, v74, v75
	v_cvt_pk_bf16_f32 v68, v68, v69
	v_cvt_pk_bf16_f32 v69, v70, v71
	v_cvt_pk_bf16_f32 v70, v64, v65
	v_cvt_pk_bf16_f32 v71, v66, v67
	v_mov_b32_dpp v246, v68 row_ror:8 row_mask:0xf bank_mask:0xf
	v_mov_b32_dpp v247, v69 row_ror:8 row_mask:0xf bank_mask:0xf
	v_mov_b32_dpp v248, v70 row_ror:8 row_mask:0xf bank_mask:0xf
	v_mov_b32_dpp v249, v71 row_ror:8 row_mask:0xf bank_mask:0xf
	v_mov_b32_dpp v250, v76 row_ror:8 row_mask:0xf bank_mask:0xf
	v_mov_b32_dpp v251, v77 row_ror:8 row_mask:0xf bank_mask:0xf
	v_mov_b32_dpp v252, v78 row_ror:8 row_mask:0xf bank_mask:0xf
	v_mov_b32_dpp v253, v79 row_ror:8 row_mask:0xf bank_mask:0xf
	v_cndmask_b32_e32 v246, v76, v246, vcc
	v_cndmask_b32_e32 v247, v77, v247, vcc
	v_cndmask_b32_e32 v248, v78, v248, vcc
	v_cndmask_b32_e32 v249, v79, v249, vcc
	v_cndmask_b32_e32 v250, v250, v68, vcc
	v_cndmask_b32_e32 v251, v251, v69, vcc
	v_cndmask_b32_e32 v252, v252, v70, vcc
	v_cndmask_b32_e32 v253, v253, v71, vcc
	ds_bpermute_b32 v246, v240, v246
	ds_bpermute_b32 v247, v240, v247
	ds_bpermute_b32 v248, v240, v248
	ds_bpermute_b32 v249, v240, v249
	ds_bpermute_b32 v250, v240, v250
	ds_bpermute_b32 v251, v240, v251
	ds_bpermute_b32 v252, v240, v252
	ds_bpermute_b32 v253, v240, v253
	v_mov_b32_e32 v76, 0
	v_mov_b32_e32 v77, 0
	v_mov_b32_e32 v78, 0
	v_mov_b32_e32 v79, 0
	v_mov_b32_e32 v72, 0
	v_mov_b32_e32 v73, 0
	v_mov_b32_e32 v74, 0
	v_mov_b32_e32 v75, 0
	v_mov_b32_e32 v68, 0
	v_mov_b32_e32 v69, 0
	v_mov_b32_e32 v70, 0
	v_mov_b32_e32 v71, 0
	v_mov_b32_e32 v64, 0
	v_mov_b32_e32 v65, 0
	v_mov_b32_e32 v66, 0
	v_mov_b32_e32 v67, 0
	v_lshl_add_u64 v[238:239], v[140:141], 0, v[242:243]
	s_waitcnt lgkmcnt(4)
; __device__ __forceinline__ u32x4 pack8_bf16(f32x4 a, f32x4 b) { u32x4 w; w.x = cvt_pk_bf16(a[0], a[1]); w.y = cvt_pk_bf16(a[2], a[3]); w.z = cvt_pk_bf16(b[0], b[1]); w.w = cvt_pk_bf16(b[2], b[3]); return w; }
; #define ACT(t) (KBASE(t) <= qlo + QBLK - 1 && KBASE(t) + KVBLK - 1 >= qlo - W + 1)
;     __device__ __forceinline__ void operator()(const f32x4 (&acc)[2][2][4][2], const Unit& u, int wr, int wc, int fr, int fq) const {
;     ...
;             for (int m = 0; m < 4; ++m) { bf16_t* rowp = base + (size_t)(row0 + ai * HALF + m * 16) * ldc + col0;
; #pragma unroll
;                 for (int bj = 0; bj < 2; ++bj) { f32x4 v0 = acc[ai][bj][m][0], v1 = acc[ai][bj][m][1];
;                     if (ACT == 1) {
; #pragma unroll
;                         for (int j = 0; j < 4; ++j) { float a = fmaxf(v0[j], 0.f), b = fmaxf(v1[j], 0.f); v0[j] = a * a; v1[j] = b * b; } }
;                     *(u32x4*)(rowp + bj * HALF) = pack8_bf16(v0, v1); } }
	global_store_dwordx4 v[140:141], v[246:249], off
	s_waitcnt lgkmcnt(0)
	global_store_dwordx4 v[238:239], v[250:253], off
	s_mov_b64 s[34:35], 0x140000
	v_lshl_add_u64 v[140:141], v[140:141], 0, s[34:35]
	s_mov_b64 s[34:35], 0x40000
	v_max_f32_e32 v60, 0, v60
	v_max_f32_e32 v61, 0, v61
	v_max_f32_e32 v62, 0, v62
	v_max_f32_e32 v63, 0, v63
	v_max_f32_e32 v56, 0, v56
	v_max_f32_e32 v57, 0, v57
	v_max_f32_e32 v58, 0, v58
	v_max_f32_e32 v59, 0, v59
	v_max_f32_e32 v52, 0, v52
	v_max_f32_e32 v53, 0, v53
	v_max_f32_e32 v54, 0, v54
	v_max_f32_e32 v55, 0, v55
	v_max_f32_e32 v48, 0, v48
	v_max_f32_e32 v49, 0, v49
	v_max_f32_e32 v50, 0, v50
	v_max_f32_e32 v51, 0, v51
	v_mul_f32_e32 v60, v60, v60
	v_mul_f32_e32 v61, v61, v61
	v_mul_f32_e32 v62, v62, v62
	v_mul_f32_e32 v63, v63, v63
	v_mul_f32_e32 v56, v56, v56
	v_mul_f32_e32 v57, v57, v57
	v_mul_f32_e32 v58, v58, v58
	v_mul_f32_e32 v59, v59, v59
	v_mul_f32_e32 v52, v52, v52
	v_mul_f32_e32 v53, v53, v53
	v_mul_f32_e32 v54, v54, v54
	v_mul_f32_e32 v55, v55, v55
	v_mul_f32_e32 v48, v48, v48
	v_mul_f32_e32 v49, v49, v49
	v_mul_f32_e32 v50, v50, v50
	v_mul_f32_e32 v51, v51, v51
	v_cvt_pk_bf16_f32 v60, v60, v61
	v_cvt_pk_bf16_f32 v61, v62, v63
	v_cvt_pk_bf16_f32 v62, v56, v57
	v_cvt_pk_bf16_f32 v63, v58, v59
	v_cvt_pk_bf16_f32 v52, v52, v53
	v_cvt_pk_bf16_f32 v53, v54, v55
	v_cvt_pk_bf16_f32 v54, v48, v49
	v_cvt_pk_bf16_f32 v55, v50, v51
	v_mov_b32_dpp v246, v52 row_ror:8 row_mask:0xf bank_mask:0xf
	v_mov_b32_dpp v247, v53 row_ror:8 row_mask:0xf bank_mask:0xf
	v_mov_b32_dpp v248, v54 row_ror:8 row_mask:0xf bank_mask:0xf
	v_mov_b32_dpp v249, v55 row_ror:8 row_mask:0xf bank_mask:0xf
	v_mov_b32_dpp v250, v60 row_ror:8 row_mask:0xf bank_mask:0xf
	v_mov_b32_dpp v251, v61 row_ror:8 row_mask:0xf bank_mask:0xf
	v_mov_b32_dpp v252, v62 row_ror:8 row_mask:0xf bank_mask:0xf
	v_mov_b32_dpp v253, v63 row_ror:8 row_mask:0xf bank_mask:0xf
	v_cndmask_b32_e32 v246, v60, v246, vcc
	v_cndmask_b32_e32 v247, v61, v247, vcc
	v_cndmask_b32_e32 v248, v62, v248, vcc
	v_cndmask_b32_e32 v249, v63, v249, vcc
	v_cndmask_b32_e32 v250, v250, v52, vcc
	v_cndmask_b32_e32 v251, v251, v53, vcc
	v_cndmask_b32_e32 v252, v252, v54, vcc
	v_cndmask_b32_e32 v253, v253, v55, vcc
	ds_bpermute_b32 v246, v240, v246
	ds_bpermute_b32 v247, v240, v247
	ds_bpermute_b32 v248, v240, v248
	ds_bpermute_b32 v249, v240, v249
	ds_bpermute_b32 v250, v240, v250
	ds_bpermute_b32 v251, v240, v251
	ds_bpermute_b32 v252, v240, v252
	ds_bpermute_b32 v253, v240, v253
	v_mov_b32_e32 v60, 0
	v_mov_b32_e32 v61, 0
	v_mov_b32_e32 v62, 0
	v_mov_b32_e32 v63, 0
	v_mov_b32_e32 v56, 0
	v_mov_b32_e32 v57, 0
	v_mov_b32_e32 v58, 0
	v_mov_b32_e32 v59, 0
	v_mov_b32_e32 v52, 0
	v_mov_b32_e32 v53, 0
	v_mov_b32_e32 v54, 0
	v_mov_b32_e32 v55, 0
	v_mov_b32_e32 v48, 0
	v_mov_b32_e32 v49, 0
	v_mov_b32_e32 v50, 0
	v_mov_b32_e32 v51, 0
	v_lshl_add_u64 v[238:239], v[140:141], 0, v[242:243]
	s_waitcnt lgkmcnt(4)
	global_store_dwordx4 v[140:141], v[246:249], off
	s_waitcnt lgkmcnt(0)
	global_store_dwordx4 v[238:239], v[250:253], off
	v_lshl_add_u64 v[140:141], v[140:141], 0, s[34:35]
	v_max_f32_e32 v44, 0, v44
	v_max_f32_e32 v45, 0, v45
	v_max_f32_e32 v46, 0, v46
	v_max_f32_e32 v47, 0, v47
	v_max_f32_e32 v40, 0, v40
	v_max_f32_e32 v41, 0, v41
	v_max_f32_e32 v42, 0, v42
	v_max_f32_e32 v43, 0, v43
	v_max_f32_e32 v36, 0, v36
	v_max_f32_e32 v37, 0, v37
	v_max_f32_e32 v38, 0, v38
	v_max_f32_e32 v39, 0, v39
	v_max_f32_e32 v32, 0, v32
	v_max_f32_e32 v33, 0, v33
	v_max_f32_e32 v34, 0, v34
	v_max_f32_e32 v35, 0, v35
	v_mul_f32_e32 v44, v44, v44
	v_mul_f32_e32 v45, v45, v45
	v_mul_f32_e32 v46, v46, v46
	v_mul_f32_e32 v47, v47, v47
	v_mul_f32_e32 v40, v40, v40
	v_mul_f32_e32 v41, v41, v41
	v_mul_f32_e32 v42, v42, v42
	v_mul_f32_e32 v43, v43, v43
	v_mul_f32_e32 v36, v36, v36
	v_mul_f32_e32 v37, v37, v37
	v_mul_f32_e32 v38, v38, v38
	v_mul_f32_e32 v39, v39, v39
	v_mul_f32_e32 v32, v32, v32
	v_mul_f32_e32 v33, v33, v33
	v_mul_f32_e32 v34, v34, v34
	v_mul_f32_e32 v35, v35, v35
	v_cvt_pk_bf16_f32 v44, v44, v45
	v_cvt_pk_bf16_f32 v45, v46, v47
	v_cvt_pk_bf16_f32 v46, v40, v41
	v_cvt_pk_bf16_f32 v47, v42, v43
	v_cvt_pk_bf16_f32 v36, v36, v37
	v_cvt_pk_bf16_f32 v37, v38, v39
	v_cvt_pk_bf16_f32 v38, v32, v33
	v_cvt_pk_bf16_f32 v39, v34, v35
	v_mov_b32_dpp v246, v36 row_ror:8 row_mask:0xf bank_mask:0xf
	v_mov_b32_dpp v247, v37 row_ror:8 row_mask:0xf bank_mask:0xf
	v_mov_b32_dpp v248, v38 row_ror:8 row_mask:0xf bank_mask:0xf
	v_mov_b32_dpp v249, v39 row_ror:8 row_mask:0xf bank_mask:0xf
	v_mov_b32_dpp v250, v44 row_ror:8 row_mask:0xf bank_mask:0xf
	v_mov_b32_dpp v251, v45 row_ror:8 row_mask:0xf bank_mask:0xf
	v_mov_b32_dpp v252, v46 row_ror:8 row_mask:0xf bank_mask:0xf
	v_mov_b32_dpp v253, v47 row_ror:8 row_mask:0xf bank_mask:0xf
	v_cndmask_b32_e32 v246, v44, v246, vcc
	v_cndmask_b32_e32 v247, v45, v247, vcc
	v_cndmask_b32_e32 v248, v46, v248, vcc
	v_cndmask_b32_e32 v249, v47, v249, vcc
	v_cndmask_b32_e32 v250, v250, v36, vcc
	v_cndmask_b32_e32 v251, v251, v37, vcc
	v_cndmask_b32_e32 v252, v252, v38, vcc
	v_cndmask_b32_e32 v253, v253, v39, vcc
	ds_bpermute_b32 v246, v240, v246
	ds_bpermute_b32 v247, v240, v247
	ds_bpermute_b32 v248, v240, v248
	ds_bpermute_b32 v249, v240, v249
	ds_bpermute_b32 v250, v240, v250
	ds_bpermute_b32 v251, v240, v251
	ds_bpermute_b32 v252, v240, v252
	ds_bpermute_b32 v253, v240, v253
	v_mov_b32_e32 v44, 0
	v_mov_b32_e32 v45, 0
	v_mov_b32_e32 v46, 0
	v_mov_b32_e32 v47, 0
	v_mov_b32_e32 v40, 0
	v_mov_b32_e32 v41, 0
	v_mov_b32_e32 v42, 0
	v_mov_b32_e32 v43, 0
	v_mov_b32_e32 v36, 0
	v_mov_b32_e32 v37, 0
	v_mov_b32_e32 v38, 0
	v_mov_b32_e32 v39, 0
	v_mov_b32_e32 v32, 0
	v_mov_b32_e32 v33, 0
	v_mov_b32_e32 v34, 0
	v_mov_b32_e32 v35, 0
	v_lshl_add_u64 v[238:239], v[140:141], 0, v[242:243]
	s_waitcnt lgkmcnt(4)
; __device__ __forceinline__ u32x4 pack8_bf16(f32x4 a, f32x4 b) { u32x4 w; w.x = cvt_pk_bf16(a[0], a[1]); w.y = cvt_pk_bf16(a[2], a[3]); w.z = cvt_pk_bf16(b[0], b[1]); w.w = cvt_pk_bf16(b[2], b[3]); return w; }
; #define PG8_BAR __builtin_amdgcn_s_barrier()
; #define ACT(t) (KBASE(t) <= qlo + QBLK - 1 && KBASE(t) + KVBLK - 1 >= qlo - W + 1)
;     __device__ __forceinline__ void operator()(const f32x4 (&acc)[2][2][4][2], const Unit& u, int wr, int wc, int fr, int fq) const {
;     ...
;             for (int m = 0; m < 4; ++m) { bf16_t* rowp = base + (size_t)(row0 + ai * HALF + m * 16) * ldc + col0;
; #pragma unroll
;                 for (int bj = 0; bj < 2; ++bj) { f32x4 v0 = acc[ai][bj][m][0], v1 = acc[ai][bj][m][1];
;                     if (ACT == 1) {
; #pragma unroll
;                         for (int j = 0; j < 4; ++j) { float a = fmaxf(v0[j], 0.f), b = fmaxf(v1[j], 0.f); v0[j] = a * a; v1[j] = b * b; } }
;                     *(u32x4*)(rowp + bj * HALF) = pack8_bf16(v0, v1); } }
; template <class Epi, class Sched, bool ALIGN_EPI = false, bool SP2 = false>
; __device__ __forceinline__ void gemm_phase(PG8_LAS unsigned char* lds, const Gemm g, const Sched& S, const Epi& E) {
;     ...
;         if (!has_next) break;
; #pragma unroll
;         for (int a = 0; a < 2; ++a)
; #pragma unroll
;             for (int b = 0; b < 2; ++b)
; #pragma unroll
;                 for (int m = 0; m < 4; ++m)
; #pragma unroll
;                     for (int n = 0; n < 2; ++n) acc[a][b][m][n] = (f32x4){0.f, 0.f, 0.f, 0.f};
;         cur = nxt; cA = nA; cB = nB; ++ui;
;         if constexpr (ALIGN_EPI) { if (wr == 1) PG8_BAR; }
	global_store_dwordx4 v[140:141], v[246:249], off
	s_waitcnt lgkmcnt(0)
	global_store_dwordx4 v[238:239], v[250:253], off
	v_lshl_add_u64 v[140:141], v[140:141], 0, s[34:35]
	v_max_f32_e32 v28, 0, v28
	v_max_f32_e32 v29, 0, v29
	v_max_f32_e32 v30, 0, v30
	v_max_f32_e32 v31, 0, v31
	v_max_f32_e32 v24, 0, v24
	v_max_f32_e32 v25, 0, v25
	v_max_f32_e32 v26, 0, v26
	v_max_f32_e32 v27, 0, v27
	v_max_f32_e32 v20, 0, v20
	v_max_f32_e32 v21, 0, v21
	v_max_f32_e32 v22, 0, v22
	v_max_f32_e32 v23, 0, v23
	v_max_f32_e32 v16, 0, v16
	v_max_f32_e32 v17, 0, v17
	v_max_f32_e32 v18, 0, v18
	v_max_f32_e32 v19, 0, v19
	v_mul_f32_e32 v28, v28, v28
	v_mul_f32_e32 v29, v29, v29
	v_mul_f32_e32 v30, v30, v30
	v_mul_f32_e32 v31, v31, v31
	v_mul_f32_e32 v24, v24, v24
	v_mul_f32_e32 v25, v25, v25
	v_mul_f32_e32 v26, v26, v26
	v_mul_f32_e32 v27, v27, v27
	v_mul_f32_e32 v20, v20, v20
	v_mul_f32_e32 v21, v21, v21
	v_mul_f32_e32 v22, v22, v22
	v_mul_f32_e32 v23, v23, v23
	v_mul_f32_e32 v16, v16, v16
	v_mul_f32_e32 v17, v17, v17
	v_mul_f32_e32 v18, v18, v18
	v_mul_f32_e32 v19, v19, v19
	v_cvt_pk_bf16_f32 v28, v28, v29
	v_cvt_pk_bf16_f32 v29, v30, v31
	v_cvt_pk_bf16_f32 v30, v24, v25
	v_cvt_pk_bf16_f32 v31, v26, v27
	v_cvt_pk_bf16_f32 v20, v20, v21
	v_cvt_pk_bf16_f32 v21, v22, v23
	v_cvt_pk_bf16_f32 v22, v16, v17
	v_cvt_pk_bf16_f32 v23, v18, v19
	v_mov_b32_dpp v246, v20 row_ror:8 row_mask:0xf bank_mask:0xf
	v_mov_b32_dpp v247, v21 row_ror:8 row_mask:0xf bank_mask:0xf
	v_mov_b32_dpp v248, v22 row_ror:8 row_mask:0xf bank_mask:0xf
	v_mov_b32_dpp v249, v23 row_ror:8 row_mask:0xf bank_mask:0xf
	v_mov_b32_dpp v250, v28 row_ror:8 row_mask:0xf bank_mask:0xf
	v_mov_b32_dpp v251, v29 row_ror:8 row_mask:0xf bank_mask:0xf
	v_mov_b32_dpp v252, v30 row_ror:8 row_mask:0xf bank_mask:0xf
	v_mov_b32_dpp v253, v31 row_ror:8 row_mask:0xf bank_mask:0xf
	v_cndmask_b32_e32 v246, v28, v246, vcc
	v_cndmask_b32_e32 v247, v29, v247, vcc
	v_cndmask_b32_e32 v248, v30, v248, vcc
	v_cndmask_b32_e32 v249, v31, v249, vcc
	v_cndmask_b32_e32 v250, v250, v20, vcc
	v_cndmask_b32_e32 v251, v251, v21, vcc
	v_cndmask_b32_e32 v252, v252, v22, vcc
	v_cndmask_b32_e32 v253, v253, v23, vcc
	ds_bpermute_b32 v246, v240, v246
	ds_bpermute_b32 v247, v240, v247
	ds_bpermute_b32 v248, v240, v248
	ds_bpermute_b32 v249, v240, v249
	ds_bpermute_b32 v250, v240, v250
	ds_bpermute_b32 v251, v240, v251
	ds_bpermute_b32 v252, v240, v252
	ds_bpermute_b32 v253, v240, v253
	v_mov_b32_e32 v28, 0
	v_mov_b32_e32 v29, 0
	v_mov_b32_e32 v30, 0
	v_mov_b32_e32 v31, 0
	v_mov_b32_e32 v24, 0
	v_mov_b32_e32 v25, 0
	v_mov_b32_e32 v26, 0
	v_mov_b32_e32 v27, 0
	v_mov_b32_e32 v20, 0
	v_mov_b32_e32 v21, 0
	v_mov_b32_e32 v22, 0
	v_mov_b32_e32 v23, 0
	v_mov_b32_e32 v16, 0
	v_mov_b32_e32 v17, 0
	v_mov_b32_e32 v18, 0
	v_mov_b32_e32 v19, 0
	v_lshl_add_u64 v[238:239], v[140:141], 0, v[242:243]
	s_waitcnt lgkmcnt(4)
	global_store_dwordx4 v[140:141], v[246:249], off
	s_waitcnt lgkmcnt(0)
	global_store_dwordx4 v[238:239], v[250:253], off
	v_lshl_add_u64 v[140:141], v[140:141], 0, s[34:35]
	v_max_f32_e32 v12, 0, v12
	v_max_f32_e32 v13, 0, v13
	v_max_f32_e32 v14, 0, v14
	v_max_f32_e32 v15, 0, v15
	v_max_f32_e32 v8, 0, v8
	v_max_f32_e32 v9, 0, v9
	v_max_f32_e32 v10, 0, v10
	v_max_f32_e32 v11, 0, v11
	v_max_f32_e32 v4, 0, v4
	v_max_f32_e32 v5, 0, v5
	v_max_f32_e32 v6, 0, v6
	v_max_f32_e32 v7, 0, v7
	v_max_f32_e32 v0, 0, v0
	v_max_f32_e32 v1, 0, v1
	v_max_f32_e32 v2, 0, v2
	v_max_f32_e32 v3, 0, v3
	v_mul_f32_e32 v12, v12, v12
	v_mul_f32_e32 v13, v13, v13
	v_mul_f32_e32 v14, v14, v14
	v_mul_f32_e32 v15, v15, v15
	v_mul_f32_e32 v8, v8, v8
	v_mul_f32_e32 v9, v9, v9
	v_mul_f32_e32 v10, v10, v10
	v_mul_f32_e32 v11, v11, v11
	v_mul_f32_e32 v4, v4, v4
	v_mul_f32_e32 v5, v5, v5
	v_mul_f32_e32 v6, v6, v6
	v_mul_f32_e32 v7, v7, v7
	v_mul_f32_e32 v0, v0, v0
	v_mul_f32_e32 v1, v1, v1
	v_mul_f32_e32 v2, v2, v2
	v_mul_f32_e32 v3, v3, v3
	v_cvt_pk_bf16_f32 v12, v12, v13
	v_cvt_pk_bf16_f32 v13, v14, v15
	v_cvt_pk_bf16_f32 v14, v8, v9
	v_cvt_pk_bf16_f32 v15, v10, v11
	v_cvt_pk_bf16_f32 v4, v4, v5
	v_cvt_pk_bf16_f32 v5, v6, v7
	v_cvt_pk_bf16_f32 v6, v0, v1
	v_cvt_pk_bf16_f32 v7, v2, v3
	v_mov_b32_dpp v246, v4 row_ror:8 row_mask:0xf bank_mask:0xf
	v_mov_b32_dpp v247, v5 row_ror:8 row_mask:0xf bank_mask:0xf
	v_mov_b32_dpp v248, v6 row_ror:8 row_mask:0xf bank_mask:0xf
	v_mov_b32_dpp v249, v7 row_ror:8 row_mask:0xf bank_mask:0xf
	v_mov_b32_dpp v250, v12 row_ror:8 row_mask:0xf bank_mask:0xf
	v_mov_b32_dpp v251, v13 row_ror:8 row_mask:0xf bank_mask:0xf
	v_mov_b32_dpp v252, v14 row_ror:8 row_mask:0xf bank_mask:0xf
	v_mov_b32_dpp v253, v15 row_ror:8 row_mask:0xf bank_mask:0xf
	v_cndmask_b32_e32 v246, v12, v246, vcc
	v_cndmask_b32_e32 v247, v13, v247, vcc
	v_cndmask_b32_e32 v248, v14, v248, vcc
	v_cndmask_b32_e32 v249, v15, v249, vcc
	v_cndmask_b32_e32 v250, v250, v4, vcc
	v_cndmask_b32_e32 v251, v251, v5, vcc
	v_cndmask_b32_e32 v252, v252, v6, vcc
	v_cndmask_b32_e32 v253, v253, v7, vcc
	ds_bpermute_b32 v246, v240, v246
	ds_bpermute_b32 v247, v240, v247
	ds_bpermute_b32 v248, v240, v248
	ds_bpermute_b32 v249, v240, v249
	ds_bpermute_b32 v250, v240, v250
	ds_bpermute_b32 v251, v240, v251
	ds_bpermute_b32 v252, v240, v252
	ds_bpermute_b32 v253, v240, v253
	v_mov_b32_e32 v12, 0
	v_mov_b32_e32 v13, 0
	v_mov_b32_e32 v14, 0
	v_mov_b32_e32 v15, 0
	v_mov_b32_e32 v8, 0
	v_mov_b32_e32 v9, 0
	v_mov_b32_e32 v10, 0
	v_mov_b32_e32 v11, 0
	v_mov_b32_e32 v4, 0
	v_mov_b32_e32 v5, 0
	v_mov_b32_e32 v6, 0
	v_mov_b32_e32 v7, 0
	v_mov_b32_e32 v0, 0
	v_mov_b32_e32 v1, 0
	v_mov_b32_e32 v2, 0
	v_mov_b32_e32 v3, 0
	v_lshl_add_u64 v[238:239], v[140:141], 0, v[242:243]
	s_waitcnt lgkmcnt(4)
	global_store_dwordx4 v[140:141], v[246:249], off
	s_waitcnt lgkmcnt(0)
	global_store_dwordx4 v[238:239], v[250:253], off
	s_andn2_b64 vcc, exec, s[40:41]
	s_mov_b64 s[34:35], -1
	s_cbranch_vccnz .LBB0_51
	s_andn2_b64 vcc, exec, s[30:31]
	s_cbranch_vccnz .LBB0_50
	s_barrier
	s_branch .LBB0_50

; #define PG8_STAGE(bufoff, gbase, voff) do { _Pragma("unroll") for (int _i = 0; _i < 2; ++_i) \
;         __builtin_amdgcn_global_load_lds((const unsigned*)((const char*)(gbase) + (voff)[_i]), (PG8_LAS unsigned*)(lds + (bufoff) + ldsw + _i * 8192), 16, 0, 0); } while (0)
; #define PG8_LDA(dst, b, h) do { _Pragma("unroll") for (int m = 0; m < 4; ++m) _Pragma("unroll") for (int k = 0; k < 2; ++k) dst[m][k] = *(const PG8_LAS bf16x8*)(lds + PG8_SA(b, h) + aoff + m * 2048 + k * 1024); } while (0)
; #define PG8_LDB(dst, b, h) do { _Pragma("unroll") for (int n = 0; n < 2; ++n) _Pragma("unroll") for (int k = 0; k < 2; ++k) dst[n][k] = *(const PG8_LAS bf16x8*)(lds + PG8_SB(b, h) + boff + n * 2048 + k * 1024); } while (0)
; #define PG8_SCHED __builtin_amdgcn_sched_barrier(0)
; template <class Epi, class Sched, bool ALIGN_EPI = false, bool SP2 = false>
; __device__ __forceinline__ void gemm_phase(PG8_LAS unsigned char* lds, const Gemm g, const Sched& S, const Epi& E) {
;     ...
;         const bool has_next = S.next(ui + 1, nxt);
;         const char* nA = has_next ? (const char*)g.A + (size_t)nxt.pm * tstep : cA; const char* nB = has_next ? (const char*)g.Bt + (size_t)nxt.pn * tstep : cB;
; #pragma nounroll
;         for (int t = 0; t < nt; t += 2) {
;             const bool last = (t == nt - 2);
;             const char* a1 = cA + (size_t)(t + 1) * kstep;
;             const char* a2 = last ? nA : cA + (size_t)(t + 2) * kstep; const char* b2 = last ? nB : cB + (size_t)(t + 2) * kstep;
;             const char* a3 = a2 + kstep; const char* b3 = b2 + kstep;
;             if (last && has_next) S.a_ready(nxt);
;             if constexpr (SP2) {
;             PG8_LDB(B0, 0, 0); PG8_LDB(B1, 0, 1); PG8_SCHED; PG8_LDA(At, 0, 0); PG8_STAGE(PG8_SA(1, 1), a1 + hstep, voffA);
;     ...
; #pragma unroll
;         for (int a = 0; a < 2; ++a)
; #pragma unroll
;             for (int b = 0; b < 2; ++b)
; #pragma unroll
;                 for (int m = 0; m < 4; ++m)
; #pragma unroll
;                     for (int n = 0; n < 2; ++n) acc[a][b][m][n] = (f32x4){0.f, 0.f, 0.f, 0.f};
.LBB0_95:
	s_ashr_i32 s43, s42, 31
	s_lshl_b64 s[34:35], s[42:43], 20
	s_add_u32 s50, s83, s34
	s_addc_u32 s51, s93, s35
	s_and_b64 s[34:35], s[40:41], exec
	s_cselect_b32 s34, s51, s55
	s_cselect_b32 s35, s50, s54
	s_ashr_i32 s45, s44, 31
	s_lshl_b64 s[52:53], s[44:45], 20
	s_add_u32 s52, s80, s52
	s_addc_u32 s53, s81, s53
	s_and_b64 s[58:59], s[40:41], exec
	s_cselect_b32 s37, s53, s57
	s_cselect_b32 s43, s52, s56
	s_add_u32 s54, s54, 0x80080
	s_addc_u32 s55, s55, 0
	s_add_u32 s45, s56, 0x100
	v_mov_b32_e32 v0, 0
	s_addc_u32 s47, s57, 0
	s_mov_b32 s49, -2
	s_cmp_lt_u32 s33, 2
	s_cbranch_scc0 .Lzs16
	v_mov_b32_e32 v1, v0
	v_mov_b32_e32 v2, v0
	v_mov_b32_e32 v3, v0
	v_mov_b32_e32 v4, v0
	v_mov_b32_e32 v5, v0
	v_mov_b32_e32 v6, v0
	v_mov_b32_e32 v7, v0
	v_mov_b32_e32 v8, v0
	v_mov_b32_e32 v9, v0
	v_mov_b32_e32 v10, v0
	v_mov_b32_e32 v11, v0
	v_mov_b32_e32 v16, v0
	v_mov_b32_e32 v17, v0
	v_mov_b32_e32 v18, v0
	v_mov_b32_e32 v19, v0
	v_mov_b32_e32 v24, v0
	v_mov_b32_e32 v25, v0
	v_mov_b32_e32 v26, v0
	v_mov_b32_e32 v27, v0
	v_mov_b32_e32 v32, v0
	v_mov_b32_e32 v33, v0
	v_mov_b32_e32 v34, v0
	v_mov_b32_e32 v35, v0
	v_mov_b32_e32 v40, v0
	v_mov_b32_e32 v41, v0
	v_mov_b32_e32 v42, v0
	v_mov_b32_e32 v43, v0
	v_mov_b32_e32 v48, v0
	v_mov_b32_e32 v49, v0
	v_mov_b32_e32 v50, v0
	v_mov_b32_e32 v51, v0
	v_mov_b32_e32 v12, v0
	v_mov_b32_e32 v13, v0
	v_mov_b32_e32 v14, v0
	v_mov_b32_e32 v15, v0
	v_mov_b32_e32 v20, v0
	v_mov_b32_e32 v21, v0
	v_mov_b32_e32 v22, v0
	v_mov_b32_e32 v23, v0
	v_mov_b32_e32 v28, v0
	v_mov_b32_e32 v29, v0
	v_mov_b32_e32 v30, v0
	v_mov_b32_e32 v31, v0
	v_mov_b32_e32 v36, v0
	v_mov_b32_e32 v37, v0
	v_mov_b32_e32 v38, v0
	v_mov_b32_e32 v39, v0
	v_mov_b32_e32 v44, v0
	v_mov_b32_e32 v45, v0
	v_mov_b32_e32 v46, v0
	v_mov_b32_e32 v47, v0
	v_mov_b32_e32 v52, v0
	v_mov_b32_e32 v53, v0
	v_mov_b32_e32 v54, v0
	v_mov_b32_e32 v55, v0
	v_mov_b32_e32 v56, v0
	v_mov_b32_e32 v57, v0
	v_mov_b32_e32 v58, v0
	v_mov_b32_e32 v59, v0
	v_mov_b32_e32 v60, v0
	v_mov_b32_e32 v61, v0
	v_mov_b32_e32 v62, v0
	v_mov_b32_e32 v63, v0
	v_mov_b32_e32 v64, v0
	v_mov_b32_e32 v65, v0
	v_mov_b32_e32 v66, v0
	v_mov_b32_e32 v67, v0
	v_mov_b32_e32 v68, v0
	v_mov_b32_e32 v69, v0
	v_mov_b32_e32 v70, v0
	v_mov_b32_e32 v71, v0
	v_mov_b32_e32 v72, v0
	v_mov_b32_e32 v73, v0
	v_mov_b32_e32 v74, v0
	v_mov_b32_e32 v75, v0
	v_mov_b32_e32 v80, v0
	v_mov_b32_e32 v81, v0
	v_mov_b32_e32 v82, v0
	v_mov_b32_e32 v83, v0
	v_mov_b32_e32 v88, v0
	v_mov_b32_e32 v89, v0
	v_mov_b32_e32 v90, v0
	v_mov_b32_e32 v91, v0
	v_mov_b32_e32 v96, v0
	v_mov_b32_e32 v97, v0
	v_mov_b32_e32 v98, v0
	v_mov_b32_e32 v99, v0
	v_mov_b32_e32 v104, v0
	v_mov_b32_e32 v105, v0
	v_mov_b32_e32 v106, v0
	v_mov_b32_e32 v107, v0
	v_mov_b32_e32 v112, v0
	v_mov_b32_e32 v113, v0
	v_mov_b32_e32 v114, v0
	v_mov_b32_e32 v115, v0
	v_mov_b32_e32 v76, v0
	v_mov_b32_e32 v77, v0
	v_mov_b32_e32 v78, v0
	v_mov_b32_e32 v79, v0
	v_mov_b32_e32 v84, v0
	v_mov_b32_e32 v85, v0
	v_mov_b32_e32 v86, v0
	v_mov_b32_e32 v87, v0
	v_mov_b32_e32 v92, v0
	v_mov_b32_e32 v93, v0
	v_mov_b32_e32 v94, v0
	v_mov_b32_e32 v95, v0
	v_mov_b32_e32 v100, v0
	v_mov_b32_e32 v101, v0
	v_mov_b32_e32 v102, v0
	v_mov_b32_e32 v103, v0
	v_mov_b32_e32 v108, v0
	v_mov_b32_e32 v109, v0
	v_mov_b32_e32 v110, v0
	v_mov_b32_e32 v111, v0
	v_mov_b32_e32 v116, v0
	v_mov_b32_e32 v117, v0
	v_mov_b32_e32 v118, v0
	v_mov_b32_e32 v119, v0
	v_mov_b32_e32 v120, v0
	v_mov_b32_e32 v121, v0
	v_mov_b32_e32 v122, v0
	v_mov_b32_e32 v123, v0
	v_mov_b32_e32 v124, v0
	v_mov_b32_e32 v125, v0
	v_mov_b32_e32 v126, v0
	v_mov_b32_e32 v127, v0
.Lzs16:
.LBB0_96:
	s_add_u32 s7, s54, 0xfff80080
	s_addc_u32 s56, s55, -1
	s_add_i32 s60, 0, 0x10000
	s_cmp_eq_u32 s49, 28
	s_cselect_b32 s59, s34, s56
	s_cselect_b32 s58, s35, s7
	v_add_u32_e32 v140, s60, v143
	s_cselect_b32 s57, s37, s47
	s_cselect_b32 s56, s43, s45
	s_add_i32 s7, 0, 0x14000
	ds_read_b128 v[146:149], v140
	ds_read_b128 v[150:153], v140 offset:1024
	ds_read_b128 v[154:157], v140 offset:2048
	ds_read_b128 v[158:161], v140 offset:3072
	v_add_u32_e32 v140, s7, v143
	ds_read_b128 v[162:165], v140
	ds_read_b128 v[166:169], v140 offset:1024
	ds_read_b128 v[170:173], v140 offset:2048
	ds_read_b128 v[174:177], v140 offset:3072
	v_lshl_add_u64 v[140:141], s[54:55], 0, v[136:137]
	s_add_i32 m0, s10, 0xc000
	ds_read_b128 v[178:181], v145
	ds_read_b128 v[182:185], v145 offset:1024
	ds_read_b128 v[186:189], v145 offset:2048
	ds_read_b128 v[190:193], v145 offset:3072
	ds_read_b128 v[214:217], v145 offset:4096
	ds_read_b128 v[220:223], v145 offset:5120
	ds_read_b128 v[224:227], v145 offset:6144
	ds_read_b128 v[228:231], v145 offset:7168
	global_load_lds_dwordx4 v[140:141], off
	v_lshl_add_u64 v[140:141], s[54:55], 0, v[138:139]
	s_add_i32 m0, s10, 0xe000
	s_nop 0
	global_load_lds_dwordx4 v[140:141], off
	s_cmp_lt_i32 s49, 0
	s_cbranch_scc0 .Lrx16_0_norm
	s_cmp_lt_u32 s33, 2
	s_cbranch_scc1 .Lrx16_0_norm
	s_waitcnt vmcnt(24)
	s_branch .Lrx16_0_join

; __device__ __forceinline__ u32x4 pack8_bf16(f32x4 a, f32x4 b) { u32x4 w; w.x = cvt_pk_bf16(a[0], a[1]); w.y = cvt_pk_bf16(a[2], a[3]); w.z = cvt_pk_bf16(b[0], b[1]); w.w = cvt_pk_bf16(b[2], b[3]); return w; }
; #define ACT(t) (KBASE(t) <= qlo + QBLK - 1 && KBASE(t) + KVBLK - 1 >= qlo - W + 1)
;     __device__ __forceinline__ void operator()(const f32x4 (&acc)[2][2][4][2], const Unit& u, int wr, int wc, int fr, int fq) const {
;         const int g = u.pn / nNper, pnl = u.pn - g * nNper, pml = u.pm & 63;
;         bf16_t* base = O + (size_t)g * gstride;
;         const int row0 = pml * BM + wr * 64 + fr, col0 = pnl * BM + wc * 32 + 8 * fq;
; #pragma unroll
;         for (int ai = 0; ai < 2; ++ai)
; #pragma unroll
;             for (int m = 0; m < 4; ++m) { bf16_t* rowp = base + (size_t)(row0 + ai * HALF + m * 16) * ldc + col0;
; #pragma unroll
;                 for (int bj = 0; bj < 2; ++bj) { f32x4 v0 = acc[ai][bj][m][0], v1 = acc[ai][bj][m][1];
;                     if (ACT == 1) {
; #pragma unroll
;                         for (int j = 0; j < 4; ++j) { float a = fmaxf(v0[j], 0.f), b = fmaxf(v1[j], 0.f); v0[j] = a * a; v1[j] = b * b; } }
;                     *(u32x4*)(rowp + bj * HALF) = pack8_bf16(v0, v1); } }
.LBB0_99:
	s_ashr_i32 s7, s48, 31
	s_lshr_b32 s7, s7, 29
	s_add_i32 s7, s48, s7
	s_and_b32 s7, s7, 0xfffff8
	s_lshl_b32 s34, s46, 8
	s_sub_i32 s7, s48, s7
	s_and_b32 s34, s34, 0x3f00
	v_add_u32_e32 v146, s34, v142
	v_lshl_or_b32 v140, s7, 8, v144
	v_ashrrev_i32_e32 v141, 31, v140
	v_ashrrev_i32_e32 v147, 31, v146
	v_lshl_add_u64 v[148:149], v[140:141], 1, s[12:13]
	v_lshlrev_b64 v[140:141], 12, v[146:147]
	v_lshl_add_u64 v[140:141], v[148:149], 0, v[140:141]
	s_mov_b64 s[34:35], 0x10000
	v_mov_b32_e32 v242, 0x8000
	v_mov_b32_e32 v243, 0
	v_and_b32_e32 v238, 8, v208
	v_cmp_ne_u32_e32 vcc, 0, v238
	v_and_b32_e32 v240, 63, v208
	v_lshrrev_b32_e32 v241, 3, v240
	v_and_b32_e32 v244, 3, v240
	v_lshl_add_u32 v241, v244, 4, v241
	v_and_b32_e32 v244, 4, v240
	v_lshl_add_u32 v241, v244, 1, v241
	v_lshlrev_b32_e32 v240, 2, v241
	v_cvt_pk_bf16_f32 v124, v124, v125
	v_cvt_pk_bf16_f32 v125, v126, v127
	v_cvt_pk_bf16_f32 v126, v120, v121
	v_cvt_pk_bf16_f32 v127, v122, v123
	v_cvt_pk_bf16_f32 v112, v112, v113
	v_cvt_pk_bf16_f32 v113, v114, v115
	v_cvt_pk_bf16_f32 v114, v104, v105
	v_cvt_pk_bf16_f32 v115, v106, v107
	v_mov_b32_dpp v246, v112 row_ror:8 row_mask:0xf bank_mask:0xf
	v_mov_b32_dpp v247, v113 row_ror:8 row_mask:0xf bank_mask:0xf
	v_mov_b32_dpp v248, v114 row_ror:8 row_mask:0xf bank_mask:0xf
	v_mov_b32_dpp v249, v115 row_ror:8 row_mask:0xf bank_mask:0xf
	v_mov_b32_dpp v250, v124 row_ror:8 row_mask:0xf bank_mask:0xf
	v_mov_b32_dpp v251, v125 row_ror:8 row_mask:0xf bank_mask:0xf
	v_mov_b32_dpp v252, v126 row_ror:8 row_mask:0xf bank_mask:0xf
	v_mov_b32_dpp v253, v127 row_ror:8 row_mask:0xf bank_mask:0xf
	v_cndmask_b32_e32 v246, v124, v246, vcc
	v_cndmask_b32_e32 v247, v125, v247, vcc
	v_cndmask_b32_e32 v248, v126, v248, vcc
	v_cndmask_b32_e32 v249, v127, v249, vcc
	v_cndmask_b32_e32 v250, v250, v112, vcc
	v_cndmask_b32_e32 v251, v251, v113, vcc
	v_cndmask_b32_e32 v252, v252, v114, vcc
	v_cndmask_b32_e32 v253, v253, v115, vcc
	ds_bpermute_b32 v246, v240, v246
	ds_bpermute_b32 v247, v240, v247
	ds_bpermute_b32 v248, v240, v248
	ds_bpermute_b32 v249, v240, v249
	ds_bpermute_b32 v250, v240, v250
	ds_bpermute_b32 v251, v240, v251
	ds_bpermute_b32 v252, v240, v252
	ds_bpermute_b32 v253, v240, v253
	v_mov_b32_e32 v124, 0
	v_mov_b32_e32 v125, 0
	v_mov_b32_e32 v126, 0
	v_mov_b32_e32 v127, 0
	v_mov_b32_e32 v120, 0
	v_mov_b32_e32 v121, 0
	v_mov_b32_e32 v122, 0
	v_mov_b32_e32 v123, 0
	v_mov_b32_e32 v112, 0
	v_mov_b32_e32 v113, 0
	v_mov_b32_e32 v114, 0
	v_mov_b32_e32 v115, 0
	v_mov_b32_e32 v104, 0
	v_mov_b32_e32 v105, 0
	v_mov_b32_e32 v106, 0
	v_mov_b32_e32 v107, 0
	v_lshl_add_u64 v[238:239], v[140:141], 0, v[242:243]
	s_waitcnt lgkmcnt(4)
	global_store_dwordx4 v[140:141], v[246:249], off
	s_waitcnt lgkmcnt(0)
	global_store_dwordx4 v[238:239], v[250:253], off
	v_lshl_add_u64 v[140:141], v[140:141], 0, s[34:35]
	v_cvt_pk_bf16_f32 v116, v116, v117
	v_cvt_pk_bf16_f32 v117, v118, v119
	v_cvt_pk_bf16_f32 v118, v108, v109
	v_cvt_pk_bf16_f32 v119, v110, v111
	v_cvt_pk_bf16_f32 v96, v96, v97
	v_cvt_pk_bf16_f32 v97, v98, v99
	v_cvt_pk_bf16_f32 v98, v88, v89
	v_cvt_pk_bf16_f32 v99, v90, v91
	v_mov_b32_dpp v246, v96 row_ror:8 row_mask:0xf bank_mask:0xf
	v_mov_b32_dpp v247, v97 row_ror:8 row_mask:0xf bank_mask:0xf
	v_mov_b32_dpp v248, v98 row_ror:8 row_mask:0xf bank_mask:0xf
	v_mov_b32_dpp v249, v99 row_ror:8 row_mask:0xf bank_mask:0xf
	v_mov_b32_dpp v250, v116 row_ror:8 row_mask:0xf bank_mask:0xf
	v_mov_b32_dpp v251, v117 row_ror:8 row_mask:0xf bank_mask:0xf
	v_mov_b32_dpp v252, v118 row_ror:8 row_mask:0xf bank_mask:0xf
	v_mov_b32_dpp v253, v119 row_ror:8 row_mask:0xf bank_mask:0xf
	v_cndmask_b32_e32 v246, v116, v246, vcc
	v_cndmask_b32_e32 v247, v117, v247, vcc
	v_cndmask_b32_e32 v248, v118, v248, vcc
	v_cndmask_b32_e32 v249, v119, v249, vcc
	v_cndmask_b32_e32 v250, v250, v96, vcc
	v_cndmask_b32_e32 v251, v251, v97, vcc
	v_cndmask_b32_e32 v252, v252, v98, vcc
	v_cndmask_b32_e32 v253, v253, v99, vcc
	ds_bpermute_b32 v246, v240, v246
	ds_bpermute_b32 v247, v240, v247
	ds_bpermute_b32 v248, v240, v248
	ds_bpermute_b32 v249, v240, v249
	ds_bpermute_b32 v250, v240, v250
	ds_bpermute_b32 v251, v240, v251
	ds_bpermute_b32 v252, v240, v252
	ds_bpermute_b32 v253, v240, v253
	v_mov_b32_e32 v116, 0
	v_mov_b32_e32 v117, 0
	v_mov_b32_e32 v118, 0
	v_mov_b32_e32 v119, 0
	v_mov_b32_e32 v108, 0
	v_mov_b32_e32 v109, 0
	v_mov_b32_e32 v110, 0
	v_mov_b32_e32 v111, 0
	v_mov_b32_e32 v96, 0
	v_mov_b32_e32 v97, 0
	v_mov_b32_e32 v98, 0
	v_mov_b32_e32 v99, 0
	v_mov_b32_e32 v88, 0
	v_mov_b32_e32 v89, 0
	v_mov_b32_e32 v90, 0
	v_mov_b32_e32 v91, 0
	v_lshl_add_u64 v[238:239], v[140:141], 0, v[242:243]
	s_waitcnt lgkmcnt(4)
	global_store_dwordx4 v[140:141], v[246:249], off
	s_waitcnt lgkmcnt(0)
; __device__ __forceinline__ u32x4 pack8_bf16(f32x4 a, f32x4 b) { u32x4 w; w.x = cvt_pk_bf16(a[0], a[1]); w.y = cvt_pk_bf16(a[2], a[3]); w.z = cvt_pk_bf16(b[0], b[1]); w.w = cvt_pk_bf16(b[2], b[3]); return w; }
; #define ACT(t) (KBASE(t) <= qlo + QBLK - 1 && KBASE(t) + KVBLK - 1 >= qlo - W + 1)
;     __device__ __forceinline__ void operator()(const f32x4 (&acc)[2][2][4][2], const Unit& u, int wr, int wc, int fr, int fq) const {
;     ...
;             for (int m = 0; m < 4; ++m) { bf16_t* rowp = base + (size_t)(row0 + ai * HALF + m * 16) * ldc + col0;
; #pragma unroll
;                 for (int bj = 0; bj < 2; ++bj) { f32x4 v0 = acc[ai][bj][m][0], v1 = acc[ai][bj][m][1];
;                     if (ACT == 1) {
; #pragma unroll
;                         for (int j = 0; j < 4; ++j) { float a = fmaxf(v0[j], 0.f), b = fmaxf(v1[j], 0.f); v0[j] = a * a; v1[j] = b * b; } }
;                     *(u32x4*)(rowp + bj * HALF) = pack8_bf16(v0, v1); } }
	global_store_dwordx4 v[238:239], v[250:253], off
	v_lshl_add_u64 v[140:141], v[140:141], 0, s[34:35]
	v_cvt_pk_bf16_f32 v100, v100, v101
	v_cvt_pk_bf16_f32 v101, v102, v103
	v_cvt_pk_bf16_f32 v102, v92, v93
	v_cvt_pk_bf16_f32 v103, v94, v95
	v_cvt_pk_bf16_f32 v80, v80, v81
	v_cvt_pk_bf16_f32 v81, v82, v83
	v_cvt_pk_bf16_f32 v82, v72, v73
	v_cvt_pk_bf16_f32 v83, v74, v75
	v_mov_b32_dpp v246, v80 row_ror:8 row_mask:0xf bank_mask:0xf
	v_mov_b32_dpp v247, v81 row_ror:8 row_mask:0xf bank_mask:0xf
	v_mov_b32_dpp v248, v82 row_ror:8 row_mask:0xf bank_mask:0xf
	v_mov_b32_dpp v249, v83 row_ror:8 row_mask:0xf bank_mask:0xf
	v_mov_b32_dpp v250, v100 row_ror:8 row_mask:0xf bank_mask:0xf
	v_mov_b32_dpp v251, v101 row_ror:8 row_mask:0xf bank_mask:0xf
	v_mov_b32_dpp v252, v102 row_ror:8 row_mask:0xf bank_mask:0xf
	v_mov_b32_dpp v253, v103 row_ror:8 row_mask:0xf bank_mask:0xf
	v_cndmask_b32_e32 v246, v100, v246, vcc
	v_cndmask_b32_e32 v247, v101, v247, vcc
	v_cndmask_b32_e32 v248, v102, v248, vcc
	v_cndmask_b32_e32 v249, v103, v249, vcc
	v_cndmask_b32_e32 v250, v250, v80, vcc
	v_cndmask_b32_e32 v251, v251, v81, vcc
	v_cndmask_b32_e32 v252, v252, v82, vcc
	v_cndmask_b32_e32 v253, v253, v83, vcc
	ds_bpermute_b32 v246, v240, v246
	ds_bpermute_b32 v247, v240, v247
	ds_bpermute_b32 v248, v240, v248
	ds_bpermute_b32 v249, v240, v249
	ds_bpermute_b32 v250, v240, v250
	ds_bpermute_b32 v251, v240, v251
	ds_bpermute_b32 v252, v240, v252
	ds_bpermute_b32 v253, v240, v253
	v_mov_b32_e32 v100, 0
	v_mov_b32_e32 v101, 0
	v_mov_b32_e32 v102, 0
	v_mov_b32_e32 v103, 0
	v_mov_b32_e32 v92, 0
	v_mov_b32_e32 v93, 0
	v_mov_b32_e32 v94, 0
	v_mov_b32_e32 v95, 0
	v_mov_b32_e32 v80, 0
	v_mov_b32_e32 v81, 0
	v_mov_b32_e32 v82, 0
	v_mov_b32_e32 v83, 0
	v_mov_b32_e32 v72, 0
	v_mov_b32_e32 v73, 0
	v_mov_b32_e32 v74, 0
	v_mov_b32_e32 v75, 0
	v_lshl_add_u64 v[238:239], v[140:141], 0, v[242:243]
	s_waitcnt lgkmcnt(4)
	global_store_dwordx4 v[140:141], v[246:249], off
	s_waitcnt lgkmcnt(0)
	global_store_dwordx4 v[238:239], v[250:253], off
	v_lshl_add_u64 v[140:141], v[140:141], 0, s[34:35]
	v_cvt_pk_bf16_f32 v84, v84, v85
	v_cvt_pk_bf16_f32 v85, v86, v87
	v_cvt_pk_bf16_f32 v86, v76, v77
	v_cvt_pk_bf16_f32 v87, v78, v79
	v_cvt_pk_bf16_f32 v68, v68, v69
	v_cvt_pk_bf16_f32 v69, v70, v71
	v_cvt_pk_bf16_f32 v70, v64, v65
	v_cvt_pk_bf16_f32 v71, v66, v67
	v_mov_b32_dpp v246, v68 row_ror:8 row_mask:0xf bank_mask:0xf
	v_mov_b32_dpp v247, v69 row_ror:8 row_mask:0xf bank_mask:0xf
	v_mov_b32_dpp v248, v70 row_ror:8 row_mask:0xf bank_mask:0xf
	v_mov_b32_dpp v249, v71 row_ror:8 row_mask:0xf bank_mask:0xf
	v_mov_b32_dpp v250, v84 row_ror:8 row_mask:0xf bank_mask:0xf
	v_mov_b32_dpp v251, v85 row_ror:8 row_mask:0xf bank_mask:0xf
	v_mov_b32_dpp v252, v86 row_ror:8 row_mask:0xf bank_mask:0xf
	v_mov_b32_dpp v253, v87 row_ror:8 row_mask:0xf bank_mask:0xf
	v_cndmask_b32_e32 v246, v84, v246, vcc
	v_cndmask_b32_e32 v247, v85, v247, vcc
	v_cndmask_b32_e32 v248, v86, v248, vcc
	v_cndmask_b32_e32 v249, v87, v249, vcc
	v_cndmask_b32_e32 v250, v250, v68, vcc
	v_cndmask_b32_e32 v251, v251, v69, vcc
	v_cndmask_b32_e32 v252, v252, v70, vcc
	v_cndmask_b32_e32 v253, v253, v71, vcc
	ds_bpermute_b32 v246, v240, v246
	ds_bpermute_b32 v247, v240, v247
	ds_bpermute_b32 v248, v240, v248
	ds_bpermute_b32 v249, v240, v249
	ds_bpermute_b32 v250, v240, v250
	ds_bpermute_b32 v251, v240, v251
	ds_bpermute_b32 v252, v240, v252
	ds_bpermute_b32 v253, v240, v253
	v_mov_b32_e32 v84, 0
	v_mov_b32_e32 v85, 0
	v_mov_b32_e32 v86, 0
	v_mov_b32_e32 v87, 0
	v_mov_b32_e32 v76, 0
	v_mov_b32_e32 v77, 0
	v_mov_b32_e32 v78, 0
	v_mov_b32_e32 v79, 0
	v_mov_b32_e32 v68, 0
	v_mov_b32_e32 v69, 0
	v_mov_b32_e32 v70, 0
	v_mov_b32_e32 v71, 0
	v_mov_b32_e32 v64, 0
	v_mov_b32_e32 v65, 0
	v_mov_b32_e32 v66, 0
	v_mov_b32_e32 v67, 0
	v_lshl_add_u64 v[238:239], v[140:141], 0, v[242:243]
	s_waitcnt lgkmcnt(4)
	global_store_dwordx4 v[140:141], v[246:249], off
	s_waitcnt lgkmcnt(0)
	global_store_dwordx4 v[238:239], v[250:253], off
	s_mov_b64 s[34:35], 0x50000
	v_lshl_add_u64 v[140:141], v[140:141], 0, s[34:35]
	s_mov_b64 s[34:35], 0x10000
	v_cvt_pk_bf16_f32 v60, v60, v61
	v_cvt_pk_bf16_f32 v61, v62, v63
	v_cvt_pk_bf16_f32 v62, v56, v57
	v_cvt_pk_bf16_f32 v63, v58, v59
	v_cvt_pk_bf16_f32 v48, v48, v49
	v_cvt_pk_bf16_f32 v49, v50, v51
	v_cvt_pk_bf16_f32 v50, v40, v41
	v_cvt_pk_bf16_f32 v51, v42, v43
	v_mov_b32_dpp v246, v48 row_ror:8 row_mask:0xf bank_mask:0xf
	v_mov_b32_dpp v247, v49 row_ror:8 row_mask:0xf bank_mask:0xf
	v_mov_b32_dpp v248, v50 row_ror:8 row_mask:0xf bank_mask:0xf
	v_mov_b32_dpp v249, v51 row_ror:8 row_mask:0xf bank_mask:0xf
	v_mov_b32_dpp v250, v60 row_ror:8 row_mask:0xf bank_mask:0xf
	v_mov_b32_dpp v251, v61 row_ror:8 row_mask:0xf bank_mask:0xf
	v_mov_b32_dpp v252, v62 row_ror:8 row_mask:0xf bank_mask:0xf
	v_mov_b32_dpp v253, v63 row_ror:8 row_mask:0xf bank_mask:0xf
	v_cndmask_b32_e32 v246, v60, v246, vcc
	v_cndmask_b32_e32 v247, v61, v247, vcc
	v_cndmask_b32_e32 v248, v62, v248, vcc
	v_cndmask_b32_e32 v249, v63, v249, vcc
	v_cndmask_b32_e32 v250, v250, v48, vcc
	v_cndmask_b32_e32 v251, v251, v49, vcc
	v_cndmask_b32_e32 v252, v252, v50, vcc
	v_cndmask_b32_e32 v253, v253, v51, vcc
	ds_bpermute_b32 v246, v240, v246
	ds_bpermute_b32 v247, v240, v247
	ds_bpermute_b32 v248, v240, v248
	ds_bpermute_b32 v249, v240, v249
	ds_bpermute_b32 v250, v240, v250
	ds_bpermute_b32 v251, v240, v251
	ds_bpermute_b32 v252, v240, v252
	ds_bpermute_b32 v253, v240, v253
	v_mov_b32_e32 v60, 0
	v_mov_b32_e32 v61, 0
	v_mov_b32_e32 v62, 0
	v_mov_b32_e32 v63, 0
	v_mov_b32_e32 v56, 0
	v_mov_b32_e32 v57, 0
	v_mov_b32_e32 v58, 0
	v_mov_b32_e32 v59, 0
	v_mov_b32_e32 v48, 0
	v_mov_b32_e32 v49, 0
	v_mov_b32_e32 v50, 0
	v_mov_b32_e32 v51, 0
	v_mov_b32_e32 v40, 0
	v_mov_b32_e32 v41, 0
	v_mov_b32_e32 v42, 0
	v_mov_b32_e32 v43, 0
	v_lshl_add_u64 v[238:239], v[140:141], 0, v[242:243]
	s_waitcnt lgkmcnt(4)
; __device__ __forceinline__ u32x4 pack8_bf16(f32x4 a, f32x4 b) { u32x4 w; w.x = cvt_pk_bf16(a[0], a[1]); w.y = cvt_pk_bf16(a[2], a[3]); w.z = cvt_pk_bf16(b[0], b[1]); w.w = cvt_pk_bf16(b[2], b[3]); return w; }
; #define PG8_BAR __builtin_amdgcn_s_barrier()
; #define ACT(t) (KBASE(t) <= qlo + QBLK - 1 && KBASE(t) + KVBLK - 1 >= qlo - W + 1)
;     __device__ __forceinline__ void operator()(const f32x4 (&acc)[2][2][4][2], const Unit& u, int wr, int wc, int fr, int fq) const {
;     ...
;             for (int m = 0; m < 4; ++m) { bf16_t* rowp = base + (size_t)(row0 + ai * HALF + m * 16) * ldc + col0;
; #pragma unroll
;                 for (int bj = 0; bj < 2; ++bj) { f32x4 v0 = acc[ai][bj][m][0], v1 = acc[ai][bj][m][1];
;                     if (ACT == 1) {
; #pragma unroll
;                         for (int j = 0; j < 4; ++j) { float a = fmaxf(v0[j], 0.f), b = fmaxf(v1[j], 0.f); v0[j] = a * a; v1[j] = b * b; } }
;                     *(u32x4*)(rowp + bj * HALF) = pack8_bf16(v0, v1); } }
; template <class Epi, class Sched, bool ALIGN_EPI = false, bool SP2 = false>
; __device__ __forceinline__ void gemm_phase(PG8_LAS unsigned char* lds, const Gemm g, const Sched& S, const Epi& E) {
;     ...
;         if (!has_next) break;
; #pragma unroll
;         for (int a = 0; a < 2; ++a)
; #pragma unroll
;             for (int b = 0; b < 2; ++b)
; #pragma unroll
;                 for (int m = 0; m < 4; ++m)
; #pragma unroll
;                     for (int n = 0; n < 2; ++n) acc[a][b][m][n] = (f32x4){0.f, 0.f, 0.f, 0.f};
;         cur = nxt; cA = nA; cB = nB; ++ui;
;         if constexpr (ALIGN_EPI) { if (wr == 1) PG8_BAR; }
	global_store_dwordx4 v[140:141], v[246:249], off
	s_waitcnt lgkmcnt(0)
	global_store_dwordx4 v[238:239], v[250:253], off
	v_lshl_add_u64 v[140:141], v[140:141], 0, s[34:35]
	v_cvt_pk_bf16_f32 v52, v52, v53
	v_cvt_pk_bf16_f32 v53, v54, v55
	v_cvt_pk_bf16_f32 v54, v44, v45
	v_cvt_pk_bf16_f32 v55, v46, v47
	v_cvt_pk_bf16_f32 v32, v32, v33
	v_cvt_pk_bf16_f32 v33, v34, v35
	v_cvt_pk_bf16_f32 v34, v24, v25
	v_cvt_pk_bf16_f32 v35, v26, v27
	v_mov_b32_dpp v246, v32 row_ror:8 row_mask:0xf bank_mask:0xf
	v_mov_b32_dpp v247, v33 row_ror:8 row_mask:0xf bank_mask:0xf
	v_mov_b32_dpp v248, v34 row_ror:8 row_mask:0xf bank_mask:0xf
	v_mov_b32_dpp v249, v35 row_ror:8 row_mask:0xf bank_mask:0xf
	v_mov_b32_dpp v250, v52 row_ror:8 row_mask:0xf bank_mask:0xf
	v_mov_b32_dpp v251, v53 row_ror:8 row_mask:0xf bank_mask:0xf
	v_mov_b32_dpp v252, v54 row_ror:8 row_mask:0xf bank_mask:0xf
	v_mov_b32_dpp v253, v55 row_ror:8 row_mask:0xf bank_mask:0xf
	v_cndmask_b32_e32 v246, v52, v246, vcc
	v_cndmask_b32_e32 v247, v53, v247, vcc
	v_cndmask_b32_e32 v248, v54, v248, vcc
	v_cndmask_b32_e32 v249, v55, v249, vcc
	v_cndmask_b32_e32 v250, v250, v32, vcc
	v_cndmask_b32_e32 v251, v251, v33, vcc
	v_cndmask_b32_e32 v252, v252, v34, vcc
	v_cndmask_b32_e32 v253, v253, v35, vcc
	ds_bpermute_b32 v246, v240, v246
	ds_bpermute_b32 v247, v240, v247
	ds_bpermute_b32 v248, v240, v248
	ds_bpermute_b32 v249, v240, v249
	ds_bpermute_b32 v250, v240, v250
	ds_bpermute_b32 v251, v240, v251
	ds_bpermute_b32 v252, v240, v252
	ds_bpermute_b32 v253, v240, v253
	v_mov_b32_e32 v52, 0
	v_mov_b32_e32 v53, 0
	v_mov_b32_e32 v54, 0
	v_mov_b32_e32 v55, 0
	v_mov_b32_e32 v44, 0
	v_mov_b32_e32 v45, 0
	v_mov_b32_e32 v46, 0
	v_mov_b32_e32 v47, 0
	v_mov_b32_e32 v32, 0
	v_mov_b32_e32 v33, 0
	v_mov_b32_e32 v34, 0
	v_mov_b32_e32 v35, 0
	v_mov_b32_e32 v24, 0
	v_mov_b32_e32 v25, 0
	v_mov_b32_e32 v26, 0
	v_mov_b32_e32 v27, 0
	v_lshl_add_u64 v[238:239], v[140:141], 0, v[242:243]
	s_waitcnt lgkmcnt(4)
	global_store_dwordx4 v[140:141], v[246:249], off
	s_waitcnt lgkmcnt(0)
	global_store_dwordx4 v[238:239], v[250:253], off
	v_lshl_add_u64 v[140:141], v[140:141], 0, s[34:35]
	v_cvt_pk_bf16_f32 v36, v36, v37
	v_cvt_pk_bf16_f32 v37, v38, v39
	v_cvt_pk_bf16_f32 v38, v28, v29
	v_cvt_pk_bf16_f32 v39, v30, v31
	v_cvt_pk_bf16_f32 v16, v16, v17
	v_cvt_pk_bf16_f32 v17, v18, v19
	v_cvt_pk_bf16_f32 v18, v8, v9
	v_cvt_pk_bf16_f32 v19, v10, v11
	v_mov_b32_dpp v246, v16 row_ror:8 row_mask:0xf bank_mask:0xf
	v_mov_b32_dpp v247, v17 row_ror:8 row_mask:0xf bank_mask:0xf
	v_mov_b32_dpp v248, v18 row_ror:8 row_mask:0xf bank_mask:0xf
	v_mov_b32_dpp v249, v19 row_ror:8 row_mask:0xf bank_mask:0xf
	v_mov_b32_dpp v250, v36 row_ror:8 row_mask:0xf bank_mask:0xf
	v_mov_b32_dpp v251, v37 row_ror:8 row_mask:0xf bank_mask:0xf
	v_mov_b32_dpp v252, v38 row_ror:8 row_mask:0xf bank_mask:0xf
	v_mov_b32_dpp v253, v39 row_ror:8 row_mask:0xf bank_mask:0xf
	v_cndmask_b32_e32 v246, v36, v246, vcc
	v_cndmask_b32_e32 v247, v37, v247, vcc
	v_cndmask_b32_e32 v248, v38, v248, vcc
	v_cndmask_b32_e32 v249, v39, v249, vcc
	v_cndmask_b32_e32 v250, v250, v16, vcc
	v_cndmask_b32_e32 v251, v251, v17, vcc
	v_cndmask_b32_e32 v252, v252, v18, vcc
	v_cndmask_b32_e32 v253, v253, v19, vcc
	ds_bpermute_b32 v246, v240, v246
	ds_bpermute_b32 v247, v240, v247
	ds_bpermute_b32 v248, v240, v248
	ds_bpermute_b32 v249, v240, v249
	ds_bpermute_b32 v250, v240, v250
	ds_bpermute_b32 v251, v240, v251
	ds_bpermute_b32 v252, v240, v252
	ds_bpermute_b32 v253, v240, v253
	v_mov_b32_e32 v36, 0
	v_mov_b32_e32 v37, 0
	v_mov_b32_e32 v38, 0
	v_mov_b32_e32 v39, 0
	v_mov_b32_e32 v28, 0
	v_mov_b32_e32 v29, 0
	v_mov_b32_e32 v30, 0
	v_mov_b32_e32 v31, 0
	v_mov_b32_e32 v16, 0
	v_mov_b32_e32 v17, 0
	v_mov_b32_e32 v18, 0
	v_mov_b32_e32 v19, 0
	v_mov_b32_e32 v8, 0
	v_mov_b32_e32 v9, 0
	v_mov_b32_e32 v10, 0
	v_mov_b32_e32 v11, 0
	v_lshl_add_u64 v[238:239], v[140:141], 0, v[242:243]
	s_waitcnt lgkmcnt(4)
	global_store_dwordx4 v[140:141], v[246:249], off
	s_waitcnt lgkmcnt(0)
	global_store_dwordx4 v[238:239], v[250:253], off
	v_lshl_add_u64 v[140:141], v[140:141], 0, s[34:35]
	v_cvt_pk_bf16_f32 v20, v20, v21
	v_cvt_pk_bf16_f32 v21, v22, v23
	v_cvt_pk_bf16_f32 v22, v12, v13
	v_cvt_pk_bf16_f32 v23, v14, v15
	v_cvt_pk_bf16_f32 v4, v4, v5
	v_cvt_pk_bf16_f32 v5, v6, v7
	v_cvt_pk_bf16_f32 v6, v0, v1
	v_cvt_pk_bf16_f32 v7, v2, v3
	v_mov_b32_dpp v246, v4 row_ror:8 row_mask:0xf bank_mask:0xf
	v_mov_b32_dpp v247, v5 row_ror:8 row_mask:0xf bank_mask:0xf
	v_mov_b32_dpp v248, v6 row_ror:8 row_mask:0xf bank_mask:0xf
	v_mov_b32_dpp v249, v7 row_ror:8 row_mask:0xf bank_mask:0xf
	v_mov_b32_dpp v250, v20 row_ror:8 row_mask:0xf bank_mask:0xf
	v_mov_b32_dpp v251, v21 row_ror:8 row_mask:0xf bank_mask:0xf
	v_mov_b32_dpp v252, v22 row_ror:8 row_mask:0xf bank_mask:0xf
	v_mov_b32_dpp v253, v23 row_ror:8 row_mask:0xf bank_mask:0xf
	v_cndmask_b32_e32 v246, v20, v246, vcc
	v_cndmask_b32_e32 v247, v21, v247, vcc
	v_cndmask_b32_e32 v248, v22, v248, vcc
	v_cndmask_b32_e32 v249, v23, v249, vcc
	v_cndmask_b32_e32 v250, v250, v4, vcc
	v_cndmask_b32_e32 v251, v251, v5, vcc
	v_cndmask_b32_e32 v252, v252, v6, vcc
	v_cndmask_b32_e32 v253, v253, v7, vcc
	ds_bpermute_b32 v246, v240, v246
	ds_bpermute_b32 v247, v240, v247
	ds_bpermute_b32 v248, v240, v248
	ds_bpermute_b32 v249, v240, v249
	ds_bpermute_b32 v250, v240, v250
	ds_bpermute_b32 v251, v240, v251
	ds_bpermute_b32 v252, v240, v252
	ds_bpermute_b32 v253, v240, v253
	v_mov_b32_e32 v20, 0
	v_mov_b32_e32 v21, 0
	v_mov_b32_e32 v22, 0
	v_mov_b32_e32 v23, 0
	v_mov_b32_e32 v12, 0
	v_mov_b32_e32 v13, 0
	v_mov_b32_e32 v14, 0
	v_mov_b32_e32 v15, 0
	v_mov_b32_e32 v4, 0
	v_mov_b32_e32 v5, 0
	v_mov_b32_e32 v6, 0
	v_mov_b32_e32 v7, 0
	v_mov_b32_e32 v0, 0
	v_mov_b32_e32 v1, 0
	v_mov_b32_e32 v2, 0
	v_mov_b32_e32 v3, 0
	v_lshl_add_u64 v[238:239], v[140:141], 0, v[242:243]
	s_waitcnt lgkmcnt(4)
	global_store_dwordx4 v[140:141], v[246:249], off
	s_waitcnt lgkmcnt(0)
	global_store_dwordx4 v[238:239], v[250:253], off
	s_andn2_b64 vcc, exec, s[40:41]
	s_mov_b64 s[34:35], -1
	s_cbranch_vccnz .LBB0_88
	s_andn2_b64 vcc, exec, s[18:19]
	s_cbranch_vccnz .LBB0_87
	s_barrier
	s_branch .LBB0_87

; #define PG8_STAGE(bufoff, gbase, voff) do { _Pragma("unroll") for (int _i = 0; _i < 2; ++_i) \
;         __builtin_amdgcn_global_load_lds((const unsigned*)((const char*)(gbase) + (voff)[_i]), (PG8_LAS unsigned*)(lds + (bufoff) + ldsw + _i * 8192), 16, 0, 0); } while (0)
; #define PG8_LDA(dst, b, h) do { _Pragma("unroll") for (int m = 0; m < 4; ++m) _Pragma("unroll") for (int k = 0; k < 2; ++k) dst[m][k] = *(const PG8_LAS bf16x8*)(lds + PG8_SA(b, h) + aoff + m * 2048 + k * 1024); } while (0)
; #define PG8_LDB(dst, b, h) do { _Pragma("unroll") for (int n = 0; n < 2; ++n) _Pragma("unroll") for (int k = 0; k < 2; ++k) dst[n][k] = *(const PG8_LAS bf16x8*)(lds + PG8_SB(b, h) + boff + n * 2048 + k * 1024); } while (0)
; #define PG8_SCHED __builtin_amdgcn_sched_barrier(0)
; template <class Epi, class Sched, bool ALIGN_EPI = false, bool SP2 = false>
; __device__ __forceinline__ void gemm_phase(PG8_LAS unsigned char* lds, const Gemm g, const Sched& S, const Epi& E) {
;     ...
;         const bool has_next = S.next(ui + 1, nxt);
;         const char* nA = has_next ? (const char*)g.A + (size_t)nxt.pm * tstep : cA; const char* nB = has_next ? (const char*)g.Bt + (size_t)nxt.pn * tstep : cB;
; #pragma nounroll
;         for (int t = 0; t < nt; t += 2) {
;             const bool last = (t == nt - 2);
;             const char* a1 = cA + (size_t)(t + 1) * kstep;
;             const char* a2 = last ? nA : cA + (size_t)(t + 2) * kstep; const char* b2 = last ? nB : cB + (size_t)(t + 2) * kstep;
;             const char* a3 = a2 + kstep; const char* b3 = b2 + kstep;
;             if (last && has_next) S.a_ready(nxt);
;             if constexpr (SP2) {
;             PG8_LDB(B0, 0, 0); PG8_LDB(B1, 0, 1); PG8_SCHED; PG8_LDA(At, 0, 0); PG8_STAGE(PG8_SA(1, 1), a1 + hstep, voffA);
;     ...
; #pragma unroll
;         for (int a = 0; a < 2; ++a)
; #pragma unroll
;             for (int b = 0; b < 2; ++b)
; #pragma unroll
;                 for (int m = 0; m < 4; ++m)
; #pragma unroll
;                     for (int n = 0; n < 2; ++n) acc[a][b][m][n] = (f32x4){0.f, 0.f, 0.f, 0.f};
.LBB0_326:
	s_ashr_i32 s19, s18, 31
	s_lshl_b64 s[34:35], s[18:19], 20
	s_add_u32 s46, s84, s34
	s_addc_u32 s47, s85, s35
	s_and_b64 s[34:35], s[40:41], exec
	s_cselect_b32 s19, s47, s51
	s_cselect_b32 s34, s46, s50
	s_ashr_i32 s31, s30, 31
	s_lshl_b64 s[48:49], s[30:31], 20
	s_add_u32 s48, s0, s48
	s_addc_u32 s49, s1, s49
	s_and_b64 s[54:55], s[40:41], exec
	s_cselect_b32 s31, s49, s53
	s_cselect_b32 s35, s48, s52
	s_add_u32 s50, s50, 0x80080
	s_addc_u32 s51, s51, 0
	s_add_u32 s37, s52, 0x100
	v_mov_b32_e32 v0, 0
	s_addc_u32 s43, s53, 0
	s_mov_b32 s45, -2
	s_cmp_lt_u32 s33, 2
	s_cbranch_scc0 .Lzs10
	v_mov_b32_e32 v1, v0
	v_mov_b32_e32 v2, v0
	v_mov_b32_e32 v3, v0
	v_mov_b32_e32 v4, v0
	v_mov_b32_e32 v5, v0
	v_mov_b32_e32 v6, v0
	v_mov_b32_e32 v7, v0
	v_mov_b32_e32 v8, v0
	v_mov_b32_e32 v9, v0
	v_mov_b32_e32 v10, v0
	v_mov_b32_e32 v11, v0
	v_mov_b32_e32 v16, v0
	v_mov_b32_e32 v17, v0
	v_mov_b32_e32 v18, v0
	v_mov_b32_e32 v19, v0
	v_mov_b32_e32 v24, v0
	v_mov_b32_e32 v25, v0
	v_mov_b32_e32 v26, v0
	v_mov_b32_e32 v27, v0
	v_mov_b32_e32 v32, v0
	v_mov_b32_e32 v33, v0
	v_mov_b32_e32 v34, v0
	v_mov_b32_e32 v35, v0
	v_mov_b32_e32 v40, v0
	v_mov_b32_e32 v41, v0
	v_mov_b32_e32 v42, v0
	v_mov_b32_e32 v43, v0
	v_mov_b32_e32 v48, v0
	v_mov_b32_e32 v49, v0
	v_mov_b32_e32 v50, v0
	v_mov_b32_e32 v51, v0
	v_mov_b32_e32 v12, v0
	v_mov_b32_e32 v13, v0
	v_mov_b32_e32 v14, v0
	v_mov_b32_e32 v15, v0
	v_mov_b32_e32 v20, v0
	v_mov_b32_e32 v21, v0
	v_mov_b32_e32 v22, v0
	v_mov_b32_e32 v23, v0
	v_mov_b32_e32 v28, v0
	v_mov_b32_e32 v29, v0
	v_mov_b32_e32 v30, v0
	v_mov_b32_e32 v31, v0
	v_mov_b32_e32 v36, v0
	v_mov_b32_e32 v37, v0
	v_mov_b32_e32 v38, v0
	v_mov_b32_e32 v39, v0
	v_mov_b32_e32 v44, v0
	v_mov_b32_e32 v45, v0
	v_mov_b32_e32 v46, v0
	v_mov_b32_e32 v47, v0
	v_mov_b32_e32 v52, v0
	v_mov_b32_e32 v53, v0
	v_mov_b32_e32 v54, v0
	v_mov_b32_e32 v55, v0
	v_mov_b32_e32 v56, v0
	v_mov_b32_e32 v57, v0
	v_mov_b32_e32 v58, v0
	v_mov_b32_e32 v59, v0
	v_mov_b32_e32 v60, v0
	v_mov_b32_e32 v61, v0
	v_mov_b32_e32 v62, v0
	v_mov_b32_e32 v63, v0
	v_mov_b32_e32 v64, v0
	v_mov_b32_e32 v65, v0
	v_mov_b32_e32 v66, v0
	v_mov_b32_e32 v67, v0
	v_mov_b32_e32 v68, v0
	v_mov_b32_e32 v69, v0
	v_mov_b32_e32 v70, v0
	v_mov_b32_e32 v71, v0
	v_mov_b32_e32 v72, v0
	v_mov_b32_e32 v73, v0
	v_mov_b32_e32 v74, v0
	v_mov_b32_e32 v75, v0
	v_mov_b32_e32 v80, v0
	v_mov_b32_e32 v81, v0
	v_mov_b32_e32 v82, v0
	v_mov_b32_e32 v83, v0
	v_mov_b32_e32 v88, v0
	v_mov_b32_e32 v89, v0
	v_mov_b32_e32 v90, v0
	v_mov_b32_e32 v91, v0
	v_mov_b32_e32 v96, v0
	v_mov_b32_e32 v97, v0
	v_mov_b32_e32 v98, v0
	v_mov_b32_e32 v99, v0
	v_mov_b32_e32 v104, v0
	v_mov_b32_e32 v105, v0
	v_mov_b32_e32 v106, v0
	v_mov_b32_e32 v107, v0
	v_mov_b32_e32 v112, v0
	v_mov_b32_e32 v113, v0
	v_mov_b32_e32 v114, v0
	v_mov_b32_e32 v115, v0
	v_mov_b32_e32 v76, v0
	v_mov_b32_e32 v77, v0
	v_mov_b32_e32 v78, v0
	v_mov_b32_e32 v79, v0
	v_mov_b32_e32 v84, v0
	v_mov_b32_e32 v85, v0
	v_mov_b32_e32 v86, v0
	v_mov_b32_e32 v87, v0
	v_mov_b32_e32 v92, v0
	v_mov_b32_e32 v93, v0
	v_mov_b32_e32 v94, v0
	v_mov_b32_e32 v95, v0
	v_mov_b32_e32 v100, v0
	v_mov_b32_e32 v101, v0
	v_mov_b32_e32 v102, v0
	v_mov_b32_e32 v103, v0
	v_mov_b32_e32 v108, v0
	v_mov_b32_e32 v109, v0
	v_mov_b32_e32 v110, v0
	v_mov_b32_e32 v111, v0
	v_mov_b32_e32 v116, v0
	v_mov_b32_e32 v117, v0
	v_mov_b32_e32 v118, v0
	v_mov_b32_e32 v119, v0
	v_mov_b32_e32 v120, v0
	v_mov_b32_e32 v121, v0
	v_mov_b32_e32 v122, v0
	v_mov_b32_e32 v123, v0
	v_mov_b32_e32 v124, v0
	v_mov_b32_e32 v125, v0
	v_mov_b32_e32 v126, v0
	v_mov_b32_e32 v127, v0
.Lzs10:
.LBB0_327:
	s_add_u32 s52, s50, 0xfff80080
	s_addc_u32 s53, s51, -1
	s_add_i32 s56, 0, 0x10000
	s_cmp_eq_u32 s45, 28
	s_cselect_b32 s55, s19, s53
	s_cselect_b32 s54, s34, s52
	v_add_u32_e32 v140, s56, v143
	s_cselect_b32 s53, s31, s43
	s_cselect_b32 s52, s35, s37
	s_add_i32 s58, 0, 0x14000
	ds_read_b128 v[146:149], v140
	ds_read_b128 v[150:153], v140 offset:1024
	ds_read_b128 v[154:157], v140 offset:2048
	ds_read_b128 v[158:161], v140 offset:3072
	v_add_u32_e32 v140, s58, v143
	ds_read_b128 v[162:165], v140
	ds_read_b128 v[166:169], v140 offset:1024
	ds_read_b128 v[170:173], v140 offset:2048
	ds_read_b128 v[174:177], v140 offset:3072
	v_lshl_add_u64 v[140:141], s[50:51], 0, v[136:137]
	s_add_i32 m0, s10, 0xc000
	ds_read_b128 v[178:181], v145
	ds_read_b128 v[182:185], v145 offset:1024
	ds_read_b128 v[186:189], v145 offset:2048
	ds_read_b128 v[190:193], v145 offset:3072
	ds_read_b128 v[220:223], v145 offset:4096
	ds_read_b128 v[224:227], v145 offset:5120
	ds_read_b128 v[228:231], v145 offset:6144
	ds_read_b128 v[232:235], v145 offset:7168
	global_load_lds_dwordx4 v[140:141], off
	v_lshl_add_u64 v[140:141], s[50:51], 0, v[138:139]
	s_add_i32 m0, s10, 0xe000
	s_nop 0
	global_load_lds_dwordx4 v[140:141], off
	s_cmp_lt_i32 s45, 0
	s_cbranch_scc0 .Lrx10_0_norm
	s_cmp_lt_u32 s33, 2
	s_cbranch_scc1 .Lrx10_0_norm
	s_waitcnt vmcnt(24)
	s_branch .Lrx10_0_join

; __device__ __forceinline__ u32x4 pack8_bf16(f32x4 a, f32x4 b) { u32x4 w; w.x = cvt_pk_bf16(a[0], a[1]); w.y = cvt_pk_bf16(a[2], a[3]); w.z = cvt_pk_bf16(b[0], b[1]); w.w = cvt_pk_bf16(b[2], b[3]); return w; }
; #define ACT(t) (KBASE(t) <= qlo + QBLK - 1 && KBASE(t) + KVBLK - 1 >= qlo - W + 1)
;     __device__ __forceinline__ void operator()(const f32x4 (&acc)[2][2][4][2], const Unit& u, int wr, int wc, int fr, int fq) const {
;         const int g = u.pn / nNper, pnl = u.pn - g * nNper, pml = u.pm & 63;
;         bf16_t* base = O + (size_t)g * gstride;
;         const int row0 = pml * BM + wr * 64 + fr, col0 = pnl * BM + wc * 32 + 8 * fq;
; #pragma unroll
;         for (int ai = 0; ai < 2; ++ai)
; #pragma unroll
;             for (int m = 0; m < 4; ++m) { bf16_t* rowp = base + (size_t)(row0 + ai * HALF + m * 16) * ldc + col0;
; #pragma unroll
;                 for (int bj = 0; bj < 2; ++bj) { f32x4 v0 = acc[ai][bj][m][0], v1 = acc[ai][bj][m][1];
;                     if (ACT == 1) {
; #pragma unroll
;                         for (int j = 0; j < 4; ++j) { float a = fmaxf(v0[j], 0.f), b = fmaxf(v1[j], 0.f); v0[j] = a * a; v1[j] = b * b; } }
;                     *(u32x4*)(rowp + bj * HALF) = pack8_bf16(v0, v1); } }
.LBB0_330:
	s_ashr_i32 s19, s42, 31
	s_lshr_b32 s19, s19, 29
	s_add_i32 s19, s42, s19
	s_ashr_i32 s34, s19, 3
	s_ashr_i32 s35, s34, 31
	s_lshl_b64 s[50:51], s[34:35], 26
	s_add_u32 s50, s86, s50
	s_addc_u32 s51, s87, s51
	s_lshl_b32 s19, s44, 8
	s_and_b32 s19, s19, 0x3f00
	v_add_u32_e32 v146, s19, v142
	s_lshl_b32 s19, s34, 11
	s_lshl_b32 s31, s42, 8
	s_sub_i32 s19, s31, s19
	v_or_b32_e32 v140, s19, v144
	v_ashrrev_i32_e32 v141, 31, v140
	v_ashrrev_i32_e32 v147, 31, v146
	v_lshl_add_u64 v[148:149], v[140:141], 1, s[50:51]
	v_lshlrev_b64 v[140:141], 12, v[146:147]
	v_lshl_add_u64 v[140:141], v[148:149], 0, v[140:141]
	s_mov_b64 s[34:35], 0x10000
	v_mov_b32_e32 v242, 0x8000
	v_mov_b32_e32 v243, 0
	v_and_b32_e32 v238, 8, v208
	v_cmp_ne_u32_e32 vcc, 0, v238
	v_and_b32_e32 v240, 63, v208
	v_lshrrev_b32_e32 v241, 3, v240
	v_and_b32_e32 v244, 3, v240
	v_lshl_add_u32 v241, v244, 4, v241
	v_and_b32_e32 v244, 4, v240
	v_lshl_add_u32 v241, v244, 1, v241
	v_lshlrev_b32_e32 v240, 2, v241
	v_cvt_pk_bf16_f32 v124, v124, v125
	v_cvt_pk_bf16_f32 v125, v126, v127
	v_cvt_pk_bf16_f32 v126, v120, v121
	v_cvt_pk_bf16_f32 v127, v122, v123
	v_cvt_pk_bf16_f32 v112, v112, v113
	v_cvt_pk_bf16_f32 v113, v114, v115
	v_cvt_pk_bf16_f32 v114, v104, v105
	v_cvt_pk_bf16_f32 v115, v106, v107
	v_mov_b32_dpp v246, v112 row_ror:8 row_mask:0xf bank_mask:0xf
	v_mov_b32_dpp v247, v113 row_ror:8 row_mask:0xf bank_mask:0xf
	v_mov_b32_dpp v248, v114 row_ror:8 row_mask:0xf bank_mask:0xf
	v_mov_b32_dpp v249, v115 row_ror:8 row_mask:0xf bank_mask:0xf
	v_mov_b32_dpp v250, v124 row_ror:8 row_mask:0xf bank_mask:0xf
	v_mov_b32_dpp v251, v125 row_ror:8 row_mask:0xf bank_mask:0xf
	v_mov_b32_dpp v252, v126 row_ror:8 row_mask:0xf bank_mask:0xf
	v_mov_b32_dpp v253, v127 row_ror:8 row_mask:0xf bank_mask:0xf
	v_cndmask_b32_e32 v246, v124, v246, vcc
	v_cndmask_b32_e32 v247, v125, v247, vcc
	v_cndmask_b32_e32 v248, v126, v248, vcc
	v_cndmask_b32_e32 v249, v127, v249, vcc
	v_cndmask_b32_e32 v250, v250, v112, vcc
	v_cndmask_b32_e32 v251, v251, v113, vcc
	v_cndmask_b32_e32 v252, v252, v114, vcc
	v_cndmask_b32_e32 v253, v253, v115, vcc
	ds_bpermute_b32 v246, v240, v246
	ds_bpermute_b32 v247, v240, v247
	ds_bpermute_b32 v248, v240, v248
	ds_bpermute_b32 v249, v240, v249
	ds_bpermute_b32 v250, v240, v250
	ds_bpermute_b32 v251, v240, v251
	ds_bpermute_b32 v252, v240, v252
	ds_bpermute_b32 v253, v240, v253
	v_mov_b32_e32 v124, 0
	v_mov_b32_e32 v125, 0
	v_mov_b32_e32 v126, 0
	v_mov_b32_e32 v127, 0
	v_mov_b32_e32 v120, 0
	v_mov_b32_e32 v121, 0
	v_mov_b32_e32 v122, 0
	v_mov_b32_e32 v123, 0
	v_mov_b32_e32 v112, 0
	v_mov_b32_e32 v113, 0
	v_mov_b32_e32 v114, 0
	v_mov_b32_e32 v115, 0
	v_mov_b32_e32 v104, 0
	v_mov_b32_e32 v105, 0
	v_mov_b32_e32 v106, 0
	v_mov_b32_e32 v107, 0
	v_lshl_add_u64 v[238:239], v[140:141], 0, v[242:243]
	s_waitcnt lgkmcnt(4)
	global_store_dwordx4 v[140:141], v[246:249], off
	s_waitcnt lgkmcnt(0)
	global_store_dwordx4 v[238:239], v[250:253], off
	v_lshl_add_u64 v[140:141], v[140:141], 0, s[34:35]
	v_cvt_pk_bf16_f32 v116, v116, v117
	v_cvt_pk_bf16_f32 v117, v118, v119
	v_cvt_pk_bf16_f32 v118, v108, v109
	v_cvt_pk_bf16_f32 v119, v110, v111
	v_cvt_pk_bf16_f32 v96, v96, v97
	v_cvt_pk_bf16_f32 v97, v98, v99
	v_cvt_pk_bf16_f32 v98, v88, v89
	v_cvt_pk_bf16_f32 v99, v90, v91
	v_mov_b32_dpp v246, v96 row_ror:8 row_mask:0xf bank_mask:0xf
	v_mov_b32_dpp v247, v97 row_ror:8 row_mask:0xf bank_mask:0xf
	v_mov_b32_dpp v248, v98 row_ror:8 row_mask:0xf bank_mask:0xf
	v_mov_b32_dpp v249, v99 row_ror:8 row_mask:0xf bank_mask:0xf
	v_mov_b32_dpp v250, v116 row_ror:8 row_mask:0xf bank_mask:0xf
	v_mov_b32_dpp v251, v117 row_ror:8 row_mask:0xf bank_mask:0xf
	v_mov_b32_dpp v252, v118 row_ror:8 row_mask:0xf bank_mask:0xf
	v_mov_b32_dpp v253, v119 row_ror:8 row_mask:0xf bank_mask:0xf
	v_cndmask_b32_e32 v246, v116, v246, vcc
	v_cndmask_b32_e32 v247, v117, v247, vcc
	v_cndmask_b32_e32 v248, v118, v248, vcc
	v_cndmask_b32_e32 v249, v119, v249, vcc
	v_cndmask_b32_e32 v250, v250, v96, vcc
	v_cndmask_b32_e32 v251, v251, v97, vcc
	v_cndmask_b32_e32 v252, v252, v98, vcc
	v_cndmask_b32_e32 v253, v253, v99, vcc
	ds_bpermute_b32 v246, v240, v246
	ds_bpermute_b32 v247, v240, v247
	ds_bpermute_b32 v248, v240, v248
	ds_bpermute_b32 v249, v240, v249
	ds_bpermute_b32 v250, v240, v250
	ds_bpermute_b32 v251, v240, v251
	ds_bpermute_b32 v252, v240, v252
	ds_bpermute_b32 v253, v240, v253
	v_mov_b32_e32 v116, 0
	v_mov_b32_e32 v117, 0
	v_mov_b32_e32 v118, 0
	v_mov_b32_e32 v119, 0
	v_mov_b32_e32 v108, 0
	v_mov_b32_e32 v109, 0
	v_mov_b32_e32 v110, 0
	v_mov_b32_e32 v111, 0
	v_mov_b32_e32 v96, 0
	v_mov_b32_e32 v97, 0
	v_mov_b32_e32 v98, 0
	v_mov_b32_e32 v99, 0
	v_mov_b32_e32 v88, 0
	v_mov_b32_e32 v89, 0
	v_mov_b32_e32 v90, 0
	v_mov_b32_e32 v91, 0
	v_lshl_add_u64 v[238:239], v[140:141], 0, v[242:243]
	s_waitcnt lgkmcnt(4)
	global_store_dwordx4 v[140:141], v[246:249], off
	s_waitcnt lgkmcnt(0)
; __device__ __forceinline__ u32x4 pack8_bf16(f32x4 a, f32x4 b) { u32x4 w; w.x = cvt_pk_bf16(a[0], a[1]); w.y = cvt_pk_bf16(a[2], a[3]); w.z = cvt_pk_bf16(b[0], b[1]); w.w = cvt_pk_bf16(b[2], b[3]); return w; }
; #define ACT(t) (KBASE(t) <= qlo + QBLK - 1 && KBASE(t) + KVBLK - 1 >= qlo - W + 1)
;     __device__ __forceinline__ void operator()(const f32x4 (&acc)[2][2][4][2], const Unit& u, int wr, int wc, int fr, int fq) const {
;     ...
;             for (int m = 0; m < 4; ++m) { bf16_t* rowp = base + (size_t)(row0 + ai * HALF + m * 16) * ldc + col0;
; #pragma unroll
;                 for (int bj = 0; bj < 2; ++bj) { f32x4 v0 = acc[ai][bj][m][0], v1 = acc[ai][bj][m][1];
;                     if (ACT == 1) {
; #pragma unroll
;                         for (int j = 0; j < 4; ++j) { float a = fmaxf(v0[j], 0.f), b = fmaxf(v1[j], 0.f); v0[j] = a * a; v1[j] = b * b; } }
;                     *(u32x4*)(rowp + bj * HALF) = pack8_bf16(v0, v1); } }
	global_store_dwordx4 v[238:239], v[250:253], off
	v_lshl_add_u64 v[140:141], v[140:141], 0, s[34:35]
	v_cvt_pk_bf16_f32 v100, v100, v101
	v_cvt_pk_bf16_f32 v101, v102, v103
	v_cvt_pk_bf16_f32 v102, v92, v93
	v_cvt_pk_bf16_f32 v103, v94, v95
	v_cvt_pk_bf16_f32 v80, v80, v81
	v_cvt_pk_bf16_f32 v81, v82, v83
	v_cvt_pk_bf16_f32 v82, v72, v73
	v_cvt_pk_bf16_f32 v83, v74, v75
	v_mov_b32_dpp v246, v80 row_ror:8 row_mask:0xf bank_mask:0xf
	v_mov_b32_dpp v247, v81 row_ror:8 row_mask:0xf bank_mask:0xf
	v_mov_b32_dpp v248, v82 row_ror:8 row_mask:0xf bank_mask:0xf
	v_mov_b32_dpp v249, v83 row_ror:8 row_mask:0xf bank_mask:0xf
	v_mov_b32_dpp v250, v100 row_ror:8 row_mask:0xf bank_mask:0xf
	v_mov_b32_dpp v251, v101 row_ror:8 row_mask:0xf bank_mask:0xf
	v_mov_b32_dpp v252, v102 row_ror:8 row_mask:0xf bank_mask:0xf
	v_mov_b32_dpp v253, v103 row_ror:8 row_mask:0xf bank_mask:0xf
	v_cndmask_b32_e32 v246, v100, v246, vcc
	v_cndmask_b32_e32 v247, v101, v247, vcc
	v_cndmask_b32_e32 v248, v102, v248, vcc
	v_cndmask_b32_e32 v249, v103, v249, vcc
	v_cndmask_b32_e32 v250, v250, v80, vcc
	v_cndmask_b32_e32 v251, v251, v81, vcc
	v_cndmask_b32_e32 v252, v252, v82, vcc
	v_cndmask_b32_e32 v253, v253, v83, vcc
	ds_bpermute_b32 v246, v240, v246
	ds_bpermute_b32 v247, v240, v247
	ds_bpermute_b32 v248, v240, v248
	ds_bpermute_b32 v249, v240, v249
	ds_bpermute_b32 v250, v240, v250
	ds_bpermute_b32 v251, v240, v251
	ds_bpermute_b32 v252, v240, v252
	ds_bpermute_b32 v253, v240, v253
	v_mov_b32_e32 v100, 0
	v_mov_b32_e32 v101, 0
	v_mov_b32_e32 v102, 0
	v_mov_b32_e32 v103, 0
	v_mov_b32_e32 v92, 0
	v_mov_b32_e32 v93, 0
	v_mov_b32_e32 v94, 0
	v_mov_b32_e32 v95, 0
	v_mov_b32_e32 v80, 0
	v_mov_b32_e32 v81, 0
	v_mov_b32_e32 v82, 0
	v_mov_b32_e32 v83, 0
	v_mov_b32_e32 v72, 0
	v_mov_b32_e32 v73, 0
	v_mov_b32_e32 v74, 0
	v_mov_b32_e32 v75, 0
	v_lshl_add_u64 v[238:239], v[140:141], 0, v[242:243]
	s_waitcnt lgkmcnt(4)
	global_store_dwordx4 v[140:141], v[246:249], off
	s_waitcnt lgkmcnt(0)
	global_store_dwordx4 v[238:239], v[250:253], off
	v_lshl_add_u64 v[140:141], v[140:141], 0, s[34:35]
	v_cvt_pk_bf16_f32 v84, v84, v85
	v_cvt_pk_bf16_f32 v85, v86, v87
	v_cvt_pk_bf16_f32 v86, v76, v77
	v_cvt_pk_bf16_f32 v87, v78, v79
	v_cvt_pk_bf16_f32 v68, v68, v69
	v_cvt_pk_bf16_f32 v69, v70, v71
	v_cvt_pk_bf16_f32 v70, v64, v65
	v_cvt_pk_bf16_f32 v71, v66, v67
	v_mov_b32_dpp v246, v68 row_ror:8 row_mask:0xf bank_mask:0xf
	v_mov_b32_dpp v247, v69 row_ror:8 row_mask:0xf bank_mask:0xf
	v_mov_b32_dpp v248, v70 row_ror:8 row_mask:0xf bank_mask:0xf
	v_mov_b32_dpp v249, v71 row_ror:8 row_mask:0xf bank_mask:0xf
	v_mov_b32_dpp v250, v84 row_ror:8 row_mask:0xf bank_mask:0xf
	v_mov_b32_dpp v251, v85 row_ror:8 row_mask:0xf bank_mask:0xf
	v_mov_b32_dpp v252, v86 row_ror:8 row_mask:0xf bank_mask:0xf
	v_mov_b32_dpp v253, v87 row_ror:8 row_mask:0xf bank_mask:0xf
	v_cndmask_b32_e32 v246, v84, v246, vcc
	v_cndmask_b32_e32 v247, v85, v247, vcc
	v_cndmask_b32_e32 v248, v86, v248, vcc
	v_cndmask_b32_e32 v249, v87, v249, vcc
	v_cndmask_b32_e32 v250, v250, v68, vcc
	v_cndmask_b32_e32 v251, v251, v69, vcc
	v_cndmask_b32_e32 v252, v252, v70, vcc
	v_cndmask_b32_e32 v253, v253, v71, vcc
	ds_bpermute_b32 v246, v240, v246
	ds_bpermute_b32 v247, v240, v247
	ds_bpermute_b32 v248, v240, v248
	ds_bpermute_b32 v249, v240, v249
	ds_bpermute_b32 v250, v240, v250
	ds_bpermute_b32 v251, v240, v251
	ds_bpermute_b32 v252, v240, v252
	ds_bpermute_b32 v253, v240, v253
	v_mov_b32_e32 v84, 0
	v_mov_b32_e32 v85, 0
	v_mov_b32_e32 v86, 0
	v_mov_b32_e32 v87, 0
	v_mov_b32_e32 v76, 0
	v_mov_b32_e32 v77, 0
	v_mov_b32_e32 v78, 0
	v_mov_b32_e32 v79, 0
	v_mov_b32_e32 v68, 0
	v_mov_b32_e32 v69, 0
	v_mov_b32_e32 v70, 0
	v_mov_b32_e32 v71, 0
	v_mov_b32_e32 v64, 0
	v_mov_b32_e32 v65, 0
	v_mov_b32_e32 v66, 0
	v_mov_b32_e32 v67, 0
	v_lshl_add_u64 v[238:239], v[140:141], 0, v[242:243]
	s_waitcnt lgkmcnt(4)
	global_store_dwordx4 v[140:141], v[246:249], off
	s_waitcnt lgkmcnt(0)
	global_store_dwordx4 v[238:239], v[250:253], off
	s_mov_b64 s[34:35], 0x50000
	v_lshl_add_u64 v[140:141], v[140:141], 0, s[34:35]
	s_mov_b64 s[34:35], 0x10000
	v_cvt_pk_bf16_f32 v60, v60, v61
	v_cvt_pk_bf16_f32 v61, v62, v63
	v_cvt_pk_bf16_f32 v62, v56, v57
	v_cvt_pk_bf16_f32 v63, v58, v59
	v_cvt_pk_bf16_f32 v48, v48, v49
	v_cvt_pk_bf16_f32 v49, v50, v51
	v_cvt_pk_bf16_f32 v50, v40, v41
	v_cvt_pk_bf16_f32 v51, v42, v43
	v_mov_b32_dpp v246, v48 row_ror:8 row_mask:0xf bank_mask:0xf
	v_mov_b32_dpp v247, v49 row_ror:8 row_mask:0xf bank_mask:0xf
	v_mov_b32_dpp v248, v50 row_ror:8 row_mask:0xf bank_mask:0xf
	v_mov_b32_dpp v249, v51 row_ror:8 row_mask:0xf bank_mask:0xf
	v_mov_b32_dpp v250, v60 row_ror:8 row_mask:0xf bank_mask:0xf
	v_mov_b32_dpp v251, v61 row_ror:8 row_mask:0xf bank_mask:0xf
	v_mov_b32_dpp v252, v62 row_ror:8 row_mask:0xf bank_mask:0xf
	v_mov_b32_dpp v253, v63 row_ror:8 row_mask:0xf bank_mask:0xf
	v_cndmask_b32_e32 v246, v60, v246, vcc
	v_cndmask_b32_e32 v247, v61, v247, vcc
	v_cndmask_b32_e32 v248, v62, v248, vcc
	v_cndmask_b32_e32 v249, v63, v249, vcc
	v_cndmask_b32_e32 v250, v250, v48, vcc
	v_cndmask_b32_e32 v251, v251, v49, vcc
	v_cndmask_b32_e32 v252, v252, v50, vcc
	v_cndmask_b32_e32 v253, v253, v51, vcc
	ds_bpermute_b32 v246, v240, v246
	ds_bpermute_b32 v247, v240, v247
	ds_bpermute_b32 v248, v240, v248
	ds_bpermute_b32 v249, v240, v249
	ds_bpermute_b32 v250, v240, v250
	ds_bpermute_b32 v251, v240, v251
	ds_bpermute_b32 v252, v240, v252
	ds_bpermute_b32 v253, v240, v253
	v_mov_b32_e32 v60, 0
	v_mov_b32_e32 v61, 0
	v_mov_b32_e32 v62, 0
	v_mov_b32_e32 v63, 0
	v_mov_b32_e32 v56, 0
	v_mov_b32_e32 v57, 0
	v_mov_b32_e32 v58, 0
	v_mov_b32_e32 v59, 0
	v_mov_b32_e32 v48, 0
	v_mov_b32_e32 v49, 0
	v_mov_b32_e32 v50, 0
	v_mov_b32_e32 v51, 0
	v_mov_b32_e32 v40, 0
	v_mov_b32_e32 v41, 0
	v_mov_b32_e32 v42, 0
	v_mov_b32_e32 v43, 0
	v_lshl_add_u64 v[238:239], v[140:141], 0, v[242:243]
	s_waitcnt lgkmcnt(4)
; __device__ __forceinline__ u32x4 pack8_bf16(f32x4 a, f32x4 b) { u32x4 w; w.x = cvt_pk_bf16(a[0], a[1]); w.y = cvt_pk_bf16(a[2], a[3]); w.z = cvt_pk_bf16(b[0], b[1]); w.w = cvt_pk_bf16(b[2], b[3]); return w; }
; #define PG8_BAR __builtin_amdgcn_s_barrier()
; #define ACT(t) (KBASE(t) <= qlo + QBLK - 1 && KBASE(t) + KVBLK - 1 >= qlo - W + 1)
;     __device__ __forceinline__ void operator()(const f32x4 (&acc)[2][2][4][2], const Unit& u, int wr, int wc, int fr, int fq) const {
;     ...
;             for (int m = 0; m < 4; ++m) { bf16_t* rowp = base + (size_t)(row0 + ai * HALF + m * 16) * ldc + col0;
; #pragma unroll
;                 for (int bj = 0; bj < 2; ++bj) { f32x4 v0 = acc[ai][bj][m][0], v1 = acc[ai][bj][m][1];
;                     if (ACT == 1) {
; #pragma unroll
;                         for (int j = 0; j < 4; ++j) { float a = fmaxf(v0[j], 0.f), b = fmaxf(v1[j], 0.f); v0[j] = a * a; v1[j] = b * b; } }
;                     *(u32x4*)(rowp + bj * HALF) = pack8_bf16(v0, v1); } }
; template <class Epi, class Sched, bool ALIGN_EPI = false, bool SP2 = false>
; __device__ __forceinline__ void gemm_phase(PG8_LAS unsigned char* lds, const Gemm g, const Sched& S, const Epi& E) {
;     ...
;         if (!has_next) break;
; #pragma unroll
;         for (int a = 0; a < 2; ++a)
; #pragma unroll
;             for (int b = 0; b < 2; ++b)
; #pragma unroll
;                 for (int m = 0; m < 4; ++m)
; #pragma unroll
;                     for (int n = 0; n < 2; ++n) acc[a][b][m][n] = (f32x4){0.f, 0.f, 0.f, 0.f};
;         cur = nxt; cA = nA; cB = nB; ++ui;
;         if constexpr (ALIGN_EPI) { if (wr == 1) PG8_BAR; }
	global_store_dwordx4 v[140:141], v[246:249], off
	s_waitcnt lgkmcnt(0)
	global_store_dwordx4 v[238:239], v[250:253], off
	v_lshl_add_u64 v[140:141], v[140:141], 0, s[34:35]
	v_cvt_pk_bf16_f32 v52, v52, v53
	v_cvt_pk_bf16_f32 v53, v54, v55
	v_cvt_pk_bf16_f32 v54, v44, v45
	v_cvt_pk_bf16_f32 v55, v46, v47
	v_cvt_pk_bf16_f32 v32, v32, v33
	v_cvt_pk_bf16_f32 v33, v34, v35
	v_cvt_pk_bf16_f32 v34, v24, v25
	v_cvt_pk_bf16_f32 v35, v26, v27
	v_mov_b32_dpp v246, v32 row_ror:8 row_mask:0xf bank_mask:0xf
	v_mov_b32_dpp v247, v33 row_ror:8 row_mask:0xf bank_mask:0xf
	v_mov_b32_dpp v248, v34 row_ror:8 row_mask:0xf bank_mask:0xf
	v_mov_b32_dpp v249, v35 row_ror:8 row_mask:0xf bank_mask:0xf
	v_mov_b32_dpp v250, v52 row_ror:8 row_mask:0xf bank_mask:0xf
	v_mov_b32_dpp v251, v53 row_ror:8 row_mask:0xf bank_mask:0xf
	v_mov_b32_dpp v252, v54 row_ror:8 row_mask:0xf bank_mask:0xf
	v_mov_b32_dpp v253, v55 row_ror:8 row_mask:0xf bank_mask:0xf
	v_cndmask_b32_e32 v246, v52, v246, vcc
	v_cndmask_b32_e32 v247, v53, v247, vcc
	v_cndmask_b32_e32 v248, v54, v248, vcc
	v_cndmask_b32_e32 v249, v55, v249, vcc
	v_cndmask_b32_e32 v250, v250, v32, vcc
	v_cndmask_b32_e32 v251, v251, v33, vcc
	v_cndmask_b32_e32 v252, v252, v34, vcc
	v_cndmask_b32_e32 v253, v253, v35, vcc
	ds_bpermute_b32 v246, v240, v246
	ds_bpermute_b32 v247, v240, v247
	ds_bpermute_b32 v248, v240, v248
	ds_bpermute_b32 v249, v240, v249
	ds_bpermute_b32 v250, v240, v250
	ds_bpermute_b32 v251, v240, v251
	ds_bpermute_b32 v252, v240, v252
	ds_bpermute_b32 v253, v240, v253
	v_mov_b32_e32 v52, 0
	v_mov_b32_e32 v53, 0
	v_mov_b32_e32 v54, 0
	v_mov_b32_e32 v55, 0
	v_mov_b32_e32 v44, 0
	v_mov_b32_e32 v45, 0
	v_mov_b32_e32 v46, 0
	v_mov_b32_e32 v47, 0
	v_mov_b32_e32 v32, 0
	v_mov_b32_e32 v33, 0
	v_mov_b32_e32 v34, 0
	v_mov_b32_e32 v35, 0
	v_mov_b32_e32 v24, 0
	v_mov_b32_e32 v25, 0
	v_mov_b32_e32 v26, 0
	v_mov_b32_e32 v27, 0
	v_lshl_add_u64 v[238:239], v[140:141], 0, v[242:243]
	s_waitcnt lgkmcnt(4)
	global_store_dwordx4 v[140:141], v[246:249], off
	s_waitcnt lgkmcnt(0)
	global_store_dwordx4 v[238:239], v[250:253], off
	v_lshl_add_u64 v[140:141], v[140:141], 0, s[34:35]
	v_cvt_pk_bf16_f32 v36, v36, v37
	v_cvt_pk_bf16_f32 v37, v38, v39
	v_cvt_pk_bf16_f32 v38, v28, v29
	v_cvt_pk_bf16_f32 v39, v30, v31
	v_cvt_pk_bf16_f32 v16, v16, v17
	v_cvt_pk_bf16_f32 v17, v18, v19
	v_cvt_pk_bf16_f32 v18, v8, v9
	v_cvt_pk_bf16_f32 v19, v10, v11
	v_mov_b32_dpp v246, v16 row_ror:8 row_mask:0xf bank_mask:0xf
	v_mov_b32_dpp v247, v17 row_ror:8 row_mask:0xf bank_mask:0xf
	v_mov_b32_dpp v248, v18 row_ror:8 row_mask:0xf bank_mask:0xf
	v_mov_b32_dpp v249, v19 row_ror:8 row_mask:0xf bank_mask:0xf
	v_mov_b32_dpp v250, v36 row_ror:8 row_mask:0xf bank_mask:0xf
	v_mov_b32_dpp v251, v37 row_ror:8 row_mask:0xf bank_mask:0xf
	v_mov_b32_dpp v252, v38 row_ror:8 row_mask:0xf bank_mask:0xf
	v_mov_b32_dpp v253, v39 row_ror:8 row_mask:0xf bank_mask:0xf
	v_cndmask_b32_e32 v246, v36, v246, vcc
	v_cndmask_b32_e32 v247, v37, v247, vcc
	v_cndmask_b32_e32 v248, v38, v248, vcc
	v_cndmask_b32_e32 v249, v39, v249, vcc
	v_cndmask_b32_e32 v250, v250, v16, vcc
	v_cndmask_b32_e32 v251, v251, v17, vcc
	v_cndmask_b32_e32 v252, v252, v18, vcc
	v_cndmask_b32_e32 v253, v253, v19, vcc
	ds_bpermute_b32 v246, v240, v246
	ds_bpermute_b32 v247, v240, v247
	ds_bpermute_b32 v248, v240, v248
	ds_bpermute_b32 v249, v240, v249
	ds_bpermute_b32 v250, v240, v250
	ds_bpermute_b32 v251, v240, v251
	ds_bpermute_b32 v252, v240, v252
	ds_bpermute_b32 v253, v240, v253
	v_mov_b32_e32 v36, 0
	v_mov_b32_e32 v37, 0
	v_mov_b32_e32 v38, 0
	v_mov_b32_e32 v39, 0
	v_mov_b32_e32 v28, 0
	v_mov_b32_e32 v29, 0
	v_mov_b32_e32 v30, 0
	v_mov_b32_e32 v31, 0
	v_mov_b32_e32 v16, 0
	v_mov_b32_e32 v17, 0
	v_mov_b32_e32 v18, 0
	v_mov_b32_e32 v19, 0
	v_mov_b32_e32 v8, 0
	v_mov_b32_e32 v9, 0
	v_mov_b32_e32 v10, 0
	v_mov_b32_e32 v11, 0
	v_lshl_add_u64 v[238:239], v[140:141], 0, v[242:243]
	s_waitcnt lgkmcnt(4)
	global_store_dwordx4 v[140:141], v[246:249], off
	s_waitcnt lgkmcnt(0)
	global_store_dwordx4 v[238:239], v[250:253], off
	v_lshl_add_u64 v[140:141], v[140:141], 0, s[34:35]
	v_cvt_pk_bf16_f32 v20, v20, v21
	v_cvt_pk_bf16_f32 v21, v22, v23
	v_cvt_pk_bf16_f32 v22, v12, v13
	v_cvt_pk_bf16_f32 v23, v14, v15
	v_cvt_pk_bf16_f32 v4, v4, v5
	v_cvt_pk_bf16_f32 v5, v6, v7
	v_cvt_pk_bf16_f32 v6, v0, v1
	v_cvt_pk_bf16_f32 v7, v2, v3
	v_mov_b32_dpp v246, v4 row_ror:8 row_mask:0xf bank_mask:0xf
	v_mov_b32_dpp v247, v5 row_ror:8 row_mask:0xf bank_mask:0xf
	v_mov_b32_dpp v248, v6 row_ror:8 row_mask:0xf bank_mask:0xf
	v_mov_b32_dpp v249, v7 row_ror:8 row_mask:0xf bank_mask:0xf
	v_mov_b32_dpp v250, v20 row_ror:8 row_mask:0xf bank_mask:0xf
	v_mov_b32_dpp v251, v21 row_ror:8 row_mask:0xf bank_mask:0xf
	v_mov_b32_dpp v252, v22 row_ror:8 row_mask:0xf bank_mask:0xf
	v_mov_b32_dpp v253, v23 row_ror:8 row_mask:0xf bank_mask:0xf
	v_cndmask_b32_e32 v246, v20, v246, vcc
	v_cndmask_b32_e32 v247, v21, v247, vcc
	v_cndmask_b32_e32 v248, v22, v248, vcc
	v_cndmask_b32_e32 v249, v23, v249, vcc
	v_cndmask_b32_e32 v250, v250, v4, vcc
	v_cndmask_b32_e32 v251, v251, v5, vcc
	v_cndmask_b32_e32 v252, v252, v6, vcc
	v_cndmask_b32_e32 v253, v253, v7, vcc
	ds_bpermute_b32 v246, v240, v246
	ds_bpermute_b32 v247, v240, v247
	ds_bpermute_b32 v248, v240, v248
	ds_bpermute_b32 v249, v240, v249
	ds_bpermute_b32 v250, v240, v250
	ds_bpermute_b32 v251, v240, v251
	ds_bpermute_b32 v252, v240, v252
	ds_bpermute_b32 v253, v240, v253
	v_mov_b32_e32 v20, 0
	v_mov_b32_e32 v21, 0
	v_mov_b32_e32 v22, 0
	v_mov_b32_e32 v23, 0
	v_mov_b32_e32 v12, 0
	v_mov_b32_e32 v13, 0
	v_mov_b32_e32 v14, 0
	v_mov_b32_e32 v15, 0
	v_mov_b32_e32 v4, 0
	v_mov_b32_e32 v5, 0
	v_mov_b32_e32 v6, 0
	v_mov_b32_e32 v7, 0
	v_mov_b32_e32 v0, 0
	v_mov_b32_e32 v1, 0
	v_mov_b32_e32 v2, 0
	v_mov_b32_e32 v3, 0
	v_lshl_add_u64 v[238:239], v[140:141], 0, v[242:243]
	s_waitcnt lgkmcnt(4)
	global_store_dwordx4 v[140:141], v[246:249], off
	s_waitcnt lgkmcnt(0)
	global_store_dwordx4 v[238:239], v[250:253], off
	s_andn2_b64 vcc, exec, s[40:41]
	s_mov_b64 s[34:35], -1
	s_cbranch_vccnz .LBB0_319
	s_andn2_b64 vcc, exec, s[8:9]
	s_cbranch_vccnz .LBB0_318
	s_barrier
	s_branch .LBB0_318

; #define PG8_STAGE(bufoff, gbase, voff) do { _Pragma("unroll") for (int _i = 0; _i < 2; ++_i) \
;         __builtin_amdgcn_global_load_lds((const unsigned*)((const char*)(gbase) + (voff)[_i]), (PG8_LAS unsigned*)(lds + (bufoff) + ldsw + _i * 8192), 16, 0, 0); } while (0)
; #define PG8_LDA(dst, b, h) do { _Pragma("unroll") for (int m = 0; m < 4; ++m) _Pragma("unroll") for (int k = 0; k < 2; ++k) dst[m][k] = *(const PG8_LAS bf16x8*)(lds + PG8_SA(b, h) + aoff + m * 2048 + k * 1024); } while (0)
; #define PG8_LDB(dst, b, h) do { _Pragma("unroll") for (int n = 0; n < 2; ++n) _Pragma("unroll") for (int k = 0; k < 2; ++k) dst[n][k] = *(const PG8_LAS bf16x8*)(lds + PG8_SB(b, h) + boff + n * 2048 + k * 1024); } while (0)
; #define PG8_SCHED __builtin_amdgcn_sched_barrier(0)
; template <class Epi, class Sched, bool ALIGN_EPI = false, bool SP2 = false>
; __device__ __forceinline__ void gemm_phase(PG8_LAS unsigned char* lds, const Gemm g, const Sched& S, const Epi& E) {
;     ...
;         const bool has_next = S.next(ui + 1, nxt);
;         const char* nA = has_next ? (const char*)g.A + (size_t)nxt.pm * tstep : cA; const char* nB = has_next ? (const char*)g.Bt + (size_t)nxt.pn * tstep : cB;
; #pragma nounroll
;         for (int t = 0; t < nt; t += 2) {
;             const bool last = (t == nt - 2);
;             const char* a1 = cA + (size_t)(t + 1) * kstep;
;             const char* a2 = last ? nA : cA + (size_t)(t + 2) * kstep; const char* b2 = last ? nB : cB + (size_t)(t + 2) * kstep;
;             const char* a3 = a2 + kstep; const char* b3 = b2 + kstep;
;             if (last && has_next) S.a_ready(nxt);
;             if constexpr (SP2) {
;             PG8_LDB(B0, 0, 0); PG8_LDB(B1, 0, 1); PG8_SCHED; PG8_LDA(At, 0, 0); PG8_STAGE(PG8_SA(1, 1), a1 + hstep, voffA);
;     ...
; #pragma unroll
;         for (int a = 0; a < 2; ++a)
; #pragma unroll
;             for (int b = 0; b < 2; ++b)
; #pragma unroll
;                 for (int m = 0; m < 4; ++m)
; #pragma unroll
;                     for (int n = 0; n < 2; ++n) acc[a][b][m][n] = (f32x4){0.f, 0.f, 0.f, 0.f};
.LBB0_431:
	s_ashr_i32 s19, s18, 31
	s_lshl_b64 s[34:35], s[18:19], 22
	s_add_u32 s46, s60, s34
	s_addc_u32 s47, s61, s35
	s_and_b64 s[34:35], s[40:41], exec
	s_cselect_b32 s19, s47, s67
	s_cselect_b32 s34, s46, s66
	s_ashr_i32 s31, s30, 31
	s_lshl_b64 s[52:53], s[30:31], 22
	s_add_u32 s62, s50, s52
	s_addc_u32 s63, s51, s53
	s_and_b64 s[52:53], s[40:41], exec
	s_cselect_b32 s31, s63, s69
	s_cselect_b32 s35, s62, s68
	s_add_u32 s66, s66, 0x200080
	s_addc_u32 s67, s67, 0
	s_add_u32 s37, s68, 0x100
	v_mov_b32_e32 v0, 0
	s_addc_u32 s43, s69, 0
	s_mov_b32 s45, -2
	s_cmp_lt_u32 s33, 2
	s_cbranch_scc0 .Lzs7
	v_mov_b32_e32 v1, v0
	v_mov_b32_e32 v2, v0
	v_mov_b32_e32 v3, v0
	v_mov_b32_e32 v4, v0
	v_mov_b32_e32 v5, v0
	v_mov_b32_e32 v6, v0
	v_mov_b32_e32 v7, v0
	v_mov_b32_e32 v8, v0
	v_mov_b32_e32 v9, v0
	v_mov_b32_e32 v10, v0
	v_mov_b32_e32 v11, v0
	v_mov_b32_e32 v16, v0
	v_mov_b32_e32 v17, v0
	v_mov_b32_e32 v18, v0
	v_mov_b32_e32 v19, v0
	v_mov_b32_e32 v24, v0
	v_mov_b32_e32 v25, v0
	v_mov_b32_e32 v26, v0
	v_mov_b32_e32 v27, v0
	v_mov_b32_e32 v32, v0
	v_mov_b32_e32 v33, v0
	v_mov_b32_e32 v34, v0
	v_mov_b32_e32 v35, v0
	v_mov_b32_e32 v40, v0
	v_mov_b32_e32 v41, v0
	v_mov_b32_e32 v42, v0
	v_mov_b32_e32 v43, v0
	v_mov_b32_e32 v48, v0
	v_mov_b32_e32 v49, v0
	v_mov_b32_e32 v50, v0
	v_mov_b32_e32 v51, v0
	v_mov_b32_e32 v12, v0
	v_mov_b32_e32 v13, v0
	v_mov_b32_e32 v14, v0
	v_mov_b32_e32 v15, v0
	v_mov_b32_e32 v20, v0
	v_mov_b32_e32 v21, v0
	v_mov_b32_e32 v22, v0
	v_mov_b32_e32 v23, v0
	v_mov_b32_e32 v28, v0
	v_mov_b32_e32 v29, v0
	v_mov_b32_e32 v30, v0
	v_mov_b32_e32 v31, v0
	v_mov_b32_e32 v36, v0
	v_mov_b32_e32 v37, v0
	v_mov_b32_e32 v38, v0
	v_mov_b32_e32 v39, v0
	v_mov_b32_e32 v44, v0
	v_mov_b32_e32 v45, v0
	v_mov_b32_e32 v46, v0
	v_mov_b32_e32 v47, v0
	v_mov_b32_e32 v52, v0
	v_mov_b32_e32 v53, v0
	v_mov_b32_e32 v54, v0
	v_mov_b32_e32 v55, v0
	v_mov_b32_e32 v56, v0
	v_mov_b32_e32 v57, v0
	v_mov_b32_e32 v58, v0
	v_mov_b32_e32 v59, v0
	v_mov_b32_e32 v60, v0
	v_mov_b32_e32 v61, v0
	v_mov_b32_e32 v62, v0
	v_mov_b32_e32 v63, v0
	v_mov_b32_e32 v64, v0
	v_mov_b32_e32 v65, v0
	v_mov_b32_e32 v66, v0
	v_mov_b32_e32 v67, v0
	v_mov_b32_e32 v68, v0
	v_mov_b32_e32 v69, v0
	v_mov_b32_e32 v70, v0
	v_mov_b32_e32 v71, v0
	v_mov_b32_e32 v72, v0
	v_mov_b32_e32 v73, v0
	v_mov_b32_e32 v74, v0
	v_mov_b32_e32 v75, v0
	v_mov_b32_e32 v80, v0
	v_mov_b32_e32 v81, v0
	v_mov_b32_e32 v82, v0
	v_mov_b32_e32 v83, v0
	v_mov_b32_e32 v88, v0
	v_mov_b32_e32 v89, v0
	v_mov_b32_e32 v90, v0
	v_mov_b32_e32 v91, v0
	v_mov_b32_e32 v96, v0
	v_mov_b32_e32 v97, v0
	v_mov_b32_e32 v98, v0
	v_mov_b32_e32 v99, v0
	v_mov_b32_e32 v104, v0
	v_mov_b32_e32 v105, v0
	v_mov_b32_e32 v106, v0
	v_mov_b32_e32 v107, v0
	v_mov_b32_e32 v112, v0
	v_mov_b32_e32 v113, v0
	v_mov_b32_e32 v114, v0
	v_mov_b32_e32 v115, v0
	v_mov_b32_e32 v76, v0
	v_mov_b32_e32 v77, v0
	v_mov_b32_e32 v78, v0
	v_mov_b32_e32 v79, v0
	v_mov_b32_e32 v84, v0
	v_mov_b32_e32 v85, v0
	v_mov_b32_e32 v86, v0
	v_mov_b32_e32 v87, v0
	v_mov_b32_e32 v92, v0
	v_mov_b32_e32 v93, v0
	v_mov_b32_e32 v94, v0
	v_mov_b32_e32 v95, v0
	v_mov_b32_e32 v100, v0
	v_mov_b32_e32 v101, v0
	v_mov_b32_e32 v102, v0
	v_mov_b32_e32 v103, v0
	v_mov_b32_e32 v108, v0
	v_mov_b32_e32 v109, v0
	v_mov_b32_e32 v110, v0
	v_mov_b32_e32 v111, v0
	v_mov_b32_e32 v116, v0
	v_mov_b32_e32 v117, v0
	v_mov_b32_e32 v118, v0
	v_mov_b32_e32 v119, v0
	v_mov_b32_e32 v120, v0
	v_mov_b32_e32 v121, v0
	v_mov_b32_e32 v122, v0
	v_mov_b32_e32 v123, v0
	v_mov_b32_e32 v124, v0
	v_mov_b32_e32 v125, v0
	v_mov_b32_e32 v126, v0
	v_mov_b32_e32 v127, v0
.Lzs7:
.LBB0_432:
	s_add_u32 s49, s66, 0xffe00080
	s_addc_u32 s52, s67, -1
	s_add_i32 s53, 0, 0x10000
	s_cmpk_eq_i32 s45, 0x7c
	s_cselect_b32 s71, s19, s52
	s_cselect_b32 s70, s34, s49
	v_add_u32_e32 v140, s53, v143
	s_cselect_b32 s69, s31, s43
	s_cselect_b32 s68, s35, s37
	s_add_i32 s49, 0, 0x14000
	ds_read_b128 v[146:149], v140
	ds_read_b128 v[150:153], v140 offset:1024
	ds_read_b128 v[154:157], v140 offset:2048
	ds_read_b128 v[158:161], v140 offset:3072
	v_add_u32_e32 v140, s49, v143
	ds_read_b128 v[162:165], v140
	ds_read_b128 v[166:169], v140 offset:1024
	ds_read_b128 v[170:173], v140 offset:2048
	ds_read_b128 v[174:177], v140 offset:3072
	v_lshl_add_u64 v[140:141], s[66:67], 0, v[136:137]
	s_add_i32 m0, s10, 0xc000
	ds_read_b128 v[178:181], v145
	ds_read_b128 v[182:185], v145 offset:1024
	ds_read_b128 v[186:189], v145 offset:2048
	ds_read_b128 v[190:193], v145 offset:3072
	ds_read_b128 v[220:223], v145 offset:4096
	ds_read_b128 v[224:227], v145 offset:5120
	ds_read_b128 v[228:231], v145 offset:6144
	ds_read_b128 v[232:235], v145 offset:7168
	global_load_lds_dwordx4 v[140:141], off
	v_lshl_add_u64 v[140:141], s[66:67], 0, v[138:139]
	s_add_i32 m0, s10, 0xe000
	s_nop 0
	global_load_lds_dwordx4 v[140:141], off
	s_cmp_lt_i32 s45, 0
	s_cbranch_scc0 .Lrx7_0_norm
	s_cmp_lt_u32 s33, 2
	s_cbranch_scc1 .Lrx7_0_norm
	s_waitcnt vmcnt(24)
	s_branch .Lrx7_0_join

; __device__ __forceinline__ u32x4 pack8_bf16(f32x4 a, f32x4 b) { u32x4 w; w.x = cvt_pk_bf16(a[0], a[1]); w.y = cvt_pk_bf16(a[2], a[3]); w.z = cvt_pk_bf16(b[0], b[1]); w.w = cvt_pk_bf16(b[2], b[3]); return w; }
; #define ACT(t) (KBASE(t) <= qlo + QBLK - 1 && KBASE(t) + KVBLK - 1 >= qlo - W + 1)
;     __device__ __forceinline__ void operator()(const f32x4 (&acc)[2][2][4][2], const Unit& u, int wr, int wc, int fr, int fq) const {
;         const int g = u.pn / nNper, pnl = u.pn - g * nNper, pml = u.pm & 63;
;         bf16_t* base = O + (size_t)g * gstride;
;         const int row0 = pml * BM + wr * 64 + fr, col0 = pnl * BM + wc * 32 + 8 * fq;
; #pragma unroll
;         for (int ai = 0; ai < 2; ++ai)
; #pragma unroll
;             for (int m = 0; m < 4; ++m) { bf16_t* rowp = base + (size_t)(row0 + ai * HALF + m * 16) * ldc + col0;
; #pragma unroll
;                 for (int bj = 0; bj < 2; ++bj) { f32x4 v0 = acc[ai][bj][m][0], v1 = acc[ai][bj][m][1];
;                     if (ACT == 1) {
; #pragma unroll
;                         for (int j = 0; j < 4; ++j) { float a = fmaxf(v0[j], 0.f), b = fmaxf(v1[j], 0.f); v0[j] = a * a; v1[j] = b * b; } }
;                     *(u32x4*)(rowp + bj * HALF) = pack8_bf16(v0, v1); } }
.LBB0_435:
	s_ashr_i32 s19, s44, 31
	s_lshr_b32 s19, s19, 29
	s_add_i32 s19, s44, s19
	s_and_b32 s19, s19, 0xfffff8
	s_lshl_b32 s31, s42, 8
	s_sub_i32 s19, s44, s19
	s_and_b32 s31, s31, 0x3f00
	v_add_u32_e32 v146, s31, v142
	v_lshl_or_b32 v140, s19, 8, v144
	v_ashrrev_i32_e32 v141, 31, v140
	v_ashrrev_i32_e32 v147, 31, v146
	v_lshl_add_u64 v[148:149], v[140:141], 1, s[56:57]
	v_lshlrev_b64 v[140:141], 12, v[146:147]
	v_lshl_add_u64 v[140:141], v[148:149], 0, v[140:141]
	s_mov_b64 s[34:35], 0x10000
	v_mov_b32_e32 v242, 0x8000
	v_mov_b32_e32 v243, 0
	v_and_b32_e32 v238, 8, v208
	v_cmp_ne_u32_e32 vcc, 0, v238
	v_and_b32_e32 v240, 63, v208
	v_lshrrev_b32_e32 v241, 3, v240
	v_and_b32_e32 v244, 3, v240
	v_lshl_add_u32 v241, v244, 4, v241
	v_and_b32_e32 v244, 4, v240
	v_lshl_add_u32 v241, v244, 1, v241
	v_lshlrev_b32_e32 v240, 2, v241
	v_cvt_pk_bf16_f32 v124, v124, v125
	v_cvt_pk_bf16_f32 v125, v126, v127
	v_cvt_pk_bf16_f32 v126, v120, v121
	v_cvt_pk_bf16_f32 v127, v122, v123
	v_cvt_pk_bf16_f32 v112, v112, v113
	v_cvt_pk_bf16_f32 v113, v114, v115
	v_cvt_pk_bf16_f32 v114, v104, v105
	v_cvt_pk_bf16_f32 v115, v106, v107
	v_mov_b32_dpp v246, v112 row_ror:8 row_mask:0xf bank_mask:0xf
	v_mov_b32_dpp v247, v113 row_ror:8 row_mask:0xf bank_mask:0xf
	v_mov_b32_dpp v248, v114 row_ror:8 row_mask:0xf bank_mask:0xf
	v_mov_b32_dpp v249, v115 row_ror:8 row_mask:0xf bank_mask:0xf
	v_mov_b32_dpp v250, v124 row_ror:8 row_mask:0xf bank_mask:0xf
	v_mov_b32_dpp v251, v125 row_ror:8 row_mask:0xf bank_mask:0xf
	v_mov_b32_dpp v252, v126 row_ror:8 row_mask:0xf bank_mask:0xf
	v_mov_b32_dpp v253, v127 row_ror:8 row_mask:0xf bank_mask:0xf
	v_cndmask_b32_e32 v246, v124, v246, vcc
	v_cndmask_b32_e32 v247, v125, v247, vcc
	v_cndmask_b32_e32 v248, v126, v248, vcc
	v_cndmask_b32_e32 v249, v127, v249, vcc
	v_cndmask_b32_e32 v250, v250, v112, vcc
	v_cndmask_b32_e32 v251, v251, v113, vcc
	v_cndmask_b32_e32 v252, v252, v114, vcc
	v_cndmask_b32_e32 v253, v253, v115, vcc
	ds_bpermute_b32 v246, v240, v246
	ds_bpermute_b32 v247, v240, v247
	ds_bpermute_b32 v248, v240, v248
	ds_bpermute_b32 v249, v240, v249
	ds_bpermute_b32 v250, v240, v250
	ds_bpermute_b32 v251, v240, v251
	ds_bpermute_b32 v252, v240, v252
	ds_bpermute_b32 v253, v240, v253
	v_mov_b32_e32 v124, 0
	v_mov_b32_e32 v125, 0
	v_mov_b32_e32 v126, 0
	v_mov_b32_e32 v127, 0
	v_mov_b32_e32 v120, 0
	v_mov_b32_e32 v121, 0
	v_mov_b32_e32 v122, 0
	v_mov_b32_e32 v123, 0
	v_mov_b32_e32 v112, 0
	v_mov_b32_e32 v113, 0
	v_mov_b32_e32 v114, 0
	v_mov_b32_e32 v115, 0
	v_mov_b32_e32 v104, 0
	v_mov_b32_e32 v105, 0
	v_mov_b32_e32 v106, 0
	v_mov_b32_e32 v107, 0
	v_lshl_add_u64 v[238:239], v[140:141], 0, v[242:243]
	s_waitcnt lgkmcnt(4)
	global_store_dwordx4 v[140:141], v[246:249], off
	s_waitcnt lgkmcnt(0)
	global_store_dwordx4 v[238:239], v[250:253], off
	v_lshl_add_u64 v[140:141], v[140:141], 0, s[34:35]
	v_cvt_pk_bf16_f32 v116, v116, v117
	v_cvt_pk_bf16_f32 v117, v118, v119
	v_cvt_pk_bf16_f32 v118, v108, v109
	v_cvt_pk_bf16_f32 v119, v110, v111
	v_cvt_pk_bf16_f32 v96, v96, v97
	v_cvt_pk_bf16_f32 v97, v98, v99
	v_cvt_pk_bf16_f32 v98, v88, v89
	v_cvt_pk_bf16_f32 v99, v90, v91
	v_mov_b32_dpp v246, v96 row_ror:8 row_mask:0xf bank_mask:0xf
	v_mov_b32_dpp v247, v97 row_ror:8 row_mask:0xf bank_mask:0xf
	v_mov_b32_dpp v248, v98 row_ror:8 row_mask:0xf bank_mask:0xf
	v_mov_b32_dpp v249, v99 row_ror:8 row_mask:0xf bank_mask:0xf
	v_mov_b32_dpp v250, v116 row_ror:8 row_mask:0xf bank_mask:0xf
	v_mov_b32_dpp v251, v117 row_ror:8 row_mask:0xf bank_mask:0xf
	v_mov_b32_dpp v252, v118 row_ror:8 row_mask:0xf bank_mask:0xf
	v_mov_b32_dpp v253, v119 row_ror:8 row_mask:0xf bank_mask:0xf
	v_cndmask_b32_e32 v246, v116, v246, vcc
	v_cndmask_b32_e32 v247, v117, v247, vcc
	v_cndmask_b32_e32 v248, v118, v248, vcc
	v_cndmask_b32_e32 v249, v119, v249, vcc
	v_cndmask_b32_e32 v250, v250, v96, vcc
	v_cndmask_b32_e32 v251, v251, v97, vcc
	v_cndmask_b32_e32 v252, v252, v98, vcc
	v_cndmask_b32_e32 v253, v253, v99, vcc
	ds_bpermute_b32 v246, v240, v246
	ds_bpermute_b32 v247, v240, v247
	ds_bpermute_b32 v248, v240, v248
	ds_bpermute_b32 v249, v240, v249
	ds_bpermute_b32 v250, v240, v250
	ds_bpermute_b32 v251, v240, v251
	ds_bpermute_b32 v252, v240, v252
	ds_bpermute_b32 v253, v240, v253
	v_mov_b32_e32 v116, 0
	v_mov_b32_e32 v117, 0
	v_mov_b32_e32 v118, 0
	v_mov_b32_e32 v119, 0
	v_mov_b32_e32 v108, 0
	v_mov_b32_e32 v109, 0
	v_mov_b32_e32 v110, 0
	v_mov_b32_e32 v111, 0
	v_mov_b32_e32 v96, 0
	v_mov_b32_e32 v97, 0
	v_mov_b32_e32 v98, 0
	v_mov_b32_e32 v99, 0
	v_mov_b32_e32 v88, 0
	v_mov_b32_e32 v89, 0
	v_mov_b32_e32 v90, 0
	v_mov_b32_e32 v91, 0
	v_lshl_add_u64 v[238:239], v[140:141], 0, v[242:243]
	s_waitcnt lgkmcnt(4)
	global_store_dwordx4 v[140:141], v[246:249], off
	s_waitcnt lgkmcnt(0)
; __device__ __forceinline__ u32x4 pack8_bf16(f32x4 a, f32x4 b) { u32x4 w; w.x = cvt_pk_bf16(a[0], a[1]); w.y = cvt_pk_bf16(a[2], a[3]); w.z = cvt_pk_bf16(b[0], b[1]); w.w = cvt_pk_bf16(b[2], b[3]); return w; }
; #define ACT(t) (KBASE(t) <= qlo + QBLK - 1 && KBASE(t) + KVBLK - 1 >= qlo - W + 1)
;     __device__ __forceinline__ void operator()(const f32x4 (&acc)[2][2][4][2], const Unit& u, int wr, int wc, int fr, int fq) const {
;     ...
;             for (int m = 0; m < 4; ++m) { bf16_t* rowp = base + (size_t)(row0 + ai * HALF + m * 16) * ldc + col0;
; #pragma unroll
;                 for (int bj = 0; bj < 2; ++bj) { f32x4 v0 = acc[ai][bj][m][0], v1 = acc[ai][bj][m][1];
;                     if (ACT == 1) {
; #pragma unroll
;                         for (int j = 0; j < 4; ++j) { float a = fmaxf(v0[j], 0.f), b = fmaxf(v1[j], 0.f); v0[j] = a * a; v1[j] = b * b; } }
;                     *(u32x4*)(rowp + bj * HALF) = pack8_bf16(v0, v1); } }
	global_store_dwordx4 v[238:239], v[250:253], off
	v_lshl_add_u64 v[140:141], v[140:141], 0, s[34:35]
	v_cvt_pk_bf16_f32 v100, v100, v101
	v_cvt_pk_bf16_f32 v101, v102, v103
	v_cvt_pk_bf16_f32 v102, v92, v93
	v_cvt_pk_bf16_f32 v103, v94, v95
	v_cvt_pk_bf16_f32 v80, v80, v81
	v_cvt_pk_bf16_f32 v81, v82, v83
	v_cvt_pk_bf16_f32 v82, v72, v73
	v_cvt_pk_bf16_f32 v83, v74, v75
	v_mov_b32_dpp v246, v80 row_ror:8 row_mask:0xf bank_mask:0xf
	v_mov_b32_dpp v247, v81 row_ror:8 row_mask:0xf bank_mask:0xf
	v_mov_b32_dpp v248, v82 row_ror:8 row_mask:0xf bank_mask:0xf
	v_mov_b32_dpp v249, v83 row_ror:8 row_mask:0xf bank_mask:0xf
	v_mov_b32_dpp v250, v100 row_ror:8 row_mask:0xf bank_mask:0xf
	v_mov_b32_dpp v251, v101 row_ror:8 row_mask:0xf bank_mask:0xf
	v_mov_b32_dpp v252, v102 row_ror:8 row_mask:0xf bank_mask:0xf
	v_mov_b32_dpp v253, v103 row_ror:8 row_mask:0xf bank_mask:0xf
	v_cndmask_b32_e32 v246, v100, v246, vcc
	v_cndmask_b32_e32 v247, v101, v247, vcc
	v_cndmask_b32_e32 v248, v102, v248, vcc
	v_cndmask_b32_e32 v249, v103, v249, vcc
	v_cndmask_b32_e32 v250, v250, v80, vcc
	v_cndmask_b32_e32 v251, v251, v81, vcc
	v_cndmask_b32_e32 v252, v252, v82, vcc
	v_cndmask_b32_e32 v253, v253, v83, vcc
	ds_bpermute_b32 v246, v240, v246
	ds_bpermute_b32 v247, v240, v247
	ds_bpermute_b32 v248, v240, v248
	ds_bpermute_b32 v249, v240, v249
	ds_bpermute_b32 v250, v240, v250
	ds_bpermute_b32 v251, v240, v251
	ds_bpermute_b32 v252, v240, v252
	ds_bpermute_b32 v253, v240, v253
	v_mov_b32_e32 v100, 0
	v_mov_b32_e32 v101, 0
	v_mov_b32_e32 v102, 0
	v_mov_b32_e32 v103, 0
	v_mov_b32_e32 v92, 0
	v_mov_b32_e32 v93, 0
	v_mov_b32_e32 v94, 0
	v_mov_b32_e32 v95, 0
	v_mov_b32_e32 v80, 0
	v_mov_b32_e32 v81, 0
	v_mov_b32_e32 v82, 0
	v_mov_b32_e32 v83, 0
	v_mov_b32_e32 v72, 0
	v_mov_b32_e32 v73, 0
	v_mov_b32_e32 v74, 0
	v_mov_b32_e32 v75, 0
	v_lshl_add_u64 v[238:239], v[140:141], 0, v[242:243]
	s_waitcnt lgkmcnt(4)
	global_store_dwordx4 v[140:141], v[246:249], off
	s_waitcnt lgkmcnt(0)
	global_store_dwordx4 v[238:239], v[250:253], off
	v_lshl_add_u64 v[140:141], v[140:141], 0, s[34:35]
	v_cvt_pk_bf16_f32 v84, v84, v85
	v_cvt_pk_bf16_f32 v85, v86, v87
	v_cvt_pk_bf16_f32 v86, v76, v77
	v_cvt_pk_bf16_f32 v87, v78, v79
	v_cvt_pk_bf16_f32 v68, v68, v69
	v_cvt_pk_bf16_f32 v69, v70, v71
	v_cvt_pk_bf16_f32 v70, v64, v65
	v_cvt_pk_bf16_f32 v71, v66, v67
	v_mov_b32_dpp v246, v68 row_ror:8 row_mask:0xf bank_mask:0xf
	v_mov_b32_dpp v247, v69 row_ror:8 row_mask:0xf bank_mask:0xf
	v_mov_b32_dpp v248, v70 row_ror:8 row_mask:0xf bank_mask:0xf
	v_mov_b32_dpp v249, v71 row_ror:8 row_mask:0xf bank_mask:0xf
	v_mov_b32_dpp v250, v84 row_ror:8 row_mask:0xf bank_mask:0xf
	v_mov_b32_dpp v251, v85 row_ror:8 row_mask:0xf bank_mask:0xf
	v_mov_b32_dpp v252, v86 row_ror:8 row_mask:0xf bank_mask:0xf
	v_mov_b32_dpp v253, v87 row_ror:8 row_mask:0xf bank_mask:0xf
	v_cndmask_b32_e32 v246, v84, v246, vcc
	v_cndmask_b32_e32 v247, v85, v247, vcc
	v_cndmask_b32_e32 v248, v86, v248, vcc
	v_cndmask_b32_e32 v249, v87, v249, vcc
	v_cndmask_b32_e32 v250, v250, v68, vcc
	v_cndmask_b32_e32 v251, v251, v69, vcc
	v_cndmask_b32_e32 v252, v252, v70, vcc
	v_cndmask_b32_e32 v253, v253, v71, vcc
	ds_bpermute_b32 v246, v240, v246
	ds_bpermute_b32 v247, v240, v247
	ds_bpermute_b32 v248, v240, v248
	ds_bpermute_b32 v249, v240, v249
	ds_bpermute_b32 v250, v240, v250
	ds_bpermute_b32 v251, v240, v251
	ds_bpermute_b32 v252, v240, v252
	ds_bpermute_b32 v253, v240, v253
	v_mov_b32_e32 v84, 0
	v_mov_b32_e32 v85, 0
	v_mov_b32_e32 v86, 0
	v_mov_b32_e32 v87, 0
	v_mov_b32_e32 v76, 0
	v_mov_b32_e32 v77, 0
	v_mov_b32_e32 v78, 0
	v_mov_b32_e32 v79, 0
	v_mov_b32_e32 v68, 0
	v_mov_b32_e32 v69, 0
	v_mov_b32_e32 v70, 0
	v_mov_b32_e32 v71, 0
	v_mov_b32_e32 v64, 0
	v_mov_b32_e32 v65, 0
	v_mov_b32_e32 v66, 0
	v_mov_b32_e32 v67, 0
	v_lshl_add_u64 v[238:239], v[140:141], 0, v[242:243]
	s_waitcnt lgkmcnt(4)
	global_store_dwordx4 v[140:141], v[246:249], off
	s_waitcnt lgkmcnt(0)
	global_store_dwordx4 v[238:239], v[250:253], off
	s_mov_b64 s[34:35], 0x50000
	v_lshl_add_u64 v[140:141], v[140:141], 0, s[34:35]
	s_mov_b64 s[34:35], 0x10000
	v_cvt_pk_bf16_f32 v60, v60, v61
	v_cvt_pk_bf16_f32 v61, v62, v63
	v_cvt_pk_bf16_f32 v62, v56, v57
	v_cvt_pk_bf16_f32 v63, v58, v59
	v_cvt_pk_bf16_f32 v48, v48, v49
	v_cvt_pk_bf16_f32 v49, v50, v51
	v_cvt_pk_bf16_f32 v50, v40, v41
	v_cvt_pk_bf16_f32 v51, v42, v43
	v_mov_b32_dpp v246, v48 row_ror:8 row_mask:0xf bank_mask:0xf
	v_mov_b32_dpp v247, v49 row_ror:8 row_mask:0xf bank_mask:0xf
	v_mov_b32_dpp v248, v50 row_ror:8 row_mask:0xf bank_mask:0xf
	v_mov_b32_dpp v249, v51 row_ror:8 row_mask:0xf bank_mask:0xf
	v_mov_b32_dpp v250, v60 row_ror:8 row_mask:0xf bank_mask:0xf
	v_mov_b32_dpp v251, v61 row_ror:8 row_mask:0xf bank_mask:0xf
	v_mov_b32_dpp v252, v62 row_ror:8 row_mask:0xf bank_mask:0xf
	v_mov_b32_dpp v253, v63 row_ror:8 row_mask:0xf bank_mask:0xf
	v_cndmask_b32_e32 v246, v60, v246, vcc
	v_cndmask_b32_e32 v247, v61, v247, vcc
	v_cndmask_b32_e32 v248, v62, v248, vcc
	v_cndmask_b32_e32 v249, v63, v249, vcc
	v_cndmask_b32_e32 v250, v250, v48, vcc
	v_cndmask_b32_e32 v251, v251, v49, vcc
	v_cndmask_b32_e32 v252, v252, v50, vcc
	v_cndmask_b32_e32 v253, v253, v51, vcc
	ds_bpermute_b32 v246, v240, v246
	ds_bpermute_b32 v247, v240, v247
	ds_bpermute_b32 v248, v240, v248
	ds_bpermute_b32 v249, v240, v249
	ds_bpermute_b32 v250, v240, v250
	ds_bpermute_b32 v251, v240, v251
	ds_bpermute_b32 v252, v240, v252
	ds_bpermute_b32 v253, v240, v253
	v_mov_b32_e32 v60, 0
	v_mov_b32_e32 v61, 0
	v_mov_b32_e32 v62, 0
	v_mov_b32_e32 v63, 0
	v_mov_b32_e32 v56, 0
	v_mov_b32_e32 v57, 0
	v_mov_b32_e32 v58, 0
	v_mov_b32_e32 v59, 0
	v_mov_b32_e32 v48, 0
	v_mov_b32_e32 v49, 0
	v_mov_b32_e32 v50, 0
	v_mov_b32_e32 v51, 0
	v_mov_b32_e32 v40, 0
	v_mov_b32_e32 v41, 0
	v_mov_b32_e32 v42, 0
	v_mov_b32_e32 v43, 0
	v_lshl_add_u64 v[238:239], v[140:141], 0, v[242:243]
	s_waitcnt lgkmcnt(4)
; __device__ __forceinline__ u32x4 pack8_bf16(f32x4 a, f32x4 b) { u32x4 w; w.x = cvt_pk_bf16(a[0], a[1]); w.y = cvt_pk_bf16(a[2], a[3]); w.z = cvt_pk_bf16(b[0], b[1]); w.w = cvt_pk_bf16(b[2], b[3]); return w; }
; #define PG8_BAR __builtin_amdgcn_s_barrier()
; #define ACT(t) (KBASE(t) <= qlo + QBLK - 1 && KBASE(t) + KVBLK - 1 >= qlo - W + 1)
;     __device__ __forceinline__ void operator()(const f32x4 (&acc)[2][2][4][2], const Unit& u, int wr, int wc, int fr, int fq) const {
;     ...
;             for (int m = 0; m < 4; ++m) { bf16_t* rowp = base + (size_t)(row0 + ai * HALF + m * 16) * ldc + col0;
; #pragma unroll
;                 for (int bj = 0; bj < 2; ++bj) { f32x4 v0 = acc[ai][bj][m][0], v1 = acc[ai][bj][m][1];
;                     if (ACT == 1) {
; #pragma unroll
;                         for (int j = 0; j < 4; ++j) { float a = fmaxf(v0[j], 0.f), b = fmaxf(v1[j], 0.f); v0[j] = a * a; v1[j] = b * b; } }
;                     *(u32x4*)(rowp + bj * HALF) = pack8_bf16(v0, v1); } }
; template <class Epi, class Sched, bool ALIGN_EPI = false, bool SP2 = false>
; __device__ __forceinline__ void gemm_phase(PG8_LAS unsigned char* lds, const Gemm g, const Sched& S, const Epi& E) {
;     ...
;         if (!has_next) break;
; #pragma unroll
;         for (int a = 0; a < 2; ++a)
; #pragma unroll
;             for (int b = 0; b < 2; ++b)
; #pragma unroll
;                 for (int m = 0; m < 4; ++m)
; #pragma unroll
;                     for (int n = 0; n < 2; ++n) acc[a][b][m][n] = (f32x4){0.f, 0.f, 0.f, 0.f};
;         cur = nxt; cA = nA; cB = nB; ++ui;
;         if constexpr (ALIGN_EPI) { if (wr == 1) PG8_BAR; }
	global_store_dwordx4 v[140:141], v[246:249], off
	s_waitcnt lgkmcnt(0)
	global_store_dwordx4 v[238:239], v[250:253], off
	v_lshl_add_u64 v[140:141], v[140:141], 0, s[34:35]
	v_cvt_pk_bf16_f32 v52, v52, v53
	v_cvt_pk_bf16_f32 v53, v54, v55
	v_cvt_pk_bf16_f32 v54, v44, v45
	v_cvt_pk_bf16_f32 v55, v46, v47
	v_cvt_pk_bf16_f32 v32, v32, v33
	v_cvt_pk_bf16_f32 v33, v34, v35
	v_cvt_pk_bf16_f32 v34, v24, v25
	v_cvt_pk_bf16_f32 v35, v26, v27
	v_mov_b32_dpp v246, v32 row_ror:8 row_mask:0xf bank_mask:0xf
	v_mov_b32_dpp v247, v33 row_ror:8 row_mask:0xf bank_mask:0xf
	v_mov_b32_dpp v248, v34 row_ror:8 row_mask:0xf bank_mask:0xf
	v_mov_b32_dpp v249, v35 row_ror:8 row_mask:0xf bank_mask:0xf
	v_mov_b32_dpp v250, v52 row_ror:8 row_mask:0xf bank_mask:0xf
	v_mov_b32_dpp v251, v53 row_ror:8 row_mask:0xf bank_mask:0xf
	v_mov_b32_dpp v252, v54 row_ror:8 row_mask:0xf bank_mask:0xf
	v_mov_b32_dpp v253, v55 row_ror:8 row_mask:0xf bank_mask:0xf
	v_cndmask_b32_e32 v246, v52, v246, vcc
	v_cndmask_b32_e32 v247, v53, v247, vcc
	v_cndmask_b32_e32 v248, v54, v248, vcc
	v_cndmask_b32_e32 v249, v55, v249, vcc
	v_cndmask_b32_e32 v250, v250, v32, vcc
	v_cndmask_b32_e32 v251, v251, v33, vcc
	v_cndmask_b32_e32 v252, v252, v34, vcc
	v_cndmask_b32_e32 v253, v253, v35, vcc
	ds_bpermute_b32 v246, v240, v246
	ds_bpermute_b32 v247, v240, v247
	ds_bpermute_b32 v248, v240, v248
	ds_bpermute_b32 v249, v240, v249
	ds_bpermute_b32 v250, v240, v250
	ds_bpermute_b32 v251, v240, v251
	ds_bpermute_b32 v252, v240, v252
	ds_bpermute_b32 v253, v240, v253
	v_mov_b32_e32 v52, 0
	v_mov_b32_e32 v53, 0
	v_mov_b32_e32 v54, 0
	v_mov_b32_e32 v55, 0
	v_mov_b32_e32 v44, 0
	v_mov_b32_e32 v45, 0
	v_mov_b32_e32 v46, 0
	v_mov_b32_e32 v47, 0
	v_mov_b32_e32 v32, 0
	v_mov_b32_e32 v33, 0
	v_mov_b32_e32 v34, 0
	v_mov_b32_e32 v35, 0
	v_mov_b32_e32 v24, 0
	v_mov_b32_e32 v25, 0
	v_mov_b32_e32 v26, 0
	v_mov_b32_e32 v27, 0
	v_lshl_add_u64 v[238:239], v[140:141], 0, v[242:243]
	s_waitcnt lgkmcnt(4)
	global_store_dwordx4 v[140:141], v[246:249], off
	s_waitcnt lgkmcnt(0)
	global_store_dwordx4 v[238:239], v[250:253], off
	v_lshl_add_u64 v[140:141], v[140:141], 0, s[34:35]
	v_cvt_pk_bf16_f32 v36, v36, v37
	v_cvt_pk_bf16_f32 v37, v38, v39
	v_cvt_pk_bf16_f32 v38, v28, v29
	v_cvt_pk_bf16_f32 v39, v30, v31
	v_cvt_pk_bf16_f32 v16, v16, v17
	v_cvt_pk_bf16_f32 v17, v18, v19
	v_cvt_pk_bf16_f32 v18, v8, v9
	v_cvt_pk_bf16_f32 v19, v10, v11
	v_mov_b32_dpp v246, v16 row_ror:8 row_mask:0xf bank_mask:0xf
	v_mov_b32_dpp v247, v17 row_ror:8 row_mask:0xf bank_mask:0xf
	v_mov_b32_dpp v248, v18 row_ror:8 row_mask:0xf bank_mask:0xf
	v_mov_b32_dpp v249, v19 row_ror:8 row_mask:0xf bank_mask:0xf
	v_mov_b32_dpp v250, v36 row_ror:8 row_mask:0xf bank_mask:0xf
	v_mov_b32_dpp v251, v37 row_ror:8 row_mask:0xf bank_mask:0xf
	v_mov_b32_dpp v252, v38 row_ror:8 row_mask:0xf bank_mask:0xf
	v_mov_b32_dpp v253, v39 row_ror:8 row_mask:0xf bank_mask:0xf
	v_cndmask_b32_e32 v246, v36, v246, vcc
	v_cndmask_b32_e32 v247, v37, v247, vcc
	v_cndmask_b32_e32 v248, v38, v248, vcc
	v_cndmask_b32_e32 v249, v39, v249, vcc
	v_cndmask_b32_e32 v250, v250, v16, vcc
	v_cndmask_b32_e32 v251, v251, v17, vcc
	v_cndmask_b32_e32 v252, v252, v18, vcc
	v_cndmask_b32_e32 v253, v253, v19, vcc
	ds_bpermute_b32 v246, v240, v246
	ds_bpermute_b32 v247, v240, v247
	ds_bpermute_b32 v248, v240, v248
	ds_bpermute_b32 v249, v240, v249
	ds_bpermute_b32 v250, v240, v250
	ds_bpermute_b32 v251, v240, v251
	ds_bpermute_b32 v252, v240, v252
	ds_bpermute_b32 v253, v240, v253
	v_mov_b32_e32 v36, 0
	v_mov_b32_e32 v37, 0
	v_mov_b32_e32 v38, 0
	v_mov_b32_e32 v39, 0
	v_mov_b32_e32 v28, 0
	v_mov_b32_e32 v29, 0
	v_mov_b32_e32 v30, 0
	v_mov_b32_e32 v31, 0
	v_mov_b32_e32 v16, 0
	v_mov_b32_e32 v17, 0
	v_mov_b32_e32 v18, 0
	v_mov_b32_e32 v19, 0
	v_mov_b32_e32 v8, 0
	v_mov_b32_e32 v9, 0
	v_mov_b32_e32 v10, 0
	v_mov_b32_e32 v11, 0
	v_lshl_add_u64 v[238:239], v[140:141], 0, v[242:243]
	s_waitcnt lgkmcnt(4)
	global_store_dwordx4 v[140:141], v[246:249], off
	s_waitcnt lgkmcnt(0)
	global_store_dwordx4 v[238:239], v[250:253], off
	v_lshl_add_u64 v[140:141], v[140:141], 0, s[34:35]
	v_cvt_pk_bf16_f32 v20, v20, v21
	v_cvt_pk_bf16_f32 v21, v22, v23
	v_cvt_pk_bf16_f32 v22, v12, v13
	v_cvt_pk_bf16_f32 v23, v14, v15
	v_cvt_pk_bf16_f32 v4, v4, v5
	v_cvt_pk_bf16_f32 v5, v6, v7
	v_cvt_pk_bf16_f32 v6, v0, v1
	v_cvt_pk_bf16_f32 v7, v2, v3
	v_mov_b32_dpp v246, v4 row_ror:8 row_mask:0xf bank_mask:0xf
	v_mov_b32_dpp v247, v5 row_ror:8 row_mask:0xf bank_mask:0xf
	v_mov_b32_dpp v248, v6 row_ror:8 row_mask:0xf bank_mask:0xf
	v_mov_b32_dpp v249, v7 row_ror:8 row_mask:0xf bank_mask:0xf
	v_mov_b32_dpp v250, v20 row_ror:8 row_mask:0xf bank_mask:0xf
	v_mov_b32_dpp v251, v21 row_ror:8 row_mask:0xf bank_mask:0xf
	v_mov_b32_dpp v252, v22 row_ror:8 row_mask:0xf bank_mask:0xf
	v_mov_b32_dpp v253, v23 row_ror:8 row_mask:0xf bank_mask:0xf
	v_cndmask_b32_e32 v246, v20, v246, vcc
	v_cndmask_b32_e32 v247, v21, v247, vcc
	v_cndmask_b32_e32 v248, v22, v248, vcc
	v_cndmask_b32_e32 v249, v23, v249, vcc
	v_cndmask_b32_e32 v250, v250, v4, vcc
	v_cndmask_b32_e32 v251, v251, v5, vcc
	v_cndmask_b32_e32 v252, v252, v6, vcc
	v_cndmask_b32_e32 v253, v253, v7, vcc
	ds_bpermute_b32 v246, v240, v246
	ds_bpermute_b32 v247, v240, v247
	ds_bpermute_b32 v248, v240, v248
	ds_bpermute_b32 v249, v240, v249
	ds_bpermute_b32 v250, v240, v250
	ds_bpermute_b32 v251, v240, v251
	ds_bpermute_b32 v252, v240, v252
	ds_bpermute_b32 v253, v240, v253
	v_mov_b32_e32 v20, 0
	v_mov_b32_e32 v21, 0
	v_mov_b32_e32 v22, 0
	v_mov_b32_e32 v23, 0
	v_mov_b32_e32 v12, 0
	v_mov_b32_e32 v13, 0
	v_mov_b32_e32 v14, 0
	v_mov_b32_e32 v15, 0
	v_mov_b32_e32 v4, 0
	v_mov_b32_e32 v5, 0
	v_mov_b32_e32 v6, 0
	v_mov_b32_e32 v7, 0
	v_mov_b32_e32 v0, 0
	v_mov_b32_e32 v1, 0
	v_mov_b32_e32 v2, 0
	v_mov_b32_e32 v3, 0
	v_lshl_add_u64 v[238:239], v[140:141], 0, v[242:243]
	s_waitcnt lgkmcnt(4)
	global_store_dwordx4 v[140:141], v[246:249], off
	s_waitcnt lgkmcnt(0)
	global_store_dwordx4 v[238:239], v[250:253], off
	s_andn2_b64 vcc, exec, s[40:41]
	s_mov_b64 s[34:35], -1
	s_cbranch_vccnz .LBB0_424
	s_andn2_b64 vcc, exec, s[8:9]
	s_cbranch_vccnz .LBB0_423
	s_barrier
	s_branch .LBB0_423

; #define PG8_STAGE(bufoff, gbase, voff) do { _Pragma("unroll") for (int _i = 0; _i < 2; ++_i) \
;         __builtin_amdgcn_global_load_lds((const unsigned*)((const char*)(gbase) + (voff)[_i]), (PG8_LAS unsigned*)(lds + (bufoff) + ldsw + _i * 8192), 16, 0, 0); } while (0)
; #define PG8_LDA(dst, b, h) do { _Pragma("unroll") for (int m = 0; m < 4; ++m) _Pragma("unroll") for (int k = 0; k < 2; ++k) dst[m][k] = *(const PG8_LAS bf16x8*)(lds + PG8_SA(b, h) + aoff + m * 2048 + k * 1024); } while (0)
; #define PG8_LDB(dst, b, h) do { _Pragma("unroll") for (int n = 0; n < 2; ++n) _Pragma("unroll") for (int k = 0; k < 2; ++k) dst[n][k] = *(const PG8_LAS bf16x8*)(lds + PG8_SB(b, h) + boff + n * 2048 + k * 1024); } while (0)
; #define PG8_SCHED __builtin_amdgcn_sched_barrier(0)
; template <class Epi, class Sched, bool ALIGN_EPI = false, bool SP2 = false>
; __device__ __forceinline__ void gemm_phase(PG8_LAS unsigned char* lds, const Gemm g, const Sched& S, const Epi& E) {
;     ...
;         const bool has_next = S.next(ui + 1, nxt);
;         const char* nA = has_next ? (const char*)g.A + (size_t)nxt.pm * tstep : cA; const char* nB = has_next ? (const char*)g.Bt + (size_t)nxt.pn * tstep : cB;
; #pragma nounroll
;         for (int t = 0; t < nt; t += 2) {
;             const bool last = (t == nt - 2);
;             const char* a1 = cA + (size_t)(t + 1) * kstep;
;             const char* a2 = last ? nA : cA + (size_t)(t + 2) * kstep; const char* b2 = last ? nB : cB + (size_t)(t + 2) * kstep;
;             const char* a3 = a2 + kstep; const char* b3 = b2 + kstep;
;             if (last && has_next) S.a_ready(nxt);
;             if constexpr (SP2) {
;             PG8_LDB(B0, 0, 0); PG8_LDB(B1, 0, 1); PG8_SCHED; PG8_LDA(At, 0, 0); PG8_STAGE(PG8_SA(1, 1), a1 + hstep, voffA);
;     ...
; #pragma unroll
;         for (int a = 0; a < 2; ++a)
; #pragma unroll
;             for (int b = 0; b < 2; ++b)
; #pragma unroll
;                 for (int m = 0; m < 4; ++m)
; #pragma unroll
;                     for (int n = 0; n < 2; ++n) acc[a][b][m][n] = (f32x4){0.f, 0.f, 0.f, 0.f};
.LBB0_454:
	s_ashr_i32 s19, s18, 31
	s_lshl_b64 s[34:35], s[18:19], 20
	s_add_u32 s42, s58, s34
	s_addc_u32 s43, s59, s35
	s_and_b64 s[34:35], s[40:41], exec
	s_cselect_b32 s19, s43, s67
	s_cselect_b32 s33, s42, s66
	s_ashr_i32 s31, s30, 31
	s_lshl_b64 s[34:35], s[30:31], 20
	s_add_u32 s44, s38, s34
	s_addc_u32 s45, s39, s35
	s_and_b64 s[34:35], s[40:41], exec
	s_cselect_b32 s31, s45, s69
	s_cselect_b32 s34, s44, s68
	s_add_u32 s66, s66, 0x80080
	s_addc_u32 s67, s67, 0
	s_add_u32 s35, s68, 0x100
	v_mov_b32_e32 v0, 0
	s_addc_u32 s37, s69, 0
	s_mov_b32 s47, -2
	s_cmp_lt_u32 s29, 2
	s_cbranch_scc0 .Lzs6
	v_mov_b32_e32 v1, v0
	v_mov_b32_e32 v2, v0
	v_mov_b32_e32 v3, v0
	v_mov_b32_e32 v4, v0
	v_mov_b32_e32 v5, v0
	v_mov_b32_e32 v6, v0
	v_mov_b32_e32 v7, v0
	v_mov_b32_e32 v16, v0
	v_mov_b32_e32 v17, v0
	v_mov_b32_e32 v18, v0
	v_mov_b32_e32 v19, v0
	v_mov_b32_e32 v20, v0
	v_mov_b32_e32 v21, v0
	v_mov_b32_e32 v22, v0
	v_mov_b32_e32 v23, v0
	v_mov_b32_e32 v32, v0
	v_mov_b32_e32 v33, v0
	v_mov_b32_e32 v34, v0
	v_mov_b32_e32 v35, v0
	v_mov_b32_e32 v36, v0
	v_mov_b32_e32 v37, v0
	v_mov_b32_e32 v38, v0
	v_mov_b32_e32 v39, v0
	v_mov_b32_e32 v48, v0
	v_mov_b32_e32 v49, v0
	v_mov_b32_e32 v50, v0
	v_mov_b32_e32 v51, v0
	v_mov_b32_e32 v52, v0
	v_mov_b32_e32 v53, v0
	v_mov_b32_e32 v54, v0
	v_mov_b32_e32 v55, v0
	v_mov_b32_e32 v8, v0
	v_mov_b32_e32 v9, v0
	v_mov_b32_e32 v10, v0
	v_mov_b32_e32 v11, v0
	v_mov_b32_e32 v12, v0
	v_mov_b32_e32 v13, v0
	v_mov_b32_e32 v14, v0
	v_mov_b32_e32 v15, v0
	v_mov_b32_e32 v24, v0
	v_mov_b32_e32 v25, v0
	v_mov_b32_e32 v26, v0
	v_mov_b32_e32 v27, v0
	v_mov_b32_e32 v28, v0
	v_mov_b32_e32 v29, v0
	v_mov_b32_e32 v30, v0
	v_mov_b32_e32 v31, v0
	v_mov_b32_e32 v40, v0
	v_mov_b32_e32 v41, v0
	v_mov_b32_e32 v42, v0
	v_mov_b32_e32 v43, v0
	v_mov_b32_e32 v44, v0
	v_mov_b32_e32 v45, v0
	v_mov_b32_e32 v46, v0
	v_mov_b32_e32 v47, v0
	v_mov_b32_e32 v56, v0
	v_mov_b32_e32 v57, v0
	v_mov_b32_e32 v58, v0
	v_mov_b32_e32 v59, v0
	v_mov_b32_e32 v60, v0
	v_mov_b32_e32 v61, v0
	v_mov_b32_e32 v62, v0
	v_mov_b32_e32 v63, v0
	v_mov_b32_e32 v64, v0
	v_mov_b32_e32 v65, v0
	v_mov_b32_e32 v66, v0
	v_mov_b32_e32 v67, v0
	v_mov_b32_e32 v68, v0
	v_mov_b32_e32 v69, v0
	v_mov_b32_e32 v70, v0
	v_mov_b32_e32 v71, v0
	v_mov_b32_e32 v80, v0
	v_mov_b32_e32 v81, v0
	v_mov_b32_e32 v82, v0
	v_mov_b32_e32 v83, v0
	v_mov_b32_e32 v84, v0
	v_mov_b32_e32 v85, v0
	v_mov_b32_e32 v86, v0
	v_mov_b32_e32 v87, v0
	v_mov_b32_e32 v96, v0
	v_mov_b32_e32 v97, v0
	v_mov_b32_e32 v98, v0
	v_mov_b32_e32 v99, v0
	v_mov_b32_e32 v100, v0
	v_mov_b32_e32 v101, v0
	v_mov_b32_e32 v102, v0
	v_mov_b32_e32 v103, v0
	v_mov_b32_e32 v112, v0
	v_mov_b32_e32 v113, v0
	v_mov_b32_e32 v114, v0
	v_mov_b32_e32 v115, v0
	v_mov_b32_e32 v116, v0
	v_mov_b32_e32 v117, v0
	v_mov_b32_e32 v118, v0
	v_mov_b32_e32 v119, v0
	v_mov_b32_e32 v72, v0
	v_mov_b32_e32 v73, v0
	v_mov_b32_e32 v74, v0
	v_mov_b32_e32 v75, v0
	v_mov_b32_e32 v76, v0
	v_mov_b32_e32 v77, v0
	v_mov_b32_e32 v78, v0
	v_mov_b32_e32 v79, v0
	v_mov_b32_e32 v88, v0
	v_mov_b32_e32 v89, v0
	v_mov_b32_e32 v90, v0
	v_mov_b32_e32 v91, v0
	v_mov_b32_e32 v92, v0
	v_mov_b32_e32 v93, v0
	v_mov_b32_e32 v94, v0
	v_mov_b32_e32 v95, v0
	v_mov_b32_e32 v104, v0
	v_mov_b32_e32 v105, v0
	v_mov_b32_e32 v106, v0
	v_mov_b32_e32 v107, v0
	v_mov_b32_e32 v108, v0
	v_mov_b32_e32 v109, v0
	v_mov_b32_e32 v110, v0
	v_mov_b32_e32 v111, v0
	v_mov_b32_e32 v120, v0
	v_mov_b32_e32 v121, v0
	v_mov_b32_e32 v122, v0
	v_mov_b32_e32 v123, v0
	v_mov_b32_e32 v124, v0
	v_mov_b32_e32 v125, v0
	v_mov_b32_e32 v126, v0
	v_mov_b32_e32 v127, v0
.Lzs6:
.LBB0_455:
	s_add_u32 s49, s66, 0xfff80080
	s_addc_u32 s52, s67, -1
	s_add_i32 s53, 0, 0x10000
	s_cmp_eq_u32 s47, 28
	s_cselect_b32 s71, s19, s52
	s_cselect_b32 s70, s33, s49
	v_add_u32_e32 v140, s53, v143
	s_cselect_b32 s69, s31, s37
	s_cselect_b32 s68, s34, s35
	s_add_i32 s49, 0, 0x14000
	ds_read_b128 v[146:149], v140
	ds_read_b128 v[150:153], v140 offset:1024
	ds_read_b128 v[154:157], v140 offset:2048
	ds_read_b128 v[158:161], v140 offset:3072
	v_add_u32_e32 v140, s49, v143
	ds_read_b128 v[162:165], v140
	ds_read_b128 v[166:169], v140 offset:1024
	ds_read_b128 v[170:173], v140 offset:2048
	ds_read_b128 v[174:177], v140 offset:3072
	v_lshl_add_u64 v[140:141], s[66:67], 0, v[136:137]
	s_add_i32 m0, s7, 0xc000
	ds_read_b128 v[178:181], v145
	ds_read_b128 v[182:185], v145 offset:1024
	ds_read_b128 v[186:189], v145 offset:2048
	ds_read_b128 v[190:193], v145 offset:3072
	ds_read_b128 v[220:223], v145 offset:4096
	ds_read_b128 v[224:227], v145 offset:5120
	ds_read_b128 v[228:231], v145 offset:6144
	ds_read_b128 v[232:235], v145 offset:7168
	global_load_lds_dwordx4 v[140:141], off
	v_lshl_add_u64 v[140:141], s[66:67], 0, v[138:139]
	s_add_i32 m0, s7, 0xe000
	s_nop 0
	global_load_lds_dwordx4 v[140:141], off
	s_cmp_lt_i32 s47, 0
	s_cbranch_scc0 .Lrx6_0_norm
	s_cmp_lt_u32 s29, 2
	s_cbranch_scc1 .Lrx6_0_norm
	s_waitcnt vmcnt(24)
	s_branch .Lrx6_0_join

; __device__ __forceinline__ u32x4 pack8_bf16(f32x4 a, f32x4 b) { u32x4 w; w.x = cvt_pk_bf16(a[0], a[1]); w.y = cvt_pk_bf16(a[2], a[3]); w.z = cvt_pk_bf16(b[0], b[1]); w.w = cvt_pk_bf16(b[2], b[3]); return w; }
; #define ACT(t) (KBASE(t) <= qlo + QBLK - 1 && KBASE(t) + KVBLK - 1 >= qlo - W + 1)
;     __device__ __forceinline__ void operator()(const f32x4 (&acc)[2][2][4][2], const Unit& u, int wr, int wc, int fr, int fq) const {
;         const int g = u.pn / nNper, pnl = u.pn - g * nNper, pml = u.pm & 63;
;         bf16_t* base = O + (size_t)g * gstride;
;         const int row0 = pml * BM + wr * 64 + fr, col0 = pnl * BM + wc * 32 + 8 * fq;
; #pragma unroll
;         for (int ai = 0; ai < 2; ++ai)
; #pragma unroll
;             for (int m = 0; m < 4; ++m) { bf16_t* rowp = base + (size_t)(row0 + ai * HALF + m * 16) * ldc + col0;
; #pragma unroll
;                 for (int bj = 0; bj < 2; ++bj) { f32x4 v0 = acc[ai][bj][m][0], v1 = acc[ai][bj][m][1];
;                     if (ACT == 1) {
; #pragma unroll
;                         for (int j = 0; j < 4; ++j) { float a = fmaxf(v0[j], 0.f), b = fmaxf(v1[j], 0.f); v0[j] = a * a; v1[j] = b * b; } }
;                     *(u32x4*)(rowp + bj * HALF) = pack8_bf16(v0, v1); } }
.LBB0_458:
	s_ashr_i32 s19, s62, 31
	s_lshr_b32 s19, s19, 27
	s_add_i32 s19, s62, s19
	s_and_b32 s19, s19, 0xffffe0
	s_lshl_b32 s31, s46, 8
	s_sub_i32 s19, s62, s19
	s_and_b32 s31, s31, 0x3f00
	v_add_u32_e32 v146, s31, v142
	v_lshl_or_b32 v140, s19, 8, v144
	v_ashrrev_i32_e32 v141, 31, v140
	v_ashrrev_i32_e32 v147, 31, v146
	v_lshl_add_u64 v[148:149], v[140:141], 1, s[60:61]
	v_lshlrev_b64 v[140:141], 14, v[146:147]
	v_lshl_add_u64 v[140:141], v[148:149], 0, v[140:141]
	s_mov_b64 s[34:35], 0x40000
	v_mov_b32_e32 v242, 0x20000
	v_mov_b32_e32 v243, 0
	v_and_b32_e32 v238, 8, v208
	v_cmp_ne_u32_e32 vcc, 0, v238
	v_and_b32_e32 v240, 63, v208
	v_lshrrev_b32_e32 v241, 3, v240
	v_and_b32_e32 v244, 3, v240
	v_lshl_add_u32 v241, v244, 4, v241
	v_and_b32_e32 v244, 4, v240
	v_lshl_add_u32 v241, v244, 1, v241
	v_lshlrev_b32_e32 v240, 2, v241
	v_max_f32_e32 v124, 0, v124
	v_max_f32_e32 v125, 0, v125
	v_max_f32_e32 v126, 0, v126
	v_max_f32_e32 v127, 0, v127
	v_max_f32_e32 v120, 0, v120
	v_max_f32_e32 v121, 0, v121
	v_max_f32_e32 v122, 0, v122
	v_max_f32_e32 v123, 0, v123
	v_max_f32_e32 v116, 0, v116
	v_max_f32_e32 v117, 0, v117
	v_max_f32_e32 v118, 0, v118
	v_max_f32_e32 v119, 0, v119
	v_max_f32_e32 v112, 0, v112
	v_max_f32_e32 v113, 0, v113
	v_max_f32_e32 v114, 0, v114
	v_max_f32_e32 v115, 0, v115
	v_mul_f32_e32 v124, v124, v124
	v_mul_f32_e32 v125, v125, v125
	v_mul_f32_e32 v126, v126, v126
	v_mul_f32_e32 v127, v127, v127
	v_mul_f32_e32 v120, v120, v120
	v_mul_f32_e32 v121, v121, v121
	v_mul_f32_e32 v122, v122, v122
	v_mul_f32_e32 v123, v123, v123
	v_mul_f32_e32 v116, v116, v116
	v_mul_f32_e32 v117, v117, v117
	v_mul_f32_e32 v118, v118, v118
	v_mul_f32_e32 v119, v119, v119
	v_mul_f32_e32 v112, v112, v112
	v_mul_f32_e32 v113, v113, v113
	v_mul_f32_e32 v114, v114, v114
	v_mul_f32_e32 v115, v115, v115
	v_cvt_pk_bf16_f32 v124, v124, v125
	v_cvt_pk_bf16_f32 v125, v126, v127
	v_cvt_pk_bf16_f32 v126, v120, v121
	v_cvt_pk_bf16_f32 v127, v122, v123
	v_cvt_pk_bf16_f32 v116, v116, v117
	v_cvt_pk_bf16_f32 v117, v118, v119
	v_cvt_pk_bf16_f32 v118, v112, v113
	v_cvt_pk_bf16_f32 v119, v114, v115
	v_mov_b32_dpp v246, v116 row_ror:8 row_mask:0xf bank_mask:0xf
	v_mov_b32_dpp v247, v117 row_ror:8 row_mask:0xf bank_mask:0xf
	v_mov_b32_dpp v248, v118 row_ror:8 row_mask:0xf bank_mask:0xf
	v_mov_b32_dpp v249, v119 row_ror:8 row_mask:0xf bank_mask:0xf
	v_mov_b32_dpp v250, v124 row_ror:8 row_mask:0xf bank_mask:0xf
	v_mov_b32_dpp v251, v125 row_ror:8 row_mask:0xf bank_mask:0xf
	v_mov_b32_dpp v252, v126 row_ror:8 row_mask:0xf bank_mask:0xf
	v_mov_b32_dpp v253, v127 row_ror:8 row_mask:0xf bank_mask:0xf
	v_cndmask_b32_e32 v246, v124, v246, vcc
	v_cndmask_b32_e32 v247, v125, v247, vcc
	v_cndmask_b32_e32 v248, v126, v248, vcc
	v_cndmask_b32_e32 v249, v127, v249, vcc
	v_cndmask_b32_e32 v250, v250, v116, vcc
	v_cndmask_b32_e32 v251, v251, v117, vcc
	v_cndmask_b32_e32 v252, v252, v118, vcc
	v_cndmask_b32_e32 v253, v253, v119, vcc
	ds_bpermute_b32 v246, v240, v246
	ds_bpermute_b32 v247, v240, v247
	ds_bpermute_b32 v248, v240, v248
	ds_bpermute_b32 v249, v240, v249
	ds_bpermute_b32 v250, v240, v250
	ds_bpermute_b32 v251, v240, v251
	ds_bpermute_b32 v252, v240, v252
	ds_bpermute_b32 v253, v240, v253
	v_mov_b32_e32 v124, 0
	v_mov_b32_e32 v125, 0
	v_mov_b32_e32 v126, 0
	v_mov_b32_e32 v127, 0
	v_mov_b32_e32 v120, 0
	v_mov_b32_e32 v121, 0
	v_mov_b32_e32 v122, 0
	v_mov_b32_e32 v123, 0
	v_mov_b32_e32 v116, 0
	v_mov_b32_e32 v117, 0
	v_mov_b32_e32 v118, 0
	v_mov_b32_e32 v119, 0
	v_mov_b32_e32 v112, 0
	v_mov_b32_e32 v113, 0
	v_mov_b32_e32 v114, 0
	v_mov_b32_e32 v115, 0
	v_lshl_add_u64 v[238:239], v[140:141], 0, v[242:243]
	s_waitcnt lgkmcnt(4)
	global_store_dwordx4 v[140:141], v[246:249], off
	s_waitcnt lgkmcnt(0)
	global_store_dwordx4 v[238:239], v[250:253], off
	v_lshl_add_u64 v[140:141], v[140:141], 0, s[34:35]
	v_max_f32_e32 v108, 0, v108
	v_max_f32_e32 v109, 0, v109
	v_max_f32_e32 v110, 0, v110
	v_max_f32_e32 v111, 0, v111
	v_max_f32_e32 v104, 0, v104
	v_max_f32_e32 v105, 0, v105
	v_max_f32_e32 v106, 0, v106
	v_max_f32_e32 v107, 0, v107
	v_max_f32_e32 v100, 0, v100
	v_max_f32_e32 v101, 0, v101
	v_max_f32_e32 v102, 0, v102
	v_max_f32_e32 v103, 0, v103
	v_max_f32_e32 v96, 0, v96
	v_max_f32_e32 v97, 0, v97
	v_max_f32_e32 v98, 0, v98
	v_max_f32_e32 v99, 0, v99
	v_mul_f32_e32 v108, v108, v108
	v_mul_f32_e32 v109, v109, v109
	v_mul_f32_e32 v110, v110, v110
	v_mul_f32_e32 v111, v111, v111
	v_mul_f32_e32 v104, v104, v104
	v_mul_f32_e32 v105, v105, v105
	v_mul_f32_e32 v106, v106, v106
	v_mul_f32_e32 v107, v107, v107
	v_mul_f32_e32 v100, v100, v100
	v_mul_f32_e32 v101, v101, v101
	v_mul_f32_e32 v102, v102, v102
	v_mul_f32_e32 v103, v103, v103
	v_mul_f32_e32 v96, v96, v96
	v_mul_f32_e32 v97, v97, v97
	v_mul_f32_e32 v98, v98, v98
	v_mul_f32_e32 v99, v99, v99
	v_cvt_pk_bf16_f32 v108, v108, v109
	v_cvt_pk_bf16_f32 v109, v110, v111
	v_cvt_pk_bf16_f32 v110, v104, v105
	v_cvt_pk_bf16_f32 v111, v106, v107
	v_cvt_pk_bf16_f32 v100, v100, v101
	v_cvt_pk_bf16_f32 v101, v102, v103
	v_cvt_pk_bf16_f32 v102, v96, v97
	v_cvt_pk_bf16_f32 v103, v98, v99
	v_mov_b32_dpp v246, v100 row_ror:8 row_mask:0xf bank_mask:0xf
	v_mov_b32_dpp v247, v101 row_ror:8 row_mask:0xf bank_mask:0xf
	v_mov_b32_dpp v248, v102 row_ror:8 row_mask:0xf bank_mask:0xf
	v_mov_b32_dpp v249, v103 row_ror:8 row_mask:0xf bank_mask:0xf
	v_mov_b32_dpp v250, v108 row_ror:8 row_mask:0xf bank_mask:0xf
	v_mov_b32_dpp v251, v109 row_ror:8 row_mask:0xf bank_mask:0xf
	v_mov_b32_dpp v252, v110 row_ror:8 row_mask:0xf bank_mask:0xf
	v_mov_b32_dpp v253, v111 row_ror:8 row_mask:0xf bank_mask:0xf
	v_cndmask_b32_e32 v246, v108, v246, vcc
	v_cndmask_b32_e32 v247, v109, v247, vcc
	v_cndmask_b32_e32 v248, v110, v248, vcc
	v_cndmask_b32_e32 v249, v111, v249, vcc
	v_cndmask_b32_e32 v250, v250, v100, vcc
	v_cndmask_b32_e32 v251, v251, v101, vcc
	v_cndmask_b32_e32 v252, v252, v102, vcc
	v_cndmask_b32_e32 v253, v253, v103, vcc
	ds_bpermute_b32 v246, v240, v246
	ds_bpermute_b32 v247, v240, v247
	ds_bpermute_b32 v248, v240, v248
	ds_bpermute_b32 v249, v240, v249
	ds_bpermute_b32 v250, v240, v250
	ds_bpermute_b32 v251, v240, v251
	ds_bpermute_b32 v252, v240, v252
	ds_bpermute_b32 v253, v240, v253
	v_mov_b32_e32 v108, 0
	v_mov_b32_e32 v109, 0
	v_mov_b32_e32 v110, 0
	v_mov_b32_e32 v111, 0
	v_mov_b32_e32 v104, 0
	v_mov_b32_e32 v105, 0
	v_mov_b32_e32 v106, 0
	v_mov_b32_e32 v107, 0
	v_mov_b32_e32 v100, 0
	v_mov_b32_e32 v101, 0
	v_mov_b32_e32 v102, 0
	v_mov_b32_e32 v103, 0
	v_mov_b32_e32 v96, 0
	v_mov_b32_e32 v97, 0
	v_mov_b32_e32 v98, 0
	v_mov_b32_e32 v99, 0
	v_lshl_add_u64 v[238:239], v[140:141], 0, v[242:243]
	s_waitcnt lgkmcnt(4)
; __device__ __forceinline__ u32x4 pack8_bf16(f32x4 a, f32x4 b) { u32x4 w; w.x = cvt_pk_bf16(a[0], a[1]); w.y = cvt_pk_bf16(a[2], a[3]); w.z = cvt_pk_bf16(b[0], b[1]); w.w = cvt_pk_bf16(b[2], b[3]); return w; }
; #define ACT(t) (KBASE(t) <= qlo + QBLK - 1 && KBASE(t) + KVBLK - 1 >= qlo - W + 1)
;     __device__ __forceinline__ void operator()(const f32x4 (&acc)[2][2][4][2], const Unit& u, int wr, int wc, int fr, int fq) const {
;     ...
;             for (int m = 0; m < 4; ++m) { bf16_t* rowp = base + (size_t)(row0 + ai * HALF + m * 16) * ldc + col0;
; #pragma unroll
;                 for (int bj = 0; bj < 2; ++bj) { f32x4 v0 = acc[ai][bj][m][0], v1 = acc[ai][bj][m][1];
;                     if (ACT == 1) {
; #pragma unroll
;                         for (int j = 0; j < 4; ++j) { float a = fmaxf(v0[j], 0.f), b = fmaxf(v1[j], 0.f); v0[j] = a * a; v1[j] = b * b; } }
;                     *(u32x4*)(rowp + bj * HALF) = pack8_bf16(v0, v1); } }
	global_store_dwordx4 v[140:141], v[246:249], off
	s_waitcnt lgkmcnt(0)
	global_store_dwordx4 v[238:239], v[250:253], off
	v_lshl_add_u64 v[140:141], v[140:141], 0, s[34:35]
	v_max_f32_e32 v92, 0, v92
	v_max_f32_e32 v93, 0, v93
	v_max_f32_e32 v94, 0, v94
	v_max_f32_e32 v95, 0, v95
	v_max_f32_e32 v88, 0, v88
	v_max_f32_e32 v89, 0, v89
	v_max_f32_e32 v90, 0, v90
	v_max_f32_e32 v91, 0, v91
	v_max_f32_e32 v84, 0, v84
	v_max_f32_e32 v85, 0, v85
	v_max_f32_e32 v86, 0, v86
	v_max_f32_e32 v87, 0, v87
	v_max_f32_e32 v80, 0, v80
	v_max_f32_e32 v81, 0, v81
	v_max_f32_e32 v82, 0, v82
	v_max_f32_e32 v83, 0, v83
	v_mul_f32_e32 v92, v92, v92
	v_mul_f32_e32 v93, v93, v93
	v_mul_f32_e32 v94, v94, v94
	v_mul_f32_e32 v95, v95, v95
	v_mul_f32_e32 v88, v88, v88
	v_mul_f32_e32 v89, v89, v89
	v_mul_f32_e32 v90, v90, v90
	v_mul_f32_e32 v91, v91, v91
	v_mul_f32_e32 v84, v84, v84
	v_mul_f32_e32 v85, v85, v85
	v_mul_f32_e32 v86, v86, v86
	v_mul_f32_e32 v87, v87, v87
	v_mul_f32_e32 v80, v80, v80
	v_mul_f32_e32 v81, v81, v81
	v_mul_f32_e32 v82, v82, v82
	v_mul_f32_e32 v83, v83, v83
	v_cvt_pk_bf16_f32 v92, v92, v93
	v_cvt_pk_bf16_f32 v93, v94, v95
	v_cvt_pk_bf16_f32 v94, v88, v89
	v_cvt_pk_bf16_f32 v95, v90, v91
	v_cvt_pk_bf16_f32 v84, v84, v85
	v_cvt_pk_bf16_f32 v85, v86, v87
	v_cvt_pk_bf16_f32 v86, v80, v81
	v_cvt_pk_bf16_f32 v87, v82, v83
	v_mov_b32_dpp v246, v84 row_ror:8 row_mask:0xf bank_mask:0xf
	v_mov_b32_dpp v247, v85 row_ror:8 row_mask:0xf bank_mask:0xf
	v_mov_b32_dpp v248, v86 row_ror:8 row_mask:0xf bank_mask:0xf
	v_mov_b32_dpp v249, v87 row_ror:8 row_mask:0xf bank_mask:0xf
	v_mov_b32_dpp v250, v92 row_ror:8 row_mask:0xf bank_mask:0xf
	v_mov_b32_dpp v251, v93 row_ror:8 row_mask:0xf bank_mask:0xf
	v_mov_b32_dpp v252, v94 row_ror:8 row_mask:0xf bank_mask:0xf
	v_mov_b32_dpp v253, v95 row_ror:8 row_mask:0xf bank_mask:0xf
	v_cndmask_b32_e32 v246, v92, v246, vcc
	v_cndmask_b32_e32 v247, v93, v247, vcc
	v_cndmask_b32_e32 v248, v94, v248, vcc
	v_cndmask_b32_e32 v249, v95, v249, vcc
	v_cndmask_b32_e32 v250, v250, v84, vcc
	v_cndmask_b32_e32 v251, v251, v85, vcc
	v_cndmask_b32_e32 v252, v252, v86, vcc
	v_cndmask_b32_e32 v253, v253, v87, vcc
	ds_bpermute_b32 v246, v240, v246
	ds_bpermute_b32 v247, v240, v247
	ds_bpermute_b32 v248, v240, v248
	ds_bpermute_b32 v249, v240, v249
	ds_bpermute_b32 v250, v240, v250
	ds_bpermute_b32 v251, v240, v251
	ds_bpermute_b32 v252, v240, v252
	ds_bpermute_b32 v253, v240, v253
	v_mov_b32_e32 v92, 0
	v_mov_b32_e32 v93, 0
	v_mov_b32_e32 v94, 0
	v_mov_b32_e32 v95, 0
	v_mov_b32_e32 v88, 0
	v_mov_b32_e32 v89, 0
	v_mov_b32_e32 v90, 0
	v_mov_b32_e32 v91, 0
	v_mov_b32_e32 v84, 0
	v_mov_b32_e32 v85, 0
	v_mov_b32_e32 v86, 0
	v_mov_b32_e32 v87, 0
	v_mov_b32_e32 v80, 0
	v_mov_b32_e32 v81, 0
	v_mov_b32_e32 v82, 0
	v_mov_b32_e32 v83, 0
	v_lshl_add_u64 v[238:239], v[140:141], 0, v[242:243]
	s_waitcnt lgkmcnt(4)
	global_store_dwordx4 v[140:141], v[246:249], off
	s_waitcnt lgkmcnt(0)
	global_store_dwordx4 v[238:239], v[250:253], off
	v_lshl_add_u64 v[140:141], v[140:141], 0, s[34:35]
	v_max_f32_e32 v76, 0, v76
	v_max_f32_e32 v77, 0, v77
	v_max_f32_e32 v78, 0, v78
	v_max_f32_e32 v79, 0, v79
	v_max_f32_e32 v72, 0, v72
	v_max_f32_e32 v73, 0, v73
	v_max_f32_e32 v74, 0, v74
	v_max_f32_e32 v75, 0, v75
	v_max_f32_e32 v68, 0, v68
	v_max_f32_e32 v69, 0, v69
	v_max_f32_e32 v70, 0, v70
	v_max_f32_e32 v71, 0, v71
	v_max_f32_e32 v64, 0, v64
	v_max_f32_e32 v65, 0, v65
	v_max_f32_e32 v66, 0, v66
	v_max_f32_e32 v67, 0, v67
	v_mul_f32_e32 v76, v76, v76
	v_mul_f32_e32 v77, v77, v77
	v_mul_f32_e32 v78, v78, v78
	v_mul_f32_e32 v79, v79, v79
	v_mul_f32_e32 v72, v72, v72
	v_mul_f32_e32 v73, v73, v73
	v_mul_f32_e32 v74, v74, v74
	v_mul_f32_e32 v75, v75, v75
	v_mul_f32_e32 v68, v68, v68
	v_mul_f32_e32 v69, v69, v69
	v_mul_f32_e32 v70, v70, v70
	v_mul_f32_e32 v71, v71, v71
	v_mul_f32_e32 v64, v64, v64
	v_mul_f32_e32 v65, v65, v65
	v_mul_f32_e32 v66, v66, v66
	v_mul_f32_e32 v67, v67, v67
	v_cvt_pk_bf16_f32 v76, v76, v77
	v_cvt_pk_bf16_f32 v77, v78, v79
	v_cvt_pk_bf16_f32 v78, v72, v73
	v_cvt_pk_bf16_f32 v79, v74, v75
	v_cvt_pk_bf16_f32 v68, v68, v69
	v_cvt_pk_bf16_f32 v69, v70, v71
	v_cvt_pk_bf16_f32 v70, v64, v65
	v_cvt_pk_bf16_f32 v71, v66, v67
	v_mov_b32_dpp v246, v68 row_ror:8 row_mask:0xf bank_mask:0xf
	v_mov_b32_dpp v247, v69 row_ror:8 row_mask:0xf bank_mask:0xf
	v_mov_b32_dpp v248, v70 row_ror:8 row_mask:0xf bank_mask:0xf
	v_mov_b32_dpp v249, v71 row_ror:8 row_mask:0xf bank_mask:0xf
	v_mov_b32_dpp v250, v76 row_ror:8 row_mask:0xf bank_mask:0xf
	v_mov_b32_dpp v251, v77 row_ror:8 row_mask:0xf bank_mask:0xf
	v_mov_b32_dpp v252, v78 row_ror:8 row_mask:0xf bank_mask:0xf
	v_mov_b32_dpp v253, v79 row_ror:8 row_mask:0xf bank_mask:0xf
	v_cndmask_b32_e32 v246, v76, v246, vcc
	v_cndmask_b32_e32 v247, v77, v247, vcc
	v_cndmask_b32_e32 v248, v78, v248, vcc
	v_cndmask_b32_e32 v249, v79, v249, vcc
	v_cndmask_b32_e32 v250, v250, v68, vcc
	v_cndmask_b32_e32 v251, v251, v69, vcc
	v_cndmask_b32_e32 v252, v252, v70, vcc
	v_cndmask_b32_e32 v253, v253, v71, vcc
	ds_bpermute_b32 v246, v240, v246
	ds_bpermute_b32 v247, v240, v247
	ds_bpermute_b32 v248, v240, v248
	ds_bpermute_b32 v249, v240, v249
	ds_bpermute_b32 v250, v240, v250
	ds_bpermute_b32 v251, v240, v251
	ds_bpermute_b32 v252, v240, v252
	ds_bpermute_b32 v253, v240, v253
	v_mov_b32_e32 v76, 0
	v_mov_b32_e32 v77, 0
	v_mov_b32_e32 v78, 0
	v_mov_b32_e32 v79, 0
	v_mov_b32_e32 v72, 0
	v_mov_b32_e32 v73, 0
	v_mov_b32_e32 v74, 0
	v_mov_b32_e32 v75, 0
	v_mov_b32_e32 v68, 0
	v_mov_b32_e32 v69, 0
	v_mov_b32_e32 v70, 0
	v_mov_b32_e32 v71, 0
	v_mov_b32_e32 v64, 0
	v_mov_b32_e32 v65, 0
	v_mov_b32_e32 v66, 0
	v_mov_b32_e32 v67, 0
	v_lshl_add_u64 v[238:239], v[140:141], 0, v[242:243]
	s_waitcnt lgkmcnt(4)
; __device__ __forceinline__ u32x4 pack8_bf16(f32x4 a, f32x4 b) { u32x4 w; w.x = cvt_pk_bf16(a[0], a[1]); w.y = cvt_pk_bf16(a[2], a[3]); w.z = cvt_pk_bf16(b[0], b[1]); w.w = cvt_pk_bf16(b[2], b[3]); return w; }
; #define ACT(t) (KBASE(t) <= qlo + QBLK - 1 && KBASE(t) + KVBLK - 1 >= qlo - W + 1)
;     __device__ __forceinline__ void operator()(const f32x4 (&acc)[2][2][4][2], const Unit& u, int wr, int wc, int fr, int fq) const {
;         const int g = u.pn / nNper, pnl = u.pn - g * nNper, pml = u.pm & 63;
;         bf16_t* base = O + (size_t)g * gstride;
;         const int row0 = pml * BM + wr * 64 + fr, col0 = pnl * BM + wc * 32 + 8 * fq;
; #pragma unroll
;         for (int ai = 0; ai < 2; ++ai)
; #pragma unroll
;             for (int m = 0; m < 4; ++m) { bf16_t* rowp = base + (size_t)(row0 + ai * HALF + m * 16) * ldc + col0;
; #pragma unroll
;                 for (int bj = 0; bj < 2; ++bj) { f32x4 v0 = acc[ai][bj][m][0], v1 = acc[ai][bj][m][1];
;                     if (ACT == 1) {
; #pragma unroll
;                         for (int j = 0; j < 4; ++j) { float a = fmaxf(v0[j], 0.f), b = fmaxf(v1[j], 0.f); v0[j] = a * a; v1[j] = b * b; } }
;                     *(u32x4*)(rowp + bj * HALF) = pack8_bf16(v0, v1); } }
; template <class Epi, class Sched, bool ALIGN_EPI = false, bool SP2 = false>
; __device__ __forceinline__ void gemm_phase(PG8_LAS unsigned char* lds, const Gemm g, const Sched& S, const Epi& E) {
;     ...
; #pragma unroll
;         for (int a = 0; a < 2; ++a)
; #pragma unroll
;             for (int b = 0; b < 2; ++b)
; #pragma unroll
;                 for (int m = 0; m < 4; ++m)
; #pragma unroll
;                     for (int n = 0; n < 2; ++n) acc[a][b][m][n] = (f32x4){0.f, 0.f, 0.f, 0.f};
	global_store_dwordx4 v[140:141], v[246:249], off
	s_waitcnt lgkmcnt(0)
	global_store_dwordx4 v[238:239], v[250:253], off
	s_mov_b64 s[34:35], 0x140000
	v_lshl_add_u64 v[140:141], v[140:141], 0, s[34:35]
	s_mov_b64 s[34:35], 0x40000
	v_max_f32_e32 v60, 0, v60
	v_max_f32_e32 v61, 0, v61
	v_max_f32_e32 v62, 0, v62
	v_max_f32_e32 v63, 0, v63
	v_max_f32_e32 v56, 0, v56
	v_max_f32_e32 v57, 0, v57
	v_max_f32_e32 v58, 0, v58
	v_max_f32_e32 v59, 0, v59
	v_max_f32_e32 v52, 0, v52
	v_max_f32_e32 v53, 0, v53
	v_max_f32_e32 v54, 0, v54
	v_max_f32_e32 v55, 0, v55
	v_max_f32_e32 v48, 0, v48
	v_max_f32_e32 v49, 0, v49
	v_max_f32_e32 v50, 0, v50
	v_max_f32_e32 v51, 0, v51
	v_mul_f32_e32 v60, v60, v60
	v_mul_f32_e32 v61, v61, v61
	v_mul_f32_e32 v62, v62, v62
	v_mul_f32_e32 v63, v63, v63
	v_mul_f32_e32 v56, v56, v56
	v_mul_f32_e32 v57, v57, v57
	v_mul_f32_e32 v58, v58, v58
	v_mul_f32_e32 v59, v59, v59
	v_mul_f32_e32 v52, v52, v52
	v_mul_f32_e32 v53, v53, v53
	v_mul_f32_e32 v54, v54, v54
	v_mul_f32_e32 v55, v55, v55
	v_mul_f32_e32 v48, v48, v48
	v_mul_f32_e32 v49, v49, v49
	v_mul_f32_e32 v50, v50, v50
	v_mul_f32_e32 v51, v51, v51
	v_cvt_pk_bf16_f32 v60, v60, v61
	v_cvt_pk_bf16_f32 v61, v62, v63
	v_cvt_pk_bf16_f32 v62, v56, v57
	v_cvt_pk_bf16_f32 v63, v58, v59
	v_cvt_pk_bf16_f32 v52, v52, v53
	v_cvt_pk_bf16_f32 v53, v54, v55
	v_cvt_pk_bf16_f32 v54, v48, v49
	v_cvt_pk_bf16_f32 v55, v50, v51
	v_mov_b32_dpp v246, v52 row_ror:8 row_mask:0xf bank_mask:0xf
	v_mov_b32_dpp v247, v53 row_ror:8 row_mask:0xf bank_mask:0xf
	v_mov_b32_dpp v248, v54 row_ror:8 row_mask:0xf bank_mask:0xf
	v_mov_b32_dpp v249, v55 row_ror:8 row_mask:0xf bank_mask:0xf
	v_mov_b32_dpp v250, v60 row_ror:8 row_mask:0xf bank_mask:0xf
	v_mov_b32_dpp v251, v61 row_ror:8 row_mask:0xf bank_mask:0xf
	v_mov_b32_dpp v252, v62 row_ror:8 row_mask:0xf bank_mask:0xf
	v_mov_b32_dpp v253, v63 row_ror:8 row_mask:0xf bank_mask:0xf
	v_cndmask_b32_e32 v246, v60, v246, vcc
	v_cndmask_b32_e32 v247, v61, v247, vcc
	v_cndmask_b32_e32 v248, v62, v248, vcc
	v_cndmask_b32_e32 v249, v63, v249, vcc
	v_cndmask_b32_e32 v250, v250, v52, vcc
	v_cndmask_b32_e32 v251, v251, v53, vcc
	v_cndmask_b32_e32 v252, v252, v54, vcc
	v_cndmask_b32_e32 v253, v253, v55, vcc
	ds_bpermute_b32 v246, v240, v246
	ds_bpermute_b32 v247, v240, v247
	ds_bpermute_b32 v248, v240, v248
	ds_bpermute_b32 v249, v240, v249
	ds_bpermute_b32 v250, v240, v250
	ds_bpermute_b32 v251, v240, v251
	ds_bpermute_b32 v252, v240, v252
	ds_bpermute_b32 v253, v240, v253
	v_mov_b32_e32 v60, 0
	v_mov_b32_e32 v61, 0
	v_mov_b32_e32 v62, 0
	v_mov_b32_e32 v63, 0
	v_mov_b32_e32 v56, 0
	v_mov_b32_e32 v57, 0
	v_mov_b32_e32 v58, 0
	v_mov_b32_e32 v59, 0
	v_mov_b32_e32 v52, 0
	v_mov_b32_e32 v53, 0
	v_mov_b32_e32 v54, 0
	v_mov_b32_e32 v55, 0
	v_mov_b32_e32 v48, 0
	v_mov_b32_e32 v49, 0
	v_mov_b32_e32 v50, 0
	v_mov_b32_e32 v51, 0
	v_lshl_add_u64 v[238:239], v[140:141], 0, v[242:243]
	s_waitcnt lgkmcnt(4)
	global_store_dwordx4 v[140:141], v[246:249], off
	s_waitcnt lgkmcnt(0)
	global_store_dwordx4 v[238:239], v[250:253], off
	v_lshl_add_u64 v[140:141], v[140:141], 0, s[34:35]
	v_max_f32_e32 v44, 0, v44
	v_max_f32_e32 v45, 0, v45
	v_max_f32_e32 v46, 0, v46
	v_max_f32_e32 v47, 0, v47
	v_max_f32_e32 v40, 0, v40
	v_max_f32_e32 v41, 0, v41
	v_max_f32_e32 v42, 0, v42
	v_max_f32_e32 v43, 0, v43
	v_max_f32_e32 v36, 0, v36
	v_max_f32_e32 v37, 0, v37
	v_max_f32_e32 v38, 0, v38
	v_max_f32_e32 v39, 0, v39
	v_max_f32_e32 v32, 0, v32
	v_max_f32_e32 v33, 0, v33
	v_max_f32_e32 v34, 0, v34
	v_max_f32_e32 v35, 0, v35
	v_mul_f32_e32 v44, v44, v44
	v_mul_f32_e32 v45, v45, v45
	v_mul_f32_e32 v46, v46, v46
	v_mul_f32_e32 v47, v47, v47
	v_mul_f32_e32 v40, v40, v40
	v_mul_f32_e32 v41, v41, v41
	v_mul_f32_e32 v42, v42, v42
	v_mul_f32_e32 v43, v43, v43
	v_mul_f32_e32 v36, v36, v36
	v_mul_f32_e32 v37, v37, v37
	v_mul_f32_e32 v38, v38, v38
	v_mul_f32_e32 v39, v39, v39
	v_mul_f32_e32 v32, v32, v32
	v_mul_f32_e32 v33, v33, v33
	v_mul_f32_e32 v34, v34, v34
	v_mul_f32_e32 v35, v35, v35
	v_cvt_pk_bf16_f32 v44, v44, v45
	v_cvt_pk_bf16_f32 v45, v46, v47
	v_cvt_pk_bf16_f32 v46, v40, v41
	v_cvt_pk_bf16_f32 v47, v42, v43
	v_cvt_pk_bf16_f32 v36, v36, v37
	v_cvt_pk_bf16_f32 v37, v38, v39
	v_cvt_pk_bf16_f32 v38, v32, v33
	v_cvt_pk_bf16_f32 v39, v34, v35
	v_mov_b32_dpp v246, v36 row_ror:8 row_mask:0xf bank_mask:0xf
	v_mov_b32_dpp v247, v37 row_ror:8 row_mask:0xf bank_mask:0xf
	v_mov_b32_dpp v248, v38 row_ror:8 row_mask:0xf bank_mask:0xf
	v_mov_b32_dpp v249, v39 row_ror:8 row_mask:0xf bank_mask:0xf
	v_mov_b32_dpp v250, v44 row_ror:8 row_mask:0xf bank_mask:0xf
	v_mov_b32_dpp v251, v45 row_ror:8 row_mask:0xf bank_mask:0xf
	v_mov_b32_dpp v252, v46 row_ror:8 row_mask:0xf bank_mask:0xf
	v_mov_b32_dpp v253, v47 row_ror:8 row_mask:0xf bank_mask:0xf
	v_cndmask_b32_e32 v246, v44, v246, vcc
	v_cndmask_b32_e32 v247, v45, v247, vcc
	v_cndmask_b32_e32 v248, v46, v248, vcc
	v_cndmask_b32_e32 v249, v47, v249, vcc
	v_cndmask_b32_e32 v250, v250, v36, vcc
	v_cndmask_b32_e32 v251, v251, v37, vcc
	v_cndmask_b32_e32 v252, v252, v38, vcc
	v_cndmask_b32_e32 v253, v253, v39, vcc
	ds_bpermute_b32 v246, v240, v246
	ds_bpermute_b32 v247, v240, v247
	ds_bpermute_b32 v248, v240, v248
	ds_bpermute_b32 v249, v240, v249
	ds_bpermute_b32 v250, v240, v250
	ds_bpermute_b32 v251, v240, v251
	ds_bpermute_b32 v252, v240, v252
	ds_bpermute_b32 v253, v240, v253
	v_mov_b32_e32 v44, 0
	v_mov_b32_e32 v45, 0
	v_mov_b32_e32 v46, 0
	v_mov_b32_e32 v47, 0
	v_mov_b32_e32 v40, 0
	v_mov_b32_e32 v41, 0
	v_mov_b32_e32 v42, 0
	v_mov_b32_e32 v43, 0
	v_mov_b32_e32 v36, 0
	v_mov_b32_e32 v37, 0
	v_mov_b32_e32 v38, 0
	v_mov_b32_e32 v39, 0
	v_mov_b32_e32 v32, 0
	v_mov_b32_e32 v33, 0
	v_mov_b32_e32 v34, 0
	v_mov_b32_e32 v35, 0
	v_lshl_add_u64 v[238:239], v[140:141], 0, v[242:243]
	s_waitcnt lgkmcnt(4)
; __device__ __forceinline__ u32x4 pack8_bf16(f32x4 a, f32x4 b) { u32x4 w; w.x = cvt_pk_bf16(a[0], a[1]); w.y = cvt_pk_bf16(a[2], a[3]); w.z = cvt_pk_bf16(b[0], b[1]); w.w = cvt_pk_bf16(b[2], b[3]); return w; }
; #define PG8_BAR __builtin_amdgcn_s_barrier()
; #define ACT(t) (KBASE(t) <= qlo + QBLK - 1 && KBASE(t) + KVBLK - 1 >= qlo - W + 1)
;     __device__ __forceinline__ void operator()(const f32x4 (&acc)[2][2][4][2], const Unit& u, int wr, int wc, int fr, int fq) const {
;         const int g = u.pn / nNper, pnl = u.pn - g * nNper, pml = u.pm & 63;
;         bf16_t* base = O + (size_t)g * gstride;
;         const int row0 = pml * BM + wr * 64 + fr, col0 = pnl * BM + wc * 32 + 8 * fq;
; #pragma unroll
;         for (int ai = 0; ai < 2; ++ai)
; #pragma unroll
;             for (int m = 0; m < 4; ++m) { bf16_t* rowp = base + (size_t)(row0 + ai * HALF + m * 16) * ldc + col0;
; #pragma unroll
;                 for (int bj = 0; bj < 2; ++bj) { f32x4 v0 = acc[ai][bj][m][0], v1 = acc[ai][bj][m][1];
;                     if (ACT == 1) {
; #pragma unroll
;                         for (int j = 0; j < 4; ++j) { float a = fmaxf(v0[j], 0.f), b = fmaxf(v1[j], 0.f); v0[j] = a * a; v1[j] = b * b; } }
;                     *(u32x4*)(rowp + bj * HALF) = pack8_bf16(v0, v1); } }
; template <class Epi, class Sched, bool ALIGN_EPI = false, bool SP2 = false>
; __device__ __forceinline__ void gemm_phase(PG8_LAS unsigned char* lds, const Gemm g, const Sched& S, const Epi& E) {
;     ...
;         if constexpr (ALIGN_EPI) { if (wr == 0) PG8_BAR; }
;         if constexpr (!Epi::AFTER_DRAIN) { E(acc, cur, wr, wc, fr, fq); S.done(cur); }
;         if (!has_next) break;
; #pragma unroll
;         for (int a = 0; a < 2; ++a)
; #pragma unroll
;             for (int b = 0; b < 2; ++b)
; #pragma unroll
;                 for (int m = 0; m < 4; ++m)
; #pragma unroll
;                     for (int n = 0; n < 2; ++n) acc[a][b][m][n] = (f32x4){0.f, 0.f, 0.f, 0.f};
;         cur = nxt; cA = nA; cB = nB; ++ui;
;         if constexpr (ALIGN_EPI) { if (wr == 1) PG8_BAR; }
;     }
	global_store_dwordx4 v[140:141], v[246:249], off
	s_waitcnt lgkmcnt(0)
	global_store_dwordx4 v[238:239], v[250:253], off
	v_lshl_add_u64 v[140:141], v[140:141], 0, s[34:35]
	v_max_f32_e32 v28, 0, v28
	v_max_f32_e32 v29, 0, v29
	v_max_f32_e32 v30, 0, v30
	v_max_f32_e32 v31, 0, v31
	v_max_f32_e32 v24, 0, v24
	v_max_f32_e32 v25, 0, v25
	v_max_f32_e32 v26, 0, v26
	v_max_f32_e32 v27, 0, v27
	v_max_f32_e32 v20, 0, v20
	v_max_f32_e32 v21, 0, v21
	v_max_f32_e32 v22, 0, v22
	v_max_f32_e32 v23, 0, v23
	v_max_f32_e32 v16, 0, v16
	v_max_f32_e32 v17, 0, v17
	v_max_f32_e32 v18, 0, v18
	v_max_f32_e32 v19, 0, v19
	v_mul_f32_e32 v28, v28, v28
	v_mul_f32_e32 v29, v29, v29
	v_mul_f32_e32 v30, v30, v30
	v_mul_f32_e32 v31, v31, v31
	v_mul_f32_e32 v24, v24, v24
	v_mul_f32_e32 v25, v25, v25
	v_mul_f32_e32 v26, v26, v26
	v_mul_f32_e32 v27, v27, v27
	v_mul_f32_e32 v20, v20, v20
	v_mul_f32_e32 v21, v21, v21
	v_mul_f32_e32 v22, v22, v22
	v_mul_f32_e32 v23, v23, v23
	v_mul_f32_e32 v16, v16, v16
	v_mul_f32_e32 v17, v17, v17
	v_mul_f32_e32 v18, v18, v18
	v_mul_f32_e32 v19, v19, v19
	v_cvt_pk_bf16_f32 v28, v28, v29
	v_cvt_pk_bf16_f32 v29, v30, v31
	v_cvt_pk_bf16_f32 v30, v24, v25
	v_cvt_pk_bf16_f32 v31, v26, v27
	v_cvt_pk_bf16_f32 v20, v20, v21
	v_cvt_pk_bf16_f32 v21, v22, v23
	v_cvt_pk_bf16_f32 v22, v16, v17
	v_cvt_pk_bf16_f32 v23, v18, v19
	v_mov_b32_dpp v246, v20 row_ror:8 row_mask:0xf bank_mask:0xf
	v_mov_b32_dpp v247, v21 row_ror:8 row_mask:0xf bank_mask:0xf
	v_mov_b32_dpp v248, v22 row_ror:8 row_mask:0xf bank_mask:0xf
	v_mov_b32_dpp v249, v23 row_ror:8 row_mask:0xf bank_mask:0xf
	v_mov_b32_dpp v250, v28 row_ror:8 row_mask:0xf bank_mask:0xf
	v_mov_b32_dpp v251, v29 row_ror:8 row_mask:0xf bank_mask:0xf
	v_mov_b32_dpp v252, v30 row_ror:8 row_mask:0xf bank_mask:0xf
	v_mov_b32_dpp v253, v31 row_ror:8 row_mask:0xf bank_mask:0xf
	v_cndmask_b32_e32 v246, v28, v246, vcc
	v_cndmask_b32_e32 v247, v29, v247, vcc
	v_cndmask_b32_e32 v248, v30, v248, vcc
	v_cndmask_b32_e32 v249, v31, v249, vcc
	v_cndmask_b32_e32 v250, v250, v20, vcc
	v_cndmask_b32_e32 v251, v251, v21, vcc
	v_cndmask_b32_e32 v252, v252, v22, vcc
	v_cndmask_b32_e32 v253, v253, v23, vcc
	ds_bpermute_b32 v246, v240, v246
	ds_bpermute_b32 v247, v240, v247
	ds_bpermute_b32 v248, v240, v248
	ds_bpermute_b32 v249, v240, v249
	ds_bpermute_b32 v250, v240, v250
	ds_bpermute_b32 v251, v240, v251
	ds_bpermute_b32 v252, v240, v252
	ds_bpermute_b32 v253, v240, v253
	v_mov_b32_e32 v28, 0
	v_mov_b32_e32 v29, 0
	v_mov_b32_e32 v30, 0
	v_mov_b32_e32 v31, 0
	v_mov_b32_e32 v24, 0
	v_mov_b32_e32 v25, 0
	v_mov_b32_e32 v26, 0
	v_mov_b32_e32 v27, 0
	v_mov_b32_e32 v20, 0
	v_mov_b32_e32 v21, 0
	v_mov_b32_e32 v22, 0
	v_mov_b32_e32 v23, 0
	v_mov_b32_e32 v16, 0
	v_mov_b32_e32 v17, 0
	v_mov_b32_e32 v18, 0
	v_mov_b32_e32 v19, 0
	v_lshl_add_u64 v[238:239], v[140:141], 0, v[242:243]
	s_waitcnt lgkmcnt(4)
	global_store_dwordx4 v[140:141], v[246:249], off
	s_waitcnt lgkmcnt(0)
	global_store_dwordx4 v[238:239], v[250:253], off
	v_lshl_add_u64 v[140:141], v[140:141], 0, s[34:35]
	v_max_f32_e32 v12, 0, v12
	v_max_f32_e32 v13, 0, v13
	v_max_f32_e32 v14, 0, v14
	v_max_f32_e32 v15, 0, v15
	v_max_f32_e32 v8, 0, v8
	v_max_f32_e32 v9, 0, v9
	v_max_f32_e32 v10, 0, v10
	v_max_f32_e32 v11, 0, v11
	v_max_f32_e32 v4, 0, v4
	v_max_f32_e32 v5, 0, v5
	v_max_f32_e32 v6, 0, v6
	v_max_f32_e32 v7, 0, v7
	v_max_f32_e32 v0, 0, v0
	v_max_f32_e32 v1, 0, v1
	v_max_f32_e32 v2, 0, v2
	v_max_f32_e32 v3, 0, v3
	v_mul_f32_e32 v12, v12, v12
	v_mul_f32_e32 v13, v13, v13
	v_mul_f32_e32 v14, v14, v14
	v_mul_f32_e32 v15, v15, v15
	v_mul_f32_e32 v8, v8, v8
	v_mul_f32_e32 v9, v9, v9
	v_mul_f32_e32 v10, v10, v10
	v_mul_f32_e32 v11, v11, v11
	v_mul_f32_e32 v4, v4, v4
	v_mul_f32_e32 v5, v5, v5
	v_mul_f32_e32 v6, v6, v6
	v_mul_f32_e32 v7, v7, v7
	v_mul_f32_e32 v0, v0, v0
	v_mul_f32_e32 v1, v1, v1
	v_mul_f32_e32 v2, v2, v2
	v_mul_f32_e32 v3, v3, v3
	v_cvt_pk_bf16_f32 v12, v12, v13
	v_cvt_pk_bf16_f32 v13, v14, v15
	v_cvt_pk_bf16_f32 v14, v8, v9
	v_cvt_pk_bf16_f32 v15, v10, v11
	v_cvt_pk_bf16_f32 v4, v4, v5
	v_cvt_pk_bf16_f32 v5, v6, v7
	v_cvt_pk_bf16_f32 v6, v0, v1
	v_cvt_pk_bf16_f32 v7, v2, v3
	v_mov_b32_dpp v246, v4 row_ror:8 row_mask:0xf bank_mask:0xf
	v_mov_b32_dpp v247, v5 row_ror:8 row_mask:0xf bank_mask:0xf
	v_mov_b32_dpp v248, v6 row_ror:8 row_mask:0xf bank_mask:0xf
	v_mov_b32_dpp v249, v7 row_ror:8 row_mask:0xf bank_mask:0xf
	v_mov_b32_dpp v250, v12 row_ror:8 row_mask:0xf bank_mask:0xf
	v_mov_b32_dpp v251, v13 row_ror:8 row_mask:0xf bank_mask:0xf
	v_mov_b32_dpp v252, v14 row_ror:8 row_mask:0xf bank_mask:0xf
	v_mov_b32_dpp v253, v15 row_ror:8 row_mask:0xf bank_mask:0xf
	v_cndmask_b32_e32 v246, v12, v246, vcc
	v_cndmask_b32_e32 v247, v13, v247, vcc
	v_cndmask_b32_e32 v248, v14, v248, vcc
	v_cndmask_b32_e32 v249, v15, v249, vcc
	v_cndmask_b32_e32 v250, v250, v4, vcc
	v_cndmask_b32_e32 v251, v251, v5, vcc
	v_cndmask_b32_e32 v252, v252, v6, vcc
	v_cndmask_b32_e32 v253, v253, v7, vcc
	ds_bpermute_b32 v246, v240, v246
	ds_bpermute_b32 v247, v240, v247
	ds_bpermute_b32 v248, v240, v248
	ds_bpermute_b32 v249, v240, v249
	ds_bpermute_b32 v250, v240, v250
	ds_bpermute_b32 v251, v240, v251
	ds_bpermute_b32 v252, v240, v252
	ds_bpermute_b32 v253, v240, v253
	v_mov_b32_e32 v12, 0
	v_mov_b32_e32 v13, 0
	v_mov_b32_e32 v14, 0
	v_mov_b32_e32 v15, 0
	v_mov_b32_e32 v8, 0
	v_mov_b32_e32 v9, 0
	v_mov_b32_e32 v10, 0
	v_mov_b32_e32 v11, 0
	v_mov_b32_e32 v4, 0
	v_mov_b32_e32 v5, 0
	v_mov_b32_e32 v6, 0
	v_mov_b32_e32 v7, 0
	v_mov_b32_e32 v0, 0
	v_mov_b32_e32 v1, 0
	v_mov_b32_e32 v2, 0
	v_mov_b32_e32 v3, 0
	v_lshl_add_u64 v[238:239], v[140:141], 0, v[242:243]
	s_waitcnt lgkmcnt(4)
	global_store_dwordx4 v[140:141], v[246:249], off
	s_waitcnt lgkmcnt(0)
	global_store_dwordx4 v[238:239], v[250:253], off
	s_andn2_b64 vcc, exec, s[40:41]
	s_mov_b64 s[34:35], -1
	s_cbranch_vccnz .LBB0_447
	s_andn2_b64 vcc, exec, s[8:9]
	s_cbranch_vccnz .LBB0_446
	s_barrier
	s_branch .LBB0_446
